# 16-byte global stores at agent scope write-through (sc1 only)
# speedup vs baseline: 1.0004x; 1.0004x over previous
; #define LAS __attribute__((address_space(3)))
; __device__ __forceinline__ unsigned pk2(float lo, float hi) { return f2bf(lo) | (f2bf(hi) << 16); }
; #define LDS_WAIT() asm volatile("s_waitcnt lgkmcnt(0)" ::: "memory")
; __device__ __forceinline__ void wt_item(const float* __restrict__ W, int ldw, int K, int src_c0, bf16_t* __restrict__ WT, int dst_r0, int k0, LAS float* scr, int lane, int Ndst) {
; #pragma unroll 32
;     for (int i = 0; i < 32; ++i) { const int kk = 2 * i + (lane >> 5); scr[kk * 33 + (lane & 31)] = (src_c0 >= 0) ? W[(size_t)(k0 + kk) * ldw + src_c0 + (lane & 31)] : 0.f; }
;     LDS_WAIT(); asm volatile("" ::: "memory");
;     const int c = lane & 7;
; #pragma unroll
;     for (int j = 0; j < 4; ++j) { const int n = (lane >> 3) + 8 * j; const LAS float* s = scr + (8 * c) * 33 + n;
;         v4u o; o.x = pk2(s[0 * 33], s[1 * 33]); o.y = pk2(s[2 * 33], s[3 * 33]); o.z = pk2(s[4 * 33], s[5 * 33]); o.w = pk2(s[6 * 33], s[7 * 33]);
;         *(v4u*)(WT + ((size_t)(k0 >> 6) * Ndst + dst_r0 + n) * 64 + 8 * c) = o; }
;     LDS_WAIT(); asm volatile("" ::: "memory");
; }
; __device__ __forceinline__ void conv_plain(const float* W, int K, int N, bf16_t* WT, LAS float* scr, int gw, int NGW, int lane) {
;     const int nblk = N / 32, items = (K / 64) * nblk;
;     for (int it = gw; it < items; it += NGW) { const int kb = it / nblk, nb = it % nblk; wt_item(W, N, K, nb * 32, WT, nb * 32, kb * 64, scr, lane, N); }
.LBB0_12:
	v_add_u32_e32 v10, v56, v57
	v_add_u32_e32 v10, 0x400, v10
	s_waitcnt vmcnt(2)
	ds_write2_b32 v10, v5, v58 offset0:8 offset1:74
	s_waitcnt vmcnt(0)
	ds_write2_b32 v10, v59, v60 offset0:140 offset1:206
	s_waitcnt lgkmcnt(0)
	ds_read2_b32 v[10:11], v46 offset1:8
	ds_read2_b32 v[62:63], v46 offset0:33 offset1:41
	ds_read2_b32 v[64:65], v46 offset0:66 offset1:74
	ds_read2_b32 v[66:67], v46 offset0:99 offset1:107
	ds_read2_b32 v[68:69], v46 offset0:132 offset1:140
	s_waitcnt lgkmcnt(4)
	v_bfe_u32 v5, v10, 16, 1
	v_add3_u32 v5, v10, v5, s14
	s_waitcnt lgkmcnt(3)
	v_bfe_u32 v10, v62, 16, 1
	v_lshrrev_b32_e32 v5, 16, v5
	v_add3_u32 v10, v62, v10, s14
	ds_read2_b32 v[70:71], v46 offset0:165 offset1:173
	v_and_or_b32 v58, v10, s15, v5
	s_waitcnt lgkmcnt(3)
	v_bfe_u32 v5, v64, 16, 1
	v_add3_u32 v5, v64, v5, s14
	s_waitcnt lgkmcnt(2)
	v_bfe_u32 v10, v66, 16, 1
	ds_read2_b32 v[72:73], v46 offset0:198 offset1:206
	v_lshrrev_b32_e32 v5, 16, v5
	v_add3_u32 v10, v66, v10, s14
	ds_read2_b32 v[74:75], v46 offset0:231 offset1:239
	v_and_or_b32 v59, v10, s15, v5
	s_waitcnt lgkmcnt(3)
	v_bfe_u32 v5, v68, 16, 1
	v_add3_u32 v5, v68, v5, s14
	s_waitcnt lgkmcnt(2)
	v_bfe_u32 v10, v70, 16, 1
	s_ashr_i32 s7, s6, 31
	v_lshrrev_b32_e32 v5, 16, v5
	v_add3_u32 v10, v70, v10, s14
	s_lshl_b64 s[0:1], s[6:7], 13
	s_ashr_i32 s6, s4, 31
	v_and_or_b32 v60, v10, s15, v5
	s_waitcnt lgkmcnt(1)
	v_bfe_u32 v5, v72, 16, 1
	s_add_u32 s0, s0, s4
	v_add3_u32 v5, v72, v5, s14
	s_waitcnt lgkmcnt(0)
	v_bfe_u32 v10, v74, 16, 1
	s_addc_u32 s1, s1, s6
	v_lshrrev_b32_e32 v5, 16, v5
	v_add3_u32 v10, v74, v10, s14
	v_and_or_b32 v61, v10, s15, v5
	v_mov_b32_e32 v77, s1
	v_or_b32_e32 v76, s0, v45
	v_bfe_u32 v5, v11, 16, 1
	v_lshlrev_b64 v[76:77], 7, v[76:77]
	v_add3_u32 v5, v11, v5, s14
	v_bfe_u32 v10, v63, 16, 1
	v_lshl_add_u64 v[76:77], v[8:9], 0, v[76:77]
	v_lshrrev_b32_e32 v5, 16, v5
	v_add3_u32 v10, v63, v10, s14
	global_store_dwordx4 v[76:77], v[58:61], off sc1
	v_mov_b32_e32 v11, s1
	ds_read2_b32 v[62:63], v46 offset0:16 offset1:24
	v_and_or_b32 v58, v10, s15, v5
	v_bfe_u32 v5, v65, 16, 1
	v_add3_u32 v5, v65, v5, s14
	v_bfe_u32 v10, v67, 16, 1
	v_lshrrev_b32_e32 v5, 16, v5
	v_add3_u32 v10, v67, v10, s14
	v_and_or_b32 v59, v10, s15, v5
	v_bfe_u32 v5, v69, 16, 1
	v_add3_u32 v5, v69, v5, s14
	v_bfe_u32 v10, v71, 16, 1
	v_lshrrev_b32_e32 v5, 16, v5
	v_add3_u32 v10, v71, v10, s14
	v_and_or_b32 v60, v10, s15, v5
	v_bfe_u32 v5, v73, 16, 1
	v_add3_u32 v5, v73, v5, s14
	v_bfe_u32 v10, v75, 16, 1
	v_lshrrev_b32_e32 v5, 16, v5
	v_add3_u32 v10, v75, v10, s14
	v_and_or_b32 v61, v10, s15, v5
	v_or_b32_e32 v10, s0, v47
	v_lshlrev_b64 v[10:11], 7, v[10:11]
	v_lshl_add_u64 v[10:11], v[8:9], 0, v[10:11]
	global_store_dwordx4 v[10:11], v[58:61], off sc1
	ds_read2_b32 v[10:11], v46 offset0:49 offset1:57
	ds_read2_b32 v[64:65], v46 offset0:82 offset1:90
	ds_read2_b32 v[66:67], v46 offset0:115 offset1:123
	s_waitcnt lgkmcnt(3)
	v_bfe_u32 v5, v62, 16, 1
	v_add3_u32 v5, v62, v5, s14
	s_waitcnt lgkmcnt(2)
	v_bfe_u32 v58, v10, 16, 1
	ds_read2_b32 v[68:69], v46 offset0:148 offset1:156
	v_lshrrev_b32_e32 v5, 16, v5
	v_add3_u32 v10, v10, v58, s14
	ds_read2_b32 v[70:71], v46 offset0:181 offset1:189
	v_and_or_b32 v58, v10, s15, v5
	s_waitcnt lgkmcnt(3)
	v_bfe_u32 v5, v64, 16, 1
	v_add3_u32 v5, v64, v5, s14
	s_waitcnt lgkmcnt(2)
	v_bfe_u32 v10, v66, 16, 1
	ds_read2_b32 v[72:73], v46 offset0:214 offset1:222
	v_lshrrev_b32_e32 v5, 16, v5
	v_add3_u32 v10, v66, v10, s14
	ds_read2_b32 v[74:75], v46 offset0:247 offset1:255
	v_and_or_b32 v59, v10, s15, v5
	s_waitcnt lgkmcnt(3)
	v_bfe_u32 v5, v68, 16, 1
	v_add3_u32 v5, v68, v5, s14
	s_waitcnt lgkmcnt(2)
	v_bfe_u32 v10, v70, 16, 1
	v_lshrrev_b32_e32 v5, 16, v5
	v_add3_u32 v10, v70, v10, s14
	v_and_or_b32 v60, v10, s15, v5
	s_waitcnt lgkmcnt(1)
	v_bfe_u32 v5, v72, 16, 1
	v_add3_u32 v5, v72, v5, s14
	s_waitcnt lgkmcnt(0)
	v_bfe_u32 v10, v74, 16, 1
	v_lshrrev_b32_e32 v5, 16, v5
	v_add3_u32 v10, v74, v10, s14
	v_and_or_b32 v61, v10, s15, v5
	v_mov_b32_e32 v77, s1
	v_or_b32_e32 v76, s0, v48
	v_bfe_u32 v5, v63, 16, 1
	v_lshlrev_b64 v[76:77], 7, v[76:77]
	v_add3_u32 v5, v63, v5, s14
	v_bfe_u32 v10, v11, 16, 1
	v_lshl_add_u64 v[76:77], v[8:9], 0, v[76:77]
	v_lshrrev_b32_e32 v5, 16, v5
	v_add3_u32 v10, v11, v10, s14
	global_store_dwordx4 v[76:77], v[58:61], off sc1
	v_mov_b32_e32 v11, s1
	s_add_i32 s16, s16, s52
	v_and_or_b32 v58, v10, s15, v5
	v_bfe_u32 v5, v65, 16, 1
	v_add3_u32 v5, v65, v5, s14
	v_bfe_u32 v10, v67, 16, 1
	v_lshrrev_b32_e32 v5, 16, v5
	v_add3_u32 v10, v67, v10, s14
	v_and_or_b32 v59, v10, s15, v5
	v_bfe_u32 v5, v69, 16, 1
	v_add3_u32 v5, v69, v5, s14
	v_bfe_u32 v10, v71, 16, 1
	v_lshrrev_b32_e32 v5, 16, v5
	v_add3_u32 v10, v71, v10, s14
	v_and_or_b32 v60, v10, s15, v5
	v_bfe_u32 v5, v73, 16, 1
	v_add3_u32 v5, v73, v5, s14
	v_bfe_u32 v10, v75, 16, 1
	v_lshrrev_b32_e32 v5, 16, v5
	v_add3_u32 v10, v75, v10, s14
	v_and_or_b32 v61, v10, s15, v5
	v_or_b32_e32 v10, s0, v49
	v_lshlrev_b64 v[10:11], 7, v[10:11]
	v_lshl_add_u64 v[10:11], v[8:9], 0, v[10:11]
	global_store_dwordx4 v[10:11], v[58:61], off sc1
	s_waitcnt lgkmcnt(0)
	s_add_i32 s12, s12, s13
	s_cmpk_lt_i32 s16, 0x2000
	s_cbranch_scc0 .LBB0_29

; #define LAS __attribute__((address_space(3)))
; __device__ __forceinline__ unsigned pk2(float lo, float hi) { return f2bf(lo) | (f2bf(hi) << 16); }
; #define LDS_WAIT() asm volatile("s_waitcnt lgkmcnt(0)" ::: "memory")
; __device__ __forceinline__ void wt_item(const float* __restrict__ W, int ldw, int K, int src_c0, bf16_t* __restrict__ WT, int dst_r0, int k0, LAS float* scr, int lane, int Ndst) {
; #pragma unroll 32
;     for (int i = 0; i < 32; ++i) { const int kk = 2 * i + (lane >> 5); scr[kk * 33 + (lane & 31)] = (src_c0 >= 0) ? W[(size_t)(k0 + kk) * ldw + src_c0 + (lane & 31)] : 0.f; }
;     LDS_WAIT(); asm volatile("" ::: "memory");
;     const int c = lane & 7;
; #pragma unroll
;     for (int j = 0; j < 4; ++j) { const int n = (lane >> 3) + 8 * j; const LAS float* s = scr + (8 * c) * 33 + n;
;         v4u o; o.x = pk2(s[0 * 33], s[1 * 33]); o.y = pk2(s[2 * 33], s[3 * 33]); o.z = pk2(s[4 * 33], s[5 * 33]); o.w = pk2(s[6 * 33], s[7 * 33]);
;         *(v4u*)(WT + ((size_t)(k0 >> 6) * Ndst + dst_r0 + n) * 64 + 8 * c) = o; }
;     LDS_WAIT(); asm volatile("" ::: "memory");
; }
; __device__ __forceinline__ void conv_plain(const float* W, int K, int N, bf16_t* WT, LAS float* scr, int gw, int NGW, int lane) {
;     const int nblk = N / 32, items = (K / 64) * nblk;
;     for (int it = gw; it < items; it += NGW) { const int kb = it / nblk, nb = it % nblk; wt_item(W, N, K, nb * 32, WT, nb * 32, kb * 64, scr, lane, N); }
.LBB0_31:
	v_add_u32_e32 v10, v56, v57
	v_add_u32_e32 v10, 0x400, v10
	s_waitcnt vmcnt(2)
	ds_write2_b32 v10, v5, v58 offset0:8 offset1:74
	s_waitcnt vmcnt(0)
	ds_write2_b32 v10, v59, v60 offset0:140 offset1:206
	s_waitcnt lgkmcnt(0)
	ds_read2_b32 v[10:11], v46 offset1:8
	ds_read2_b32 v[62:63], v46 offset0:33 offset1:41
	ds_read2_b32 v[64:65], v46 offset0:66 offset1:74
	ds_read2_b32 v[66:67], v46 offset0:99 offset1:107
	ds_read2_b32 v[68:69], v46 offset0:132 offset1:140
	s_waitcnt lgkmcnt(4)
	v_bfe_u32 v5, v10, 16, 1
	v_add3_u32 v5, v10, v5, s18
	s_waitcnt lgkmcnt(3)
	v_bfe_u32 v10, v62, 16, 1
	v_lshrrev_b32_e32 v5, 16, v5
	v_add3_u32 v10, v62, v10, s18
	ds_read2_b32 v[70:71], v46 offset0:165 offset1:173
	v_and_or_b32 v58, v10, s19, v5
	s_waitcnt lgkmcnt(3)
	v_bfe_u32 v5, v64, 16, 1
	v_add3_u32 v5, v64, v5, s18
	s_waitcnt lgkmcnt(2)
	v_bfe_u32 v10, v66, 16, 1
	ds_read2_b32 v[72:73], v46 offset0:198 offset1:206
	v_lshrrev_b32_e32 v5, 16, v5
	v_add3_u32 v10, v66, v10, s18
	ds_read2_b32 v[74:75], v46 offset0:231 offset1:239
	v_and_or_b32 v59, v10, s19, v5
	s_waitcnt lgkmcnt(3)
	v_bfe_u32 v5, v68, 16, 1
	v_add3_u32 v5, v68, v5, s18
	s_waitcnt lgkmcnt(2)
	v_bfe_u32 v10, v70, 16, 1
	s_ashr_i32 s13, s12, 31
	v_lshrrev_b32_e32 v5, 16, v5
	v_add3_u32 v10, v70, v10, s18
	s_lshl_b64 s[0:1], s[12:13], 11
	s_ashr_i32 s12, s4, 31
	v_and_or_b32 v60, v10, s19, v5
	s_waitcnt lgkmcnt(1)
	v_bfe_u32 v5, v72, 16, 1
	s_add_u32 s0, s0, s4
	v_add3_u32 v5, v72, v5, s18
	s_waitcnt lgkmcnt(0)
	v_bfe_u32 v10, v74, 16, 1
	s_addc_u32 s1, s1, s12
	v_lshrrev_b32_e32 v5, 16, v5
	v_add3_u32 v10, v74, v10, s18
	v_and_or_b32 v61, v10, s19, v5
	v_mov_b32_e32 v77, s1
	v_or_b32_e32 v76, s0, v45
	v_bfe_u32 v5, v11, 16, 1
	v_lshlrev_b64 v[76:77], 7, v[76:77]
	v_add3_u32 v5, v11, v5, s18
	v_bfe_u32 v10, v63, 16, 1
	v_lshl_add_u64 v[76:77], v[8:9], 0, v[76:77]
	v_lshrrev_b32_e32 v5, 16, v5
	v_add3_u32 v10, v63, v10, s18
	global_store_dwordx4 v[76:77], v[58:61], off sc1
	v_mov_b32_e32 v11, s1
	ds_read2_b32 v[62:63], v46 offset0:16 offset1:24
	v_and_or_b32 v58, v10, s19, v5
	v_bfe_u32 v5, v65, 16, 1
	v_add3_u32 v5, v65, v5, s18
	v_bfe_u32 v10, v67, 16, 1
	v_lshrrev_b32_e32 v5, 16, v5
	v_add3_u32 v10, v67, v10, s18
	v_and_or_b32 v59, v10, s19, v5
	v_bfe_u32 v5, v69, 16, 1
	v_add3_u32 v5, v69, v5, s18
	v_bfe_u32 v10, v71, 16, 1
	v_lshrrev_b32_e32 v5, 16, v5
	v_add3_u32 v10, v71, v10, s18
	v_and_or_b32 v60, v10, s19, v5
	v_bfe_u32 v5, v73, 16, 1
	v_add3_u32 v5, v73, v5, s18
	v_bfe_u32 v10, v75, 16, 1
	v_lshrrev_b32_e32 v5, 16, v5
	v_add3_u32 v10, v75, v10, s18
	v_and_or_b32 v61, v10, s19, v5
	v_or_b32_e32 v10, s0, v47
	v_lshlrev_b64 v[10:11], 7, v[10:11]
	v_lshl_add_u64 v[10:11], v[8:9], 0, v[10:11]
	global_store_dwordx4 v[10:11], v[58:61], off sc1
	ds_read2_b32 v[10:11], v46 offset0:49 offset1:57
	ds_read2_b32 v[64:65], v46 offset0:82 offset1:90
	ds_read2_b32 v[66:67], v46 offset0:115 offset1:123
	s_waitcnt lgkmcnt(3)
	v_bfe_u32 v5, v62, 16, 1
	v_add3_u32 v5, v62, v5, s18
	s_waitcnt lgkmcnt(2)
	v_bfe_u32 v58, v10, 16, 1
	ds_read2_b32 v[68:69], v46 offset0:148 offset1:156
	v_lshrrev_b32_e32 v5, 16, v5
	v_add3_u32 v10, v10, v58, s18
	ds_read2_b32 v[70:71], v46 offset0:181 offset1:189
	v_and_or_b32 v58, v10, s19, v5
	s_waitcnt lgkmcnt(3)
	v_bfe_u32 v5, v64, 16, 1
	v_add3_u32 v5, v64, v5, s18
	s_waitcnt lgkmcnt(2)
	v_bfe_u32 v10, v66, 16, 1
	ds_read2_b32 v[72:73], v46 offset0:214 offset1:222
	v_lshrrev_b32_e32 v5, 16, v5
	v_add3_u32 v10, v66, v10, s18
	ds_read2_b32 v[74:75], v46 offset0:247 offset1:255
	v_and_or_b32 v59, v10, s19, v5
	s_waitcnt lgkmcnt(3)
	v_bfe_u32 v5, v68, 16, 1
	v_add3_u32 v5, v68, v5, s18
	s_waitcnt lgkmcnt(2)
	v_bfe_u32 v10, v70, 16, 1
	v_lshrrev_b32_e32 v5, 16, v5
	v_add3_u32 v10, v70, v10, s18
	v_and_or_b32 v60, v10, s19, v5
	s_waitcnt lgkmcnt(1)
	v_bfe_u32 v5, v72, 16, 1
	v_add3_u32 v5, v72, v5, s18
	s_waitcnt lgkmcnt(0)
	v_bfe_u32 v10, v74, 16, 1
	v_lshrrev_b32_e32 v5, 16, v5
	v_add3_u32 v10, v74, v10, s18
	v_and_or_b32 v61, v10, s19, v5
	v_mov_b32_e32 v77, s1
	v_or_b32_e32 v76, s0, v48
	v_bfe_u32 v5, v63, 16, 1
	v_lshlrev_b64 v[76:77], 7, v[76:77]
	v_add3_u32 v5, v63, v5, s18
	v_bfe_u32 v10, v11, 16, 1
	v_lshl_add_u64 v[76:77], v[8:9], 0, v[76:77]
	v_lshrrev_b32_e32 v5, 16, v5
	v_add3_u32 v10, v11, v10, s18
	global_store_dwordx4 v[76:77], v[58:61], off sc1
	v_mov_b32_e32 v11, s1
	s_add_i32 s20, s20, s52
	v_and_or_b32 v58, v10, s19, v5
	v_bfe_u32 v5, v65, 16, 1
	v_add3_u32 v5, v65, v5, s18
	v_bfe_u32 v10, v67, 16, 1
	v_lshrrev_b32_e32 v5, 16, v5
	v_add3_u32 v10, v67, v10, s18
	v_and_or_b32 v59, v10, s19, v5
	v_bfe_u32 v5, v69, 16, 1
	v_add3_u32 v5, v69, v5, s18
	v_bfe_u32 v10, v71, 16, 1
	v_lshrrev_b32_e32 v5, 16, v5
	v_add3_u32 v10, v71, v10, s18
	v_and_or_b32 v60, v10, s19, v5
	v_bfe_u32 v5, v73, 16, 1
	v_add3_u32 v5, v73, v5, s18
	v_bfe_u32 v10, v75, 16, 1
	v_lshrrev_b32_e32 v5, 16, v5
	v_add3_u32 v10, v75, v10, s18
	v_and_or_b32 v61, v10, s19, v5
	v_or_b32_e32 v10, s0, v49
	v_lshlrev_b64 v[10:11], 7, v[10:11]
	v_lshl_add_u64 v[10:11], v[8:9], 0, v[10:11]
	global_store_dwordx4 v[10:11], v[58:61], off sc1
	s_waitcnt lgkmcnt(0)
	s_add_i32 s16, s16, s17
	s_cmpk_lt_i32 s20, 0x800
	s_cbranch_scc0 .LBB0_48

; #define LAS __attribute__((address_space(3)))
; __device__ __forceinline__ unsigned pk2(float lo, float hi) { return f2bf(lo) | (f2bf(hi) << 16); }
; #define LDS_WAIT() asm volatile("s_waitcnt lgkmcnt(0)" ::: "memory")
; __device__ __forceinline__ void wt_item(const float* __restrict__ W, int ldw, int K, int src_c0, bf16_t* __restrict__ WT, int dst_r0, int k0, LAS float* scr, int lane, int Ndst) {
; #pragma unroll 32
;     for (int i = 0; i < 32; ++i) { const int kk = 2 * i + (lane >> 5); scr[kk * 33 + (lane & 31)] = (src_c0 >= 0) ? W[(size_t)(k0 + kk) * ldw + src_c0 + (lane & 31)] : 0.f; }
;     LDS_WAIT(); asm volatile("" ::: "memory");
;     const int c = lane & 7;
; #pragma unroll
;     for (int j = 0; j < 4; ++j) { const int n = (lane >> 3) + 8 * j; const LAS float* s = scr + (8 * c) * 33 + n;
;         v4u o; o.x = pk2(s[0 * 33], s[1 * 33]); o.y = pk2(s[2 * 33], s[3 * 33]); o.z = pk2(s[4 * 33], s[5 * 33]); o.w = pk2(s[6 * 33], s[7 * 33]);
;         *(v4u*)(WT + ((size_t)(k0 >> 6) * Ndst + dst_r0 + n) * 64 + 8 * c) = o; }
;     LDS_WAIT(); asm volatile("" ::: "memory");
; }
; __device__ __forceinline__ void conv_mla_win(const float* W, bf16_t* WT, LAS float* scr, int gw, int NGW, int lane) {
;     constexpr int nblk = MLA_NP / 32, items = (DM / 64) * nblk;
;     for (int it = gw; it < items; it += NGW) { const int kb = it / nblk, nb = it % nblk;
;         const int src = nb < 32 ? nb * 32 : nb < 96 ? 1088 + (nb - 32) * 32 : nb < 98 ? 1024 + (nb - 96) * 32 : -1;
;         wt_item(W, 3136, DM, src, WT, nb * 32, kb * 64, scr, lane, MLA_NP); }
.LBB0_50:
	s_waitcnt vmcnt(2)
	ds_write2_b32 v5, v57, v58 offset0:8 offset1:74
	s_waitcnt vmcnt(0)
	ds_write2_b32 v5, v59, v60 offset0:140 offset1:206
	s_waitcnt lgkmcnt(0)
	ds_read2_b32 v[10:11], v46 offset1:8
	ds_read2_b32 v[62:63], v46 offset0:33 offset1:41
	ds_read2_b32 v[64:65], v46 offset0:66 offset1:74
	ds_read2_b32 v[66:67], v46 offset0:99 offset1:107
	ds_read2_b32 v[68:69], v46 offset0:132 offset1:140
	s_waitcnt lgkmcnt(4)
	v_bfe_u32 v57, v10, 16, 1
	v_add3_u32 v10, v10, v57, s15
	s_waitcnt lgkmcnt(3)
	v_bfe_u32 v57, v62, 16, 1
	v_lshrrev_b32_e32 v10, 16, v10
	v_add3_u32 v57, v62, v57, s15
	ds_read2_b32 v[70:71], v46 offset0:165 offset1:173
	v_and_or_b32 v58, v57, s16, v10
	s_waitcnt lgkmcnt(3)
	v_bfe_u32 v10, v64, 16, 1
	v_add3_u32 v10, v64, v10, s15
	s_waitcnt lgkmcnt(2)
	v_bfe_u32 v57, v66, 16, 1
	ds_read2_b32 v[72:73], v46 offset0:198 offset1:206
	v_lshrrev_b32_e32 v10, 16, v10
	v_add3_u32 v57, v66, v57, s15
	ds_read2_b32 v[74:75], v46 offset0:231 offset1:239
	v_and_or_b32 v59, v57, s16, v10
	s_waitcnt lgkmcnt(3)
	v_bfe_u32 v10, v68, 16, 1
	v_add3_u32 v10, v68, v10, s15
	s_waitcnt lgkmcnt(2)
	v_bfe_u32 v57, v70, 16, 1
	v_lshrrev_b32_e32 v10, 16, v10
	v_add3_u32 v57, v70, v57, s15
	s_mul_hi_i32 s0, s18, 0xd00
	s_mulk_i32 s18, 0xd00
	s_ashr_i32 s1, s19, 31
	v_and_or_b32 v60, v57, s16, v10
	s_waitcnt lgkmcnt(1)
	v_bfe_u32 v10, v72, 16, 1
	s_add_u32 s4, s18, s19
	v_add3_u32 v10, v72, v10, s15
	s_waitcnt lgkmcnt(0)
	v_bfe_u32 v57, v74, 16, 1
	s_addc_u32 s0, s0, s1
	v_lshrrev_b32_e32 v10, 16, v10
	v_add3_u32 v57, v74, v57, s15
	v_and_or_b32 v61, v57, s16, v10
	v_mov_b32_e32 v77, s0
	v_or_b32_e32 v76, s4, v45
	v_bfe_u32 v10, v11, 16, 1
	v_lshlrev_b64 v[76:77], 7, v[76:77]
	v_add3_u32 v10, v11, v10, s15
	v_bfe_u32 v11, v63, 16, 1
	v_lshl_add_u64 v[76:77], v[8:9], 0, v[76:77]
	v_lshrrev_b32_e32 v10, 16, v10
	v_add3_u32 v11, v63, v11, s15
	global_store_dwordx4 v[76:77], v[58:61], off sc1
	ds_read2_b32 v[62:63], v46 offset0:16 offset1:24
	v_mov_b32_e32 v77, s0
	v_and_or_b32 v58, v11, s16, v10
	v_bfe_u32 v10, v65, 16, 1
	v_add3_u32 v10, v65, v10, s15
	v_bfe_u32 v11, v67, 16, 1
	v_lshrrev_b32_e32 v10, 16, v10
	v_add3_u32 v11, v67, v11, s15
	v_and_or_b32 v59, v11, s16, v10
	v_bfe_u32 v10, v69, 16, 1
	v_add3_u32 v10, v69, v10, s15
	v_bfe_u32 v11, v71, 16, 1
	v_lshrrev_b32_e32 v10, 16, v10
	v_add3_u32 v11, v71, v11, s15
	v_and_or_b32 v60, v11, s16, v10
	v_bfe_u32 v10, v73, 16, 1
	v_add3_u32 v10, v73, v10, s15
	v_bfe_u32 v11, v75, 16, 1
	v_lshrrev_b32_e32 v10, 16, v10
	v_add3_u32 v11, v75, v11, s15
	v_and_or_b32 v61, v11, s16, v10
	v_mov_b32_e32 v11, s0
	v_or_b32_e32 v10, s4, v47
	v_lshlrev_b64 v[10:11], 7, v[10:11]
	v_lshl_add_u64 v[10:11], v[8:9], 0, v[10:11]
	global_store_dwordx4 v[10:11], v[58:61], off sc1
	ds_read2_b32 v[10:11], v46 offset0:49 offset1:57
	ds_read2_b32 v[64:65], v46 offset0:82 offset1:90
	ds_read2_b32 v[66:67], v46 offset0:115 offset1:123
	s_waitcnt lgkmcnt(3)
	v_bfe_u32 v57, v62, 16, 1
	v_add3_u32 v57, v62, v57, s15
	s_waitcnt lgkmcnt(2)
	v_bfe_u32 v58, v10, 16, 1
	ds_read2_b32 v[68:69], v46 offset0:148 offset1:156
	v_lshrrev_b32_e32 v57, 16, v57
	v_add3_u32 v10, v10, v58, s15
	ds_read2_b32 v[70:71], v46 offset0:181 offset1:189
	v_and_or_b32 v58, v10, s16, v57
	s_waitcnt lgkmcnt(3)
	v_bfe_u32 v10, v64, 16, 1
	v_add3_u32 v10, v64, v10, s15
	s_waitcnt lgkmcnt(2)
	v_bfe_u32 v57, v66, 16, 1
	ds_read2_b32 v[72:73], v46 offset0:214 offset1:222
	v_lshrrev_b32_e32 v10, 16, v10
	v_add3_u32 v57, v66, v57, s15
	ds_read2_b32 v[74:75], v46 offset0:247 offset1:255
	v_and_or_b32 v59, v57, s16, v10
	s_waitcnt lgkmcnt(3)
	v_bfe_u32 v10, v68, 16, 1
	v_add3_u32 v10, v68, v10, s15
	s_waitcnt lgkmcnt(2)
	v_bfe_u32 v57, v70, 16, 1
	v_lshrrev_b32_e32 v10, 16, v10
	v_add3_u32 v57, v70, v57, s15
	v_and_or_b32 v60, v57, s16, v10
	s_waitcnt lgkmcnt(1)
	v_bfe_u32 v10, v72, 16, 1
	v_add3_u32 v10, v72, v10, s15
	s_waitcnt lgkmcnt(0)
	v_bfe_u32 v57, v74, 16, 1
	v_lshrrev_b32_e32 v10, 16, v10
	v_add3_u32 v57, v74, v57, s15
	v_and_or_b32 v61, v57, s16, v10
	v_or_b32_e32 v76, s4, v48
	v_bfe_u32 v10, v63, 16, 1
	v_lshlrev_b64 v[76:77], 7, v[76:77]
	v_add3_u32 v10, v63, v10, s15
	v_bfe_u32 v57, v11, 16, 1
	v_lshl_add_u64 v[76:77], v[8:9], 0, v[76:77]
	v_lshrrev_b32_e32 v10, 16, v10
	v_add3_u32 v11, v11, v57, s15
	global_store_dwordx4 v[76:77], v[58:61], off sc1
	s_add_i32 s17, s17, s52
	s_add_i32 s12, s12, s13
	v_and_or_b32 v58, v11, s16, v10
	v_bfe_u32 v10, v65, 16, 1
	v_add3_u32 v10, v65, v10, s15
	v_bfe_u32 v11, v67, 16, 1
	v_lshrrev_b32_e32 v10, 16, v10
	v_add3_u32 v11, v67, v11, s15
	v_and_or_b32 v59, v11, s16, v10
	v_bfe_u32 v10, v69, 16, 1
	v_add3_u32 v10, v69, v10, s15
	v_bfe_u32 v11, v71, 16, 1
	v_lshrrev_b32_e32 v10, 16, v10
	v_add3_u32 v11, v71, v11, s15
	v_and_or_b32 v60, v11, s16, v10
	v_bfe_u32 v10, v73, 16, 1
	v_add3_u32 v10, v73, v10, s15
	v_bfe_u32 v11, v75, 16, 1
	v_lshrrev_b32_e32 v10, 16, v10
	v_add3_u32 v11, v75, v11, s15
	v_and_or_b32 v61, v11, s16, v10
	v_mov_b32_e32 v11, s0
	v_or_b32_e32 v10, s4, v49
	v_lshlrev_b64 v[10:11], 7, v[10:11]
	v_lshl_add_u64 v[10:11], v[8:9], 0, v[10:11]
	global_store_dwordx4 v[10:11], v[58:61], off sc1
	s_waitcnt lgkmcnt(0)
	s_cmpk_lt_i32 s17, 0xd00
	s_cbranch_scc0 .LBB0_75

; #define LAS __attribute__((address_space(3)))
; __device__ __forceinline__ unsigned pk2(float lo, float hi) { return f2bf(lo) | (f2bf(hi) << 16); }
; #define LDS_WAIT() asm volatile("s_waitcnt lgkmcnt(0)" ::: "memory")
; __device__ __forceinline__ void wt_item(const float* __restrict__ W, int ldw, int K, int src_c0, bf16_t* __restrict__ WT, int dst_r0, int k0, LAS float* scr, int lane, int Ndst) {
; #pragma unroll 32
;     for (int i = 0; i < 32; ++i) { const int kk = 2 * i + (lane >> 5); scr[kk * 33 + (lane & 31)] = (src_c0 >= 0) ? W[(size_t)(k0 + kk) * ldw + src_c0 + (lane & 31)] : 0.f; }
;     LDS_WAIT(); asm volatile("" ::: "memory");
;     const int c = lane & 7;
; #pragma unroll
;     for (int j = 0; j < 4; ++j) { const int n = (lane >> 3) + 8 * j; const LAS float* s = scr + (8 * c) * 33 + n;
;         v4u o; o.x = pk2(s[0 * 33], s[1 * 33]); o.y = pk2(s[2 * 33], s[3 * 33]); o.z = pk2(s[4 * 33], s[5 * 33]); o.w = pk2(s[6 * 33], s[7 * 33]);
;         *(v4u*)(WT + ((size_t)(k0 >> 6) * Ndst + dst_r0 + n) * 64 + 8 * c) = o; }
;     LDS_WAIT(); asm volatile("" ::: "memory");
; }
; __device__ __forceinline__ void conv_plain(const float* W, int K, int N, bf16_t* WT, LAS float* scr, int gw, int NGW, int lane) {
;     const int nblk = N / 32, items = (K / 64) * nblk;
;     for (int it = gw; it < items; it += NGW) { const int kb = it / nblk, nb = it % nblk; wt_item(W, N, K, nb * 32, WT, nb * 32, kb * 64, scr, lane, N); }
.LBB0_77:
	s_waitcnt vmcnt(2)
	ds_write2_b32 v5, v57, v58 offset0:8 offset1:74
	s_waitcnt vmcnt(0)
	ds_write2_b32 v5, v59, v60 offset0:140 offset1:206
	s_waitcnt lgkmcnt(0)
	ds_read2_b32 v[10:11], v46 offset1:8
	ds_read2_b32 v[62:63], v46 offset0:33 offset1:41
	ds_read2_b32 v[64:65], v46 offset0:66 offset1:74
	ds_read2_b32 v[66:67], v46 offset0:99 offset1:107
	ds_read2_b32 v[68:69], v46 offset0:132 offset1:140
	s_waitcnt lgkmcnt(4)
	v_bfe_u32 v57, v10, 16, 1
	v_add3_u32 v10, v10, v57, s15
	s_waitcnt lgkmcnt(3)
	v_bfe_u32 v57, v62, 16, 1
	v_lshrrev_b32_e32 v10, 16, v10
	v_add3_u32 v57, v62, v57, s15
	ds_read2_b32 v[70:71], v46 offset0:165 offset1:173
	v_and_or_b32 v58, v57, s16, v10
	s_waitcnt lgkmcnt(3)
	v_bfe_u32 v10, v64, 16, 1
	v_add3_u32 v10, v64, v10, s15
	s_waitcnt lgkmcnt(2)
	v_bfe_u32 v57, v66, 16, 1
	ds_read2_b32 v[72:73], v46 offset0:198 offset1:206
	v_lshrrev_b32_e32 v10, 16, v10
	v_add3_u32 v57, v66, v57, s15
	ds_read2_b32 v[74:75], v46 offset0:231 offset1:239
	v_and_or_b32 v59, v57, s16, v10
	s_waitcnt lgkmcnt(3)
	v_bfe_u32 v10, v68, 16, 1
	v_add3_u32 v10, v68, v10, s15
	s_waitcnt lgkmcnt(2)
	v_bfe_u32 v57, v70, 16, 1
	v_lshrrev_b32_e32 v10, 16, v10
	v_add3_u32 v57, v70, v57, s15
	s_mul_hi_i32 s0, s18, 0xc00
	s_mulk_i32 s18, 0xc00
	s_ashr_i32 s1, s4, 31
	v_and_or_b32 v60, v57, s16, v10
	s_waitcnt lgkmcnt(1)
	v_bfe_u32 v10, v72, 16, 1
	s_add_u32 s4, s18, s4
	v_add3_u32 v10, v72, v10, s15
	s_waitcnt lgkmcnt(0)
	v_bfe_u32 v57, v74, 16, 1
	s_addc_u32 s0, s0, s1
	v_lshrrev_b32_e32 v10, 16, v10
	v_add3_u32 v57, v74, v57, s15
	v_and_or_b32 v61, v57, s16, v10
	v_mov_b32_e32 v77, s0
	v_or_b32_e32 v76, s4, v45
	v_bfe_u32 v10, v11, 16, 1
	v_lshlrev_b64 v[76:77], 7, v[76:77]
	v_add3_u32 v10, v11, v10, s15
	v_bfe_u32 v11, v63, 16, 1
	v_lshl_add_u64 v[76:77], v[8:9], 0, v[76:77]
	v_lshrrev_b32_e32 v10, 16, v10
	v_add3_u32 v11, v63, v11, s15
	global_store_dwordx4 v[76:77], v[58:61], off sc1
	ds_read2_b32 v[62:63], v46 offset0:16 offset1:24
	v_mov_b32_e32 v77, s0
	v_and_or_b32 v58, v11, s16, v10
	v_bfe_u32 v10, v65, 16, 1
	v_add3_u32 v10, v65, v10, s15
	v_bfe_u32 v11, v67, 16, 1
	v_lshrrev_b32_e32 v10, 16, v10
	v_add3_u32 v11, v67, v11, s15
	v_and_or_b32 v59, v11, s16, v10
	v_bfe_u32 v10, v69, 16, 1
	v_add3_u32 v10, v69, v10, s15
	v_bfe_u32 v11, v71, 16, 1
	v_lshrrev_b32_e32 v10, 16, v10
	v_add3_u32 v11, v71, v11, s15
	v_and_or_b32 v60, v11, s16, v10
	v_bfe_u32 v10, v73, 16, 1
	v_add3_u32 v10, v73, v10, s15
	v_bfe_u32 v11, v75, 16, 1
	v_lshrrev_b32_e32 v10, 16, v10
	v_add3_u32 v11, v75, v11, s15
	v_and_or_b32 v61, v11, s16, v10
	v_mov_b32_e32 v11, s0
	v_or_b32_e32 v10, s4, v47
	v_lshlrev_b64 v[10:11], 7, v[10:11]
	v_lshl_add_u64 v[10:11], v[8:9], 0, v[10:11]
	global_store_dwordx4 v[10:11], v[58:61], off sc1
	ds_read2_b32 v[10:11], v46 offset0:49 offset1:57
	ds_read2_b32 v[64:65], v46 offset0:82 offset1:90
	ds_read2_b32 v[66:67], v46 offset0:115 offset1:123
	s_waitcnt lgkmcnt(3)
	v_bfe_u32 v57, v62, 16, 1
	v_add3_u32 v57, v62, v57, s15
	s_waitcnt lgkmcnt(2)
	v_bfe_u32 v58, v10, 16, 1
	ds_read2_b32 v[68:69], v46 offset0:148 offset1:156
	v_lshrrev_b32_e32 v57, 16, v57
	v_add3_u32 v10, v10, v58, s15
	ds_read2_b32 v[70:71], v46 offset0:181 offset1:189
	v_and_or_b32 v58, v10, s16, v57
	s_waitcnt lgkmcnt(3)
	v_bfe_u32 v10, v64, 16, 1
	v_add3_u32 v10, v64, v10, s15
	s_waitcnt lgkmcnt(2)
	v_bfe_u32 v57, v66, 16, 1
	ds_read2_b32 v[72:73], v46 offset0:214 offset1:222
	v_lshrrev_b32_e32 v10, 16, v10
	v_add3_u32 v57, v66, v57, s15
	ds_read2_b32 v[74:75], v46 offset0:247 offset1:255
	v_and_or_b32 v59, v57, s16, v10
	s_waitcnt lgkmcnt(3)
	v_bfe_u32 v10, v68, 16, 1
	v_add3_u32 v10, v68, v10, s15
	s_waitcnt lgkmcnt(2)
	v_bfe_u32 v57, v70, 16, 1
	v_lshrrev_b32_e32 v10, 16, v10
	v_add3_u32 v57, v70, v57, s15
	v_and_or_b32 v60, v57, s16, v10
	s_waitcnt lgkmcnt(1)
	v_bfe_u32 v10, v72, 16, 1
	v_add3_u32 v10, v72, v10, s15
	s_waitcnt lgkmcnt(0)
	v_bfe_u32 v57, v74, 16, 1
	v_lshrrev_b32_e32 v10, 16, v10
	v_add3_u32 v57, v74, v57, s15
	v_and_or_b32 v61, v57, s16, v10
	v_or_b32_e32 v76, s4, v48
	v_bfe_u32 v10, v63, 16, 1
	v_lshlrev_b64 v[76:77], 7, v[76:77]
	v_add3_u32 v10, v63, v10, s15
	v_bfe_u32 v57, v11, 16, 1
	v_lshl_add_u64 v[76:77], v[8:9], 0, v[76:77]
	v_lshrrev_b32_e32 v10, 16, v10
	v_add3_u32 v11, v11, v57, s15
	global_store_dwordx4 v[76:77], v[58:61], off sc1
	s_add_i32 s17, s17, s52
	s_add_i32 s12, s12, s13
	v_and_or_b32 v58, v11, s16, v10
	v_bfe_u32 v10, v65, 16, 1
	v_add3_u32 v10, v65, v10, s15
	v_bfe_u32 v11, v67, 16, 1
	v_lshrrev_b32_e32 v10, 16, v10
	v_add3_u32 v11, v67, v11, s15
	v_and_or_b32 v59, v11, s16, v10
	v_bfe_u32 v10, v69, 16, 1
	v_add3_u32 v10, v69, v10, s15
	v_bfe_u32 v11, v71, 16, 1
	v_lshrrev_b32_e32 v10, 16, v10
	v_add3_u32 v11, v71, v11, s15
	v_and_or_b32 v60, v11, s16, v10
	v_bfe_u32 v10, v73, 16, 1
	v_add3_u32 v10, v73, v10, s15
	v_bfe_u32 v11, v75, 16, 1
	v_lshrrev_b32_e32 v10, 16, v10
	v_add3_u32 v11, v75, v11, s15
	v_and_or_b32 v61, v11, s16, v10
	v_mov_b32_e32 v11, s0
	v_or_b32_e32 v10, s4, v49
	v_lshlrev_b64 v[10:11], 7, v[10:11]
	v_lshl_add_u64 v[10:11], v[8:9], 0, v[10:11]
	global_store_dwordx4 v[10:11], v[58:61], off sc1
	s_waitcnt lgkmcnt(0)
	s_cmpk_lt_i32 s17, 0x300
	s_cbranch_scc0 .LBB0_94

; #define LAS __attribute__((address_space(3)))
; __device__ __forceinline__ unsigned pk2(float lo, float hi) { return f2bf(lo) | (f2bf(hi) << 16); }
; #define LDS_WAIT() asm volatile("s_waitcnt lgkmcnt(0)" ::: "memory")
; __device__ __forceinline__ void wt_item(const float* __restrict__ W, int ldw, int K, int src_c0, bf16_t* __restrict__ WT, int dst_r0, int k0, LAS float* scr, int lane, int Ndst) {
; #pragma unroll 32
;     for (int i = 0; i < 32; ++i) { const int kk = 2 * i + (lane >> 5); scr[kk * 33 + (lane & 31)] = (src_c0 >= 0) ? W[(size_t)(k0 + kk) * ldw + src_c0 + (lane & 31)] : 0.f; }
;     LDS_WAIT(); asm volatile("" ::: "memory");
;     const int c = lane & 7;
; #pragma unroll
;     for (int j = 0; j < 4; ++j) { const int n = (lane >> 3) + 8 * j; const LAS float* s = scr + (8 * c) * 33 + n;
;         v4u o; o.x = pk2(s[0 * 33], s[1 * 33]); o.y = pk2(s[2 * 33], s[3 * 33]); o.z = pk2(s[4 * 33], s[5 * 33]); o.w = pk2(s[6 * 33], s[7 * 33]);
;         *(v4u*)(WT + ((size_t)(k0 >> 6) * Ndst + dst_r0 + n) * 64 + 8 * c) = o; }
;     LDS_WAIT(); asm volatile("" ::: "memory");
; }
; __device__ __forceinline__ void conv_plain(const float* W, int K, int N, bf16_t* WT, LAS float* scr, int gw, int NGW, int lane) {
;     const int nblk = N / 32, items = (K / 64) * nblk;
;     for (int it = gw; it < items; it += NGW) { const int kb = it / nblk, nb = it % nblk; wt_item(W, N, K, nb * 32, WT, nb * 32, kb * 64, scr, lane, N); }
.LBB0_96:
	v_add_u32_e32 v10, 0x400, v56
	s_waitcnt vmcnt(2)
	ds_write2_b32 v10, v5, v57 offset0:8 offset1:74
	s_waitcnt vmcnt(0)
	ds_write2_b32 v10, v58, v59 offset0:140 offset1:206
	s_waitcnt lgkmcnt(0)
	ds_read2_b32 v[10:11], v46 offset1:8
	ds_read2_b32 v[62:63], v46 offset0:33 offset1:41
	ds_read2_b32 v[64:65], v46 offset0:66 offset1:74
	ds_read2_b32 v[66:67], v46 offset0:99 offset1:107
	ds_read2_b32 v[68:69], v46 offset0:132 offset1:140
	s_waitcnt lgkmcnt(4)
	v_bfe_u32 v5, v10, 16, 1
	v_add3_u32 v5, v10, v5, s18
	s_waitcnt lgkmcnt(3)
	v_bfe_u32 v10, v62, 16, 1
	v_lshrrev_b32_e32 v5, 16, v5
	v_add3_u32 v10, v62, v10, s18
	ds_read2_b32 v[70:71], v46 offset0:165 offset1:173
	v_and_or_b32 v58, v10, s19, v5
	s_waitcnt lgkmcnt(3)
	v_bfe_u32 v5, v64, 16, 1
	v_add3_u32 v5, v64, v5, s18
	s_waitcnt lgkmcnt(2)
	v_bfe_u32 v10, v66, 16, 1
	ds_read2_b32 v[72:73], v46 offset0:198 offset1:206
	v_lshrrev_b32_e32 v5, 16, v5
	v_add3_u32 v10, v66, v10, s18
	ds_read2_b32 v[74:75], v46 offset0:231 offset1:239
	v_and_or_b32 v59, v10, s19, v5
	s_waitcnt lgkmcnt(3)
	v_bfe_u32 v5, v68, 16, 1
	v_add3_u32 v5, v68, v5, s18
	s_waitcnt lgkmcnt(2)
	v_bfe_u32 v10, v70, 16, 1
	s_ashr_i32 s13, s12, 31
	v_lshrrev_b32_e32 v5, 16, v5
	v_add3_u32 v10, v70, v10, s18
	s_lshl_b64 s[0:1], s[12:13], 12
	s_ashr_i32 s12, s4, 31
	v_and_or_b32 v60, v10, s19, v5
	s_waitcnt lgkmcnt(1)
	v_bfe_u32 v5, v72, 16, 1
	s_add_u32 s0, s0, s4
	v_add3_u32 v5, v72, v5, s18
	s_waitcnt lgkmcnt(0)
	v_bfe_u32 v10, v74, 16, 1
	s_addc_u32 s1, s1, s12
	v_lshrrev_b32_e32 v5, 16, v5
	v_add3_u32 v10, v74, v10, s18
	v_and_or_b32 v61, v10, s19, v5
	v_mov_b32_e32 v77, s1
	v_or_b32_e32 v76, s0, v45
	v_bfe_u32 v5, v11, 16, 1
	v_lshlrev_b64 v[76:77], 7, v[76:77]
	v_add3_u32 v5, v11, v5, s18
	v_bfe_u32 v10, v63, 16, 1
	v_lshl_add_u64 v[76:77], v[8:9], 0, v[76:77]
	v_lshrrev_b32_e32 v5, 16, v5
	v_add3_u32 v10, v63, v10, s18
	global_store_dwordx4 v[76:77], v[58:61], off sc1
	v_mov_b32_e32 v11, s1
	ds_read2_b32 v[62:63], v46 offset0:16 offset1:24
	v_and_or_b32 v58, v10, s19, v5
	v_bfe_u32 v5, v65, 16, 1
	v_add3_u32 v5, v65, v5, s18
	v_bfe_u32 v10, v67, 16, 1
	v_lshrrev_b32_e32 v5, 16, v5
	v_add3_u32 v10, v67, v10, s18
	v_and_or_b32 v59, v10, s19, v5
	v_bfe_u32 v5, v69, 16, 1
	v_add3_u32 v5, v69, v5, s18
	v_bfe_u32 v10, v71, 16, 1
	v_lshrrev_b32_e32 v5, 16, v5
	v_add3_u32 v10, v71, v10, s18
	v_and_or_b32 v60, v10, s19, v5
	v_bfe_u32 v5, v73, 16, 1
	v_add3_u32 v5, v73, v5, s18
	v_bfe_u32 v10, v75, 16, 1
	v_lshrrev_b32_e32 v5, 16, v5
	v_add3_u32 v10, v75, v10, s18
	v_and_or_b32 v61, v10, s19, v5
	v_or_b32_e32 v10, s0, v47
	v_lshlrev_b64 v[10:11], 7, v[10:11]
	v_lshl_add_u64 v[10:11], v[8:9], 0, v[10:11]
	global_store_dwordx4 v[10:11], v[58:61], off sc1
	ds_read2_b32 v[10:11], v46 offset0:49 offset1:57
	ds_read2_b32 v[64:65], v46 offset0:82 offset1:90
	ds_read2_b32 v[66:67], v46 offset0:115 offset1:123
	s_waitcnt lgkmcnt(3)
	v_bfe_u32 v5, v62, 16, 1
	v_add3_u32 v5, v62, v5, s18
	s_waitcnt lgkmcnt(2)
	v_bfe_u32 v57, v10, 16, 1
	ds_read2_b32 v[68:69], v46 offset0:148 offset1:156
	v_lshrrev_b32_e32 v5, 16, v5
	v_add3_u32 v10, v10, v57, s18
	ds_read2_b32 v[70:71], v46 offset0:181 offset1:189
	v_and_or_b32 v58, v10, s19, v5
	s_waitcnt lgkmcnt(3)
	v_bfe_u32 v5, v64, 16, 1
	v_add3_u32 v5, v64, v5, s18
	s_waitcnt lgkmcnt(2)
	v_bfe_u32 v10, v66, 16, 1
	ds_read2_b32 v[72:73], v46 offset0:214 offset1:222
	v_lshrrev_b32_e32 v5, 16, v5
	v_add3_u32 v10, v66, v10, s18
	ds_read2_b32 v[74:75], v46 offset0:247 offset1:255
	v_and_or_b32 v59, v10, s19, v5
	s_waitcnt lgkmcnt(3)
	v_bfe_u32 v5, v68, 16, 1
	v_add3_u32 v5, v68, v5, s18
	s_waitcnt lgkmcnt(2)
	v_bfe_u32 v10, v70, 16, 1
	v_lshrrev_b32_e32 v5, 16, v5
	v_add3_u32 v10, v70, v10, s18
	v_and_or_b32 v60, v10, s19, v5
	s_waitcnt lgkmcnt(1)
	v_bfe_u32 v5, v72, 16, 1
	v_add3_u32 v5, v72, v5, s18
	s_waitcnt lgkmcnt(0)
	v_bfe_u32 v10, v74, 16, 1
	v_lshrrev_b32_e32 v5, 16, v5
	v_add3_u32 v10, v74, v10, s18
	v_and_or_b32 v61, v10, s19, v5
	v_mov_b32_e32 v77, s1
	v_or_b32_e32 v76, s0, v48
	v_bfe_u32 v5, v63, 16, 1
	v_lshlrev_b64 v[76:77], 7, v[76:77]
	v_add3_u32 v5, v63, v5, s18
	v_bfe_u32 v10, v11, 16, 1
	v_lshl_add_u64 v[76:77], v[8:9], 0, v[76:77]
	v_lshrrev_b32_e32 v5, 16, v5
	v_add3_u32 v10, v11, v10, s18
	global_store_dwordx4 v[76:77], v[58:61], off sc1
	v_mov_b32_e32 v11, s1
	s_add_i32 s20, s20, s52
	v_and_or_b32 v58, v10, s19, v5
	v_bfe_u32 v5, v65, 16, 1
	v_add3_u32 v5, v65, v5, s18
	v_bfe_u32 v10, v67, 16, 1
	v_lshrrev_b32_e32 v5, 16, v5
	v_add3_u32 v10, v67, v10, s18
	v_and_or_b32 v59, v10, s19, v5
	v_bfe_u32 v5, v69, 16, 1
	v_add3_u32 v5, v69, v5, s18
	v_bfe_u32 v10, v71, 16, 1
	v_lshrrev_b32_e32 v5, 16, v5
	v_add3_u32 v10, v71, v10, s18
	v_and_or_b32 v60, v10, s19, v5
	v_bfe_u32 v5, v73, 16, 1
	v_add3_u32 v5, v73, v5, s18
	v_bfe_u32 v10, v75, 16, 1
	v_lshrrev_b32_e32 v5, 16, v5
	v_add3_u32 v10, v75, v10, s18
	v_and_or_b32 v61, v10, s19, v5
	v_or_b32_e32 v10, s0, v49
	v_lshlrev_b64 v[10:11], 7, v[10:11]
	v_lshl_add_u64 v[10:11], v[8:9], 0, v[10:11]
	global_store_dwordx4 v[10:11], v[58:61], off sc1
	s_waitcnt lgkmcnt(0)
	s_add_i32 s16, s16, s17
	s_cmpk_lt_i32 s20, 0x400
	s_cbranch_scc0 .LBB0_113

; #define LAS __attribute__((address_space(3)))
; __device__ __forceinline__ unsigned pk2(float lo, float hi) { return f2bf(lo) | (f2bf(hi) << 16); }
; #define LDS_WAIT() asm volatile("s_waitcnt lgkmcnt(0)" ::: "memory")
; __device__ __forceinline__ void wt_item(const float* __restrict__ W, int ldw, int K, int src_c0, bf16_t* __restrict__ WT, int dst_r0, int k0, LAS float* scr, int lane, int Ndst) {
; #pragma unroll 32
;     for (int i = 0; i < 32; ++i) { const int kk = 2 * i + (lane >> 5); scr[kk * 33 + (lane & 31)] = (src_c0 >= 0) ? W[(size_t)(k0 + kk) * ldw + src_c0 + (lane & 31)] : 0.f; }
;     LDS_WAIT(); asm volatile("" ::: "memory");
;     const int c = lane & 7;
; #pragma unroll
;     for (int j = 0; j < 4; ++j) { const int n = (lane >> 3) + 8 * j; const LAS float* s = scr + (8 * c) * 33 + n;
;         v4u o; o.x = pk2(s[0 * 33], s[1 * 33]); o.y = pk2(s[2 * 33], s[3 * 33]); o.z = pk2(s[4 * 33], s[5 * 33]); o.w = pk2(s[6 * 33], s[7 * 33]);
;         *(v4u*)(WT + ((size_t)(k0 >> 6) * Ndst + dst_r0 + n) * 64 + 8 * c) = o; }
;     LDS_WAIT(); asm volatile("" ::: "memory");
; }
; __device__ __forceinline__ void conv_plain(const float* W, int K, int N, bf16_t* WT, LAS float* scr, int gw, int NGW, int lane) {
;     const int nblk = N / 32, items = (K / 64) * nblk;
;     for (int it = gw; it < items; it += NGW) { const int kb = it / nblk, nb = it % nblk; wt_item(W, N, K, nb * 32, WT, nb * 32, kb * 64, scr, lane, N); }
.LBB0_115:
	v_add_u32_e32 v8, 0x400, v56
	s_waitcnt vmcnt(2)
	ds_write2_b32 v8, v2, v10 offset0:8 offset1:74
	s_waitcnt vmcnt(0)
	ds_write2_b32 v8, v11, v58 offset0:140 offset1:206
	s_waitcnt lgkmcnt(0)
	ds_read2_b32 v[58:59], v46 offset1:8
	ds_read2_b32 v[60:61], v46 offset0:33 offset1:41
	ds_read2_b32 v[62:63], v46 offset0:66 offset1:74
	ds_read2_b32 v[64:65], v46 offset0:99 offset1:107
	ds_read2_b32 v[66:67], v46 offset0:132 offset1:140
	s_waitcnt lgkmcnt(4)
	v_bfe_u32 v2, v58, 16, 1
	v_add3_u32 v2, v58, v2, s14
	s_waitcnt lgkmcnt(3)
	v_bfe_u32 v8, v60, 16, 1
	v_lshrrev_b32_e32 v2, 16, v2
	v_add3_u32 v8, v60, v8, s14
	ds_read2_b32 v[68:69], v46 offset0:165 offset1:173
	v_and_or_b32 v8, v8, s15, v2
	s_waitcnt lgkmcnt(3)
	v_bfe_u32 v2, v62, 16, 1
	v_add3_u32 v2, v62, v2, s14
	s_waitcnt lgkmcnt(2)
	v_bfe_u32 v9, v64, 16, 1
	ds_read2_b32 v[70:71], v46 offset0:198 offset1:206
	v_lshrrev_b32_e32 v2, 16, v2
	v_add3_u32 v9, v64, v9, s14
	ds_read2_b32 v[72:73], v46 offset0:231 offset1:239
	s_ashr_i32 s7, s6, 31
	v_and_or_b32 v9, v9, s15, v2
	s_waitcnt lgkmcnt(3)
	v_bfe_u32 v2, v66, 16, 1
	s_lshl_b64 s[0:1], s[6:7], 11
	s_ashr_i32 s6, s4, 31
	v_add3_u32 v2, v66, v2, s14
	s_waitcnt lgkmcnt(2)
	v_bfe_u32 v10, v68, 16, 1
	s_add_u32 s0, s0, s4
	v_lshrrev_b32_e32 v2, 16, v2
	v_add3_u32 v10, v68, v10, s14
	s_addc_u32 s1, s1, s6
	v_and_or_b32 v10, v10, s15, v2
	s_waitcnt lgkmcnt(1)
	v_bfe_u32 v2, v70, 16, 1
	v_add3_u32 v2, v70, v2, s14
	s_waitcnt lgkmcnt(0)
	v_bfe_u32 v11, v72, 16, 1
	v_mov_b32_e32 v75, s1
	v_or_b32_e32 v74, s0, v45
	v_lshrrev_b32_e32 v2, 16, v2
	v_add3_u32 v11, v72, v11, s14
	v_lshlrev_b64 v[74:75], 7, v[74:75]
	v_and_or_b32 v11, v11, s15, v2
	v_lshl_add_u64 v[74:75], v[4:5], 0, v[74:75]
	v_bfe_u32 v2, v59, 16, 1
	global_store_dwordx4 v[74:75], v[8:11], off sc1
	v_add3_u32 v2, v59, v2, s14
	v_lshrrev_b32_e32 v2, 16, v2
	v_bfe_u32 v8, v61, 16, 1
	v_add3_u32 v8, v61, v8, s14
	v_and_or_b32 v8, v8, s15, v2
	v_bfe_u32 v2, v63, 16, 1
	v_add3_u32 v2, v63, v2, s14
	v_bfe_u32 v9, v65, 16, 1
	v_lshrrev_b32_e32 v2, 16, v2
	v_add3_u32 v9, v65, v9, s14
	v_and_or_b32 v9, v9, s15, v2
	v_bfe_u32 v2, v67, 16, 1
	v_add3_u32 v2, v67, v2, s14
	v_bfe_u32 v10, v69, 16, 1
	v_lshrrev_b32_e32 v2, 16, v2
	v_add3_u32 v10, v69, v10, s14
	v_and_or_b32 v10, v10, s15, v2
	v_bfe_u32 v2, v71, 16, 1
	v_add3_u32 v2, v71, v2, s14
	v_bfe_u32 v11, v73, 16, 1
	v_mov_b32_e32 v59, s1
	v_or_b32_e32 v58, s0, v47
	v_lshrrev_b32_e32 v2, 16, v2
	v_add3_u32 v11, v73, v11, s14
	v_lshlrev_b64 v[58:59], 7, v[58:59]
	v_and_or_b32 v11, v11, s15, v2
	ds_read2_b32 v[60:61], v46 offset0:16 offset1:24
	v_lshl_add_u64 v[58:59], v[4:5], 0, v[58:59]
	global_store_dwordx4 v[58:59], v[8:11], off sc1
	ds_read2_b32 v[58:59], v46 offset0:49 offset1:57
	ds_read2_b32 v[62:63], v46 offset0:82 offset1:90
	ds_read2_b32 v[64:65], v46 offset0:115 offset1:123
	s_waitcnt lgkmcnt(3)
	v_bfe_u32 v2, v60, 16, 1
	v_add3_u32 v2, v60, v2, s14
	s_waitcnt lgkmcnt(2)
	v_bfe_u32 v8, v58, 16, 1
	ds_read2_b32 v[66:67], v46 offset0:148 offset1:156
	v_lshrrev_b32_e32 v2, 16, v2
	v_add3_u32 v8, v58, v8, s14
	ds_read2_b32 v[68:69], v46 offset0:181 offset1:189
	v_and_or_b32 v8, v8, s15, v2
	s_waitcnt lgkmcnt(3)
	v_bfe_u32 v2, v62, 16, 1
	v_add3_u32 v2, v62, v2, s14
	s_waitcnt lgkmcnt(2)
	v_bfe_u32 v9, v64, 16, 1
	ds_read2_b32 v[70:71], v46 offset0:214 offset1:222
	v_lshrrev_b32_e32 v2, 16, v2
	v_add3_u32 v9, v64, v9, s14
	ds_read2_b32 v[72:73], v46 offset0:247 offset1:255
	v_and_or_b32 v9, v9, s15, v2
	s_waitcnt lgkmcnt(3)
	v_bfe_u32 v2, v66, 16, 1
	v_add3_u32 v2, v66, v2, s14
	s_waitcnt lgkmcnt(2)
	v_bfe_u32 v10, v68, 16, 1
	v_lshrrev_b32_e32 v2, 16, v2
	v_add3_u32 v10, v68, v10, s14
	v_and_or_b32 v10, v10, s15, v2
	s_waitcnt lgkmcnt(1)
	v_bfe_u32 v2, v70, 16, 1
	v_add3_u32 v2, v70, v2, s14
	s_waitcnt lgkmcnt(0)
	v_bfe_u32 v11, v72, 16, 1
	v_mov_b32_e32 v75, s1
	v_or_b32_e32 v74, s0, v48
	v_lshrrev_b32_e32 v2, 16, v2
	v_add3_u32 v11, v72, v11, s14
	v_lshlrev_b64 v[74:75], 7, v[74:75]
	v_and_or_b32 v11, v11, s15, v2
	v_lshl_add_u64 v[74:75], v[4:5], 0, v[74:75]
	v_bfe_u32 v2, v61, 16, 1
	global_store_dwordx4 v[74:75], v[8:11], off sc1
	v_add3_u32 v2, v61, v2, s14
	v_lshrrev_b32_e32 v2, 16, v2
	v_bfe_u32 v8, v59, 16, 1
	v_add3_u32 v8, v59, v8, s14
	v_and_or_b32 v8, v8, s15, v2
	v_bfe_u32 v2, v63, 16, 1
	v_add3_u32 v2, v63, v2, s14
	v_bfe_u32 v9, v65, 16, 1
	v_lshrrev_b32_e32 v2, 16, v2
	v_add3_u32 v9, v65, v9, s14
	v_and_or_b32 v9, v9, s15, v2
	v_bfe_u32 v2, v67, 16, 1
	v_add3_u32 v2, v67, v2, s14
	v_bfe_u32 v10, v69, 16, 1
	v_lshrrev_b32_e32 v2, 16, v2
	v_add3_u32 v10, v69, v10, s14
	v_and_or_b32 v10, v10, s15, v2
	v_bfe_u32 v2, v71, 16, 1
	v_add3_u32 v2, v71, v2, s14
	v_bfe_u32 v11, v73, 16, 1
	v_mov_b32_e32 v59, s1
	v_or_b32_e32 v58, s0, v49
	v_lshrrev_b32_e32 v2, 16, v2
	v_add3_u32 v11, v73, v11, s14
	v_lshlrev_b64 v[58:59], 7, v[58:59]
	v_and_or_b32 v11, v11, s15, v2
	v_lshl_add_u64 v[58:59], v[4:5], 0, v[58:59]
	global_store_dwordx4 v[58:59], v[8:11], off sc1
	s_waitcnt lgkmcnt(0)
	s_add_i32 s16, s16, s52
	s_add_i32 s12, s12, s13
	s_cmpk_lt_i32 s16, 0x800
	s_cbranch_scc0 .LBB0_132

; __device__ __forceinline__ float bf2f(unsigned h) { return __uint_as_float(h << 16); }
; __device__ __forceinline__ unsigned pk2(float lo, float hi) { return f2bf(lo) | (f2bf(hi) << 16); }
; __device__ __forceinline__ void mla_mid(const bf16_t* __restrict__ wino, const float* __restrict__ gq, const float* __restrict__ gkv, const float* __restrict__ cs_tab, const float* __restrict__ sn_tab, ...
;     ...
;     for (int m0 = 4 * gw; m0 < M_TOK; m0 += 4 * NGW) {
;         v4u v[4][2]; unsigned w[4]; float cc[4], ss[4];
; #pragma unroll
;         for (int rr = 0; rr < 4; ++rr) { const bf16_t* row = wino + (size_t)(m0 + rr) * 256; constexpr size_t TS = (size_t)M_TOK * 256;
;             v[rr][0] = *(const v4u*)(row + (size_t)(lane >> 5) * TS + (lane & 31) * 8); v[rr][1] = *(const v4u*)(row + (size_t)(2 + (lane >> 5)) * TS + (lane & 31) * 8);
;             w[rr] = *(const unsigned*)(row + 12 * TS + 2 * (lane & 31));
;             const int pos = (m0 + rr) & (SEQ - 1); cc[rr] = cs_tab[pos * 32 + (lane & 31)]; ss[rr] = sn_tab[pos * 32 + (lane & 31)]; }
; #pragma unroll
;         for (int rr = 0; rr < 4; ++rr) { const int m = m0 + rr;
; #pragma unroll
;             for (int part = 0; part < 2; ++part) {
;                 float f[8]; float s = 0.f;
; #pragma unroll
;                 for (int e = 0; e < 4; ++e) { f[2 * e] = bf2f(v[rr][part][e] & 0xffffu); f[2 * e + 1] = bf2f(v[rr][part][e] >> 16); s += f[2 * e] * f[2 * e] + f[2 * e + 1] * f[2 * e + 1]; }
;                 const float rstd = 1.0f / sqrtf(wave_sum(s) * (1.f / LORA) + RMS_EPS);
;                 const f32x4 g0 = part == 0 ? gq0 : gk0, g1 = part == 0 ? gq1 : gk1;
;                 v4u o; o.x = pk2(f[0] * rstd * g0[0], f[1] * rstd * g0[1]); o.y = pk2(f[2] * rstd * g0[2], f[3] * rstd * g0[3]);
;                 o.z = pk2(f[4] * rstd * g1[0], f[5] * rstd * g1[1]); o.w = pk2(f[6] * rstd * g1[2], f[7] * rstd * g1[3]);
;                 *(v4u*)((part == 0 ? cqn : ckvn) + ((size_t)(lane >> 3) * M_TOK + m) * 64 + (lane & 7) * 8) = o;
.LBB0_212:
	v_lshl_add_u64 v[16:17], v[4:5], 0, s[46:47]
	v_add_co_u32_e32 v18, vcc, 0x8800000, v16
	s_add_i32 s0, s8, 32
	s_nop 0
	v_addc_co_u32_e32 v19, vcc, 0, v17, vcc
	global_load_dwordx4 v[72:75], v[18:19], off
	v_add_co_u32_e32 v16, vcc, 0x9800000, v16
	s_and_b32 s0, s0, 0x3ffa0
	s_nop 0
	v_addc_co_u32_e32 v17, vcc, 0, v17, vcc
	global_load_dwordx4 v[40:43], v[16:17], off
	v_or_b32_e32 v20, s0, v1
	s_add_i32 s0, s8, 64
	v_lshlrev_b32_e32 v20, 2, v20
	s_and_b32 s0, s0, 0x3ffc0
	v_lshl_add_u64 v[70:71], v[52:53], 0, s[46:47]
	global_load_dwordx4 v[36:39], v[18:19], off offset:512
	global_load_dwordx4 v[32:35], v[16:17], off offset:512
	global_load_dword v61, v[70:71], off offset:-512
	global_load_dword v66, v20, s[34:35]
	global_load_dword v68, v20, s[86:87]
	global_load_dwordx4 v[28:31], v[18:19], off offset:1024
	global_load_dwordx4 v[24:27], v[16:17], off offset:1024
	global_load_dword v57, v[70:71], off
	v_or_b32_e32 v20, s0, v1
	v_lshlrev_b32_e32 v20, 2, v20
	s_add_i32 s0, s8, 0x60
	global_load_dword v60, v20, s[34:35]
	global_load_dword v62, v20, s[86:87]
	s_nop 0
	global_load_dwordx4 v[20:23], v[18:19], off offset:1536
	s_nop 0
	global_load_dwordx4 v[16:19], v[16:17], off offset:1536
	s_nop 0
	global_load_dword v55, v[70:71], off offset:512
	s_and_b32 s0, s0, 0x3ffe0
	s_waitcnt vmcnt(24)
	v_or_b32_e32 v54, s0, v1
	s_waitcnt vmcnt(23)
	v_lshlrev_b32_e32 v56, 2, v54
	global_load_dword v54, v56, s[34:35]
	s_nop 0
	global_load_dword v56, v56, s[86:87]
	s_waitcnt vmcnt(16)
	v_lshlrev_b32_e32 v59, 16, v73
	v_lshlrev_b32_e32 v58, 16, v72
	v_pk_mul_f32 v[64:65], v[58:59], v[58:59]
	v_and_b32_e32 v73, 0xffff0000, v73
	v_and_b32_e32 v72, 0xffff0000, v72
	v_lshlrev_b32_e32 v77, 16, v75
	v_lshlrev_b32_e32 v76, 16, v74
	v_pk_fma_f32 v[64:65], v[72:73], v[72:73], v[64:65]
	v_pk_mul_f32 v[78:79], v[76:77], v[76:77]
	v_and_b32_e32 v75, 0xffff0000, v75
	v_and_b32_e32 v74, 0xffff0000, v74
	v_pk_fma_f32 v[78:79], v[74:75], v[74:75], v[78:79]
	v_add_f32_e32 v63, v64, v65
	v_add_f32_e32 v63, v78, v63
	v_add_f32_e32 v63, v79, v63
	s_nop 1
	v_add_f32_dpp v63, v63, v63 quad_perm:[1,0,3,2] row_mask:0xf bank_mask:0xf bound_ctrl:1
	s_nop 1
	v_add_f32_dpp v63, v63, v63 quad_perm:[2,3,0,1] row_mask:0xf bank_mask:0xf bound_ctrl:1
	s_nop 1
	v_add_f32_dpp v63, v63, v63 row_half_mirror row_mask:0xf bank_mask:0xf bound_ctrl:1
	s_nop 1
	v_add_f32_dpp v63, v63, v63 row_mirror row_mask:0xf bank_mask:0xf bound_ctrl:1
	v_mov_b32_e32 v64, v63
	s_nop 1
	v_permlane16_swap_b32_e32 v63, v64
	v_add_f32_e32 v63, v63, v64
	v_mov_b32_e32 v64, v63
	s_nop 1
	v_permlane32_swap_b32_e32 v63, v64
	v_add_f32_e32 v63, v63, v64
	v_fmamk_f32 v63, v63, 0x3b000000, v218
	v_cmp_gt_f32_e32 vcc, s30, v63
	v_mul_f32_e32 v64, 0x4f800000, v63
	s_nop 0
	v_cndmask_b32_e32 v63, v63, v64, vcc
	v_sqrt_f32_e32 v64, v63
	s_nop 0
	v_add_u32_e32 v65, -1, v64
	v_fma_f32 v67, -v65, v64, v63
	v_cmp_ge_f32_e64 s[42:43], 0, v67
	v_add_u32_e32 v67, 1, v64
	s_nop 0
	v_cndmask_b32_e64 v65, v64, v65, s[42:43]
	v_fma_f32 v64, -v67, v64, v63
	v_cmp_lt_f32_e64 s[42:43], 0, v64
	s_nop 1
	v_cndmask_b32_e64 v64, v65, v67, s[42:43]
	v_mul_f32_e32 v65, 0x37800000, v64
	v_cndmask_b32_e32 v64, v64, v65, vcc
	v_cmp_class_f32_e32 vcc, v63, v215
	s_nop 1
	v_cndmask_b32_e32 v63, v64, v63, vcc
	v_div_scale_f32 v64, s[0:1], v63, v63, 1.0
	v_rcp_f32_e32 v65, v64
	s_mov_b32 s0, 0x1d000000
	v_fma_f32 v67, -v64, v65, 1.0
	v_fmac_f32_e32 v65, v67, v65
	v_div_scale_f32 v67, vcc, 1.0, v63, 1.0
	v_mul_f32_e32 v69, v67, v65
	v_fma_f32 v78, -v64, v69, v67
	v_fmac_f32_e32 v69, v78, v65
	v_fma_f32 v64, -v64, v69, v67
	v_div_fmas_f32 v64, v64, v65, v69
	v_div_fixup_f32 v64, v64, v63, 1.0
	v_pk_mul_f32 v[58:59], v[64:65], v[58:59] op_sel_hi:[0,1]
	v_pk_mul_f32 v[72:73], v[64:65], v[72:73] op_sel_hi:[0,1]
	v_pk_mul_f32 v[76:77], v[64:65], v[76:77] op_sel_hi:[0,1]
	v_pk_mul_f32 v[64:65], v[64:65], v[74:75] op_sel_hi:[0,1]
	v_pk_mul_f32 v[64:65], v[46:47], v[64:65]
	v_pk_mul_f32 v[58:59], v[14:15], v[58:59]
	v_pk_mul_f32 v[72:73], v[44:45], v[72:73]
	v_bfe_u32 v63, v65, 16, 1
	v_bfe_u32 v67, v64, 16, 1
	v_pk_mul_f32 v[76:77], v[10:11], v[76:77]
	v_bfe_u32 v69, v73, 16, 1
	v_add3_u32 v64, v64, v67, s63
	v_add3_u32 v63, v65, v63, s63
	v_bfe_u32 v65, v58, 16, 1
	v_bfe_u32 v67, v59, 16, 1
	v_bfe_u32 v74, v72, 16, 1
	v_add3_u32 v69, v73, v69, s63
	v_bfe_u32 v73, v76, 16, 1
	v_add3_u32 v59, v59, v67, s63
	v_add3_u32 v58, v58, v65, s63
	v_add3_u32 v72, v72, v74, s63
	v_bfe_u32 v74, v77, 16, 1
	v_add3_u32 v73, v76, v73, s63
	v_lshrrev_b32_e32 v58, 16, v58
	v_lshrrev_b32_e32 v59, 16, v59
	v_add3_u32 v74, v77, v74, s63
	v_lshrrev_b32_e32 v65, 16, v73
	v_and_or_b32 v73, v69, s60, v59
	v_and_or_b32 v72, v72, s60, v58
	v_lshl_add_u64 v[58:59], v[48:49], 0, s[46:47]
	v_lshrrev_b32_e32 v67, 16, v74
	v_and_or_b32 v74, v64, s60, v65
	v_add_co_u32_e32 v64, vcc, s0, v58
	v_and_or_b32 v75, v63, s60, v67
	s_nop 0
	v_addc_co_u32_e32 v65, vcc, 0, v59, vcc
	global_store_dwordx4 v[64:65], v[72:75], off sc1
	s_waitcnt vmcnt(16)
; __device__ __forceinline__ float bf2f(unsigned h) { return __uint_as_float(h << 16); }
; __device__ __forceinline__ unsigned pk2(float lo, float hi) { return f2bf(lo) | (f2bf(hi) << 16); }
; __device__ __forceinline__ void mla_mid(const bf16_t* __restrict__ wino, const float* __restrict__ gq, const float* __restrict__ gkv, const float* __restrict__ cs_tab, const float* __restrict__ sn_tab, ...
;     ...
;             for (int part = 0; part < 2; ++part) {
;                 float f[8]; float s = 0.f;
; #pragma unroll
;                 for (int e = 0; e < 4; ++e) { f[2 * e] = bf2f(v[rr][part][e] & 0xffffu); f[2 * e + 1] = bf2f(v[rr][part][e] >> 16); s += f[2 * e] * f[2 * e] + f[2 * e + 1] * f[2 * e + 1]; }
;                 const float rstd = 1.0f / sqrtf(wave_sum(s) * (1.f / LORA) + RMS_EPS);
;                 const f32x4 g0 = part == 0 ? gq0 : gk0, g1 = part == 0 ? gq1 : gk1;
;                 v4u o; o.x = pk2(f[0] * rstd * g0[0], f[1] * rstd * g0[1]); o.y = pk2(f[2] * rstd * g0[2], f[3] * rstd * g0[3]);
;                 o.z = pk2(f[4] * rstd * g1[0], f[5] * rstd * g1[1]); o.w = pk2(f[6] * rstd * g1[2], f[7] * rstd * g1[3]);
;                 *(v4u*)((part == 0 ? cqn : ckvn) + ((size_t)(lane >> 3) * M_TOK + m) * 64 + (lane & 7) * 8) = o;
;             }
;             if (lane < 32) { const float x1 = bf2f(w[rr] & 0xffffu), x2 = bf2f(w[rr] >> 16);
;                 *(unsigned*)(kr + (size_t)m * 64 + 2 * lane) = pk2(x1 * cc[rr] - x2 * ss[rr], x1 * ss[rr] + x2 * cc[rr]); }
	v_lshlrev_b32_e32 v77, 16, v43
	v_lshlrev_b32_e32 v76, 16, v42
	v_lshlrev_b32_e32 v73, 16, v41
	v_lshlrev_b32_e32 v72, 16, v40
	v_pk_mul_f32 v[74:75], v[72:73], v[72:73]
	v_and_b32_e32 v41, 0xffff0000, v41
	v_and_b32_e32 v40, 0xffff0000, v40
	v_pk_fma_f32 v[74:75], v[40:41], v[40:41], v[74:75]
	v_pk_mul_f32 v[78:79], v[76:77], v[76:77]
	v_and_b32_e32 v43, 0xffff0000, v43
	v_and_b32_e32 v42, 0xffff0000, v42
	v_pk_fma_f32 v[78:79], v[42:43], v[42:43], v[78:79]
	v_add_f32_e32 v63, v74, v75
	v_add_f32_e32 v63, v78, v63
	v_add_f32_e32 v63, v79, v63
	s_nop 1
	v_add_f32_dpp v63, v63, v63 quad_perm:[1,0,3,2] row_mask:0xf bank_mask:0xf bound_ctrl:1
	s_nop 1
	v_add_f32_dpp v63, v63, v63 quad_perm:[2,3,0,1] row_mask:0xf bank_mask:0xf bound_ctrl:1
	s_nop 1
	v_add_f32_dpp v63, v63, v63 row_half_mirror row_mask:0xf bank_mask:0xf bound_ctrl:1
	s_nop 1
	v_add_f32_dpp v63, v63, v63 row_mirror row_mask:0xf bank_mask:0xf bound_ctrl:1
	v_mov_b32_e32 v67, v63
	s_nop 1
	v_permlane16_swap_b32_e32 v63, v67
	v_add_f32_e32 v63, v63, v67
	v_mov_b32_e32 v67, v63
	s_nop 1
	v_permlane32_swap_b32_e32 v63, v67
	v_add_f32_e32 v63, v63, v67
	v_fmamk_f32 v63, v63, 0x3b000000, v218
	v_cmp_gt_f32_e32 vcc, s30, v63
	v_mul_f32_e32 v67, 0x4f800000, v63
	s_nop 0
	v_cndmask_b32_e32 v63, v63, v67, vcc
	v_sqrt_f32_e32 v67, v63
	s_nop 0
	v_add_u32_e32 v69, -1, v67
	v_fma_f32 v74, -v69, v67, v63
	v_cmp_ge_f32_e64 s[42:43], 0, v74
	v_add_u32_e32 v74, 1, v67
	s_nop 0
	v_cndmask_b32_e64 v69, v67, v69, s[42:43]
	v_fma_f32 v67, -v74, v67, v63
	v_cmp_lt_f32_e64 s[42:43], 0, v67
	s_nop 1
	v_cndmask_b32_e64 v67, v69, v74, s[42:43]
	v_mul_f32_e32 v69, 0x37800000, v67
	v_cndmask_b32_e32 v67, v67, v69, vcc
	v_cmp_class_f32_e32 vcc, v63, v215
	s_nop 1
	v_cndmask_b32_e32 v63, v67, v63, vcc
	v_div_scale_f32 v67, s[0:1], v63, v63, 1.0
	v_rcp_f32_e32 v69, v67
	s_nop 0
	v_fma_f32 v74, -v67, v69, 1.0
	v_fmac_f32_e32 v69, v74, v69
	v_div_scale_f32 v74, vcc, 1.0, v63, 1.0
	v_mul_f32_e32 v75, v74, v69
	v_fma_f32 v78, -v67, v75, v74
	v_fmac_f32_e32 v75, v78, v69
	v_fma_f32 v67, -v67, v75, v74
	v_div_fmas_f32 v67, v67, v69, v75
	v_div_fixup_f32 v74, v67, v63, 1.0
	v_pk_mul_f32 v[40:41], v[74:75], v[40:41] op_sel_hi:[0,1]
	v_pk_mul_f32 v[40:41], v[12:13], v[40:41]
	v_pk_mul_f32 v[76:77], v[74:75], v[76:77] op_sel_hi:[0,1]
	v_pk_mul_f32 v[42:43], v[74:75], v[42:43] op_sel_hi:[0,1]
	v_pk_mul_f32 v[72:73], v[74:75], v[72:73] op_sel_hi:[0,1]
	v_pk_mul_f32 v[76:77], v[2:3], v[76:77]
	v_pk_mul_f32 v[42:43], v[8:9], v[42:43]
	v_bfe_u32 v74, v40, 16, 1
	v_pk_mul_f32 v[72:73], v[6:7], v[72:73]
	v_bfe_u32 v63, v43, 16, 1
	v_bfe_u32 v67, v42, 16, 1
	v_bfe_u32 v69, v41, 16, 1
	v_add3_u32 v40, v40, v74, s63
	v_bfe_u32 v74, v77, 16, 1
	v_add3_u32 v41, v41, v69, s63
	v_add3_u32 v42, v42, v67, s63
	v_add3_u32 v43, v43, v63, s63
	v_bfe_u32 v63, v72, 16, 1
	v_bfe_u32 v67, v73, 16, 1
	v_bfe_u32 v69, v76, 16, 1
	v_add3_u32 v74, v77, v74, s63
	v_add3_u32 v69, v76, v69, s63
	v_add3_u32 v67, v73, v67, s63
	v_add3_u32 v63, v72, v63, s63
	v_lshrrev_b32_e32 v72, 16, v74
	v_lshrrev_b32_e32 v63, 16, v63
	v_lshrrev_b32_e32 v67, 16, v67
	v_lshrrev_b32_e32 v69, 16, v69
	v_and_or_b32 v43, v43, s60, v72
	v_add_co_u32_e32 v72, vcc, 0x1e000000, v58
	v_and_or_b32 v42, v42, s60, v69
	v_and_or_b32 v41, v41, s60, v67
	v_and_or_b32 v40, v40, s60, v63
	v_addc_co_u32_e32 v73, vcc, 0, v59, vcc
	global_store_dwordx4 v[72:73], v[40:43], off sc1
	s_nop 1
	v_lshl_add_u64 v[40:41], v[50:51], 0, s[46:47]
	s_and_saveexec_b64 s[6:7], s[40:41]
	s_cbranch_execz .LBB0_214
	s_and_b32 s0, s8, 0x3ff80
	global_load_dword v43, v[70:71], off offset:-1024
	v_or_b32_e32 v42, s0, v1
	v_lshlrev_b32_e32 v63, 2, v42
	global_load_dword v42, v63, s[86:87]
	global_load_dword v70, v63, s[34:35]
	s_waitcnt vmcnt(2)
	v_lshlrev_b32_e32 v73, 16, v43
	v_and_b32_e32 v72, 0xffff0000, v43
	s_waitcnt vmcnt(1)
	v_pk_mul_f32 v[42:43], v[42:43], v[72:73] op_sel:[0,1] op_sel_hi:[0,0]
	s_waitcnt vmcnt(0)
	v_pk_fma_f32 v[74:75], v[70:71], v[72:73], v[42:43]
	v_pk_fma_f32 v[42:43], v[70:71], v[72:73], v[42:43] op_sel_hi:[0,1,1] neg_lo:[0,0,1] neg_hi:[0,0,1]
	v_and_b32_sdwa v42, v43, v217 dst_sel:DWORD dst_unused:UNUSED_PAD src0_sel:WORD_1 src1_sel:DWORD
	v_and_b32_sdwa v63, v74, v217 dst_sel:DWORD dst_unused:UNUSED_PAD src0_sel:WORD_1 src1_sel:DWORD
	v_add3_u32 v42, v43, v42, s63
	v_add3_u32 v63, v74, v63, s63
	v_lshrrev_b32_e32 v42, 16, v42
	v_and_or_b32 v42, v63, s60, v42
	global_store_dword v[40:41], v42, off offset:-256
; __device__ __forceinline__ float bf2f(unsigned h) { return __uint_as_float(h << 16); }
; __device__ __forceinline__ unsigned pk2(float lo, float hi) { return f2bf(lo) | (f2bf(hi) << 16); }
; __device__ __forceinline__ void mla_mid(const bf16_t* __restrict__ wino, const float* __restrict__ gq, const float* __restrict__ gkv, const float* __restrict__ cs_tab, const float* __restrict__ sn_tab, ...
;     ...
;         for (int rr = 0; rr < 4; ++rr) { const int m = m0 + rr;
; #pragma unroll
;             for (int part = 0; part < 2; ++part) {
;                 float f[8]; float s = 0.f;
; #pragma unroll
;                 for (int e = 0; e < 4; ++e) { f[2 * e] = bf2f(v[rr][part][e] & 0xffffu); f[2 * e + 1] = bf2f(v[rr][part][e] >> 16); s += f[2 * e] * f[2 * e] + f[2 * e + 1] * f[2 * e + 1]; }
;                 const float rstd = 1.0f / sqrtf(wave_sum(s) * (1.f / LORA) + RMS_EPS);
;                 const f32x4 g0 = part == 0 ? gq0 : gk0, g1 = part == 0 ? gq1 : gk1;
;                 v4u o; o.x = pk2(f[0] * rstd * g0[0], f[1] * rstd * g0[1]); o.y = pk2(f[2] * rstd * g0[2], f[3] * rstd * g0[3]);
;                 o.z = pk2(f[4] * rstd * g1[0], f[5] * rstd * g1[1]); o.w = pk2(f[6] * rstd * g1[2], f[7] * rstd * g1[3]);
;                 *(v4u*)((part == 0 ? cqn : ckvn) + ((size_t)(lane >> 3) * M_TOK + m) * 64 + (lane & 7) * 8) = o;
.LBB0_214:
	s_or_b64 exec, exec, s[6:7]
	s_waitcnt vmcnt(16)
	v_lshlrev_b32_e32 v43, 16, v37
	v_lshlrev_b32_e32 v42, 16, v36
	v_pk_mul_f32 v[70:71], v[42:43], v[42:43]
	v_and_b32_e32 v37, 0xffff0000, v37
	v_and_b32_e32 v36, 0xffff0000, v36
	v_lshlrev_b32_e32 v73, 16, v39
	v_lshlrev_b32_e32 v72, 16, v38
	v_pk_fma_f32 v[70:71], v[36:37], v[36:37], v[70:71]
	v_pk_mul_f32 v[74:75], v[72:73], v[72:73]
	v_and_b32_e32 v39, 0xffff0000, v39
	v_and_b32_e32 v38, 0xffff0000, v38
	v_pk_fma_f32 v[74:75], v[38:39], v[38:39], v[74:75]
	v_add_f32_e32 v63, v70, v71
	v_add_f32_e32 v63, v74, v63
	v_add_f32_e32 v63, v75, v63
	s_nop 1
	v_add_f32_dpp v63, v63, v63 quad_perm:[1,0,3,2] row_mask:0xf bank_mask:0xf bound_ctrl:1
	s_nop 1
	v_add_f32_dpp v63, v63, v63 quad_perm:[2,3,0,1] row_mask:0xf bank_mask:0xf bound_ctrl:1
	s_nop 1
	v_add_f32_dpp v63, v63, v63 row_half_mirror row_mask:0xf bank_mask:0xf bound_ctrl:1
	s_nop 1
	v_add_f32_dpp v63, v63, v63 row_mirror row_mask:0xf bank_mask:0xf bound_ctrl:1
	v_mov_b32_e32 v67, v63
	s_nop 1
	v_permlane16_swap_b32_e32 v63, v67
	v_add_f32_e32 v63, v63, v67
	v_mov_b32_e32 v67, v63
	s_nop 1
	v_permlane32_swap_b32_e32 v63, v67
	v_add_f32_e32 v63, v63, v67
	v_fmamk_f32 v63, v63, 0x3b000000, v218
	v_cmp_gt_f32_e32 vcc, s30, v63
	v_mul_f32_e32 v67, 0x4f800000, v63
	s_nop 0
	v_cndmask_b32_e32 v63, v63, v67, vcc
	v_sqrt_f32_e32 v67, v63
	s_nop 0
	v_add_u32_e32 v69, -1, v67
	v_fma_f32 v70, -v69, v67, v63
	v_cmp_ge_f32_e64 s[42:43], 0, v70
	v_add_u32_e32 v70, 1, v67
	s_nop 0
	v_cndmask_b32_e64 v69, v67, v69, s[42:43]
	v_fma_f32 v67, -v70, v67, v63
	v_cmp_lt_f32_e64 s[42:43], 0, v67
	s_nop 1
	v_cndmask_b32_e64 v67, v69, v70, s[42:43]
	v_mul_f32_e32 v69, 0x37800000, v67
	v_cndmask_b32_e32 v67, v67, v69, vcc
	v_cmp_class_f32_e32 vcc, v63, v215
	s_nop 1
	v_cndmask_b32_e32 v63, v67, v63, vcc
	v_div_scale_f32 v67, s[0:1], v63, v63, 1.0
	v_rcp_f32_e32 v69, v67
	s_nop 0
	v_fma_f32 v70, -v67, v69, 1.0
	v_fmac_f32_e32 v69, v70, v69
	v_div_scale_f32 v70, vcc, 1.0, v63, 1.0
	v_mul_f32_e32 v71, v70, v69
	v_fma_f32 v74, -v67, v71, v70
	v_fmac_f32_e32 v71, v74, v69
	v_fma_f32 v67, -v67, v71, v70
	v_div_fmas_f32 v67, v67, v69, v71
	v_div_fixup_f32 v70, v67, v63, 1.0
	v_pk_mul_f32 v[36:37], v[70:71], v[36:37] op_sel_hi:[0,1]
	v_pk_mul_f32 v[38:39], v[70:71], v[38:39] op_sel_hi:[0,1]
	v_pk_mul_f32 v[42:43], v[70:71], v[42:43] op_sel_hi:[0,1]
	v_pk_mul_f32 v[36:37], v[44:45], v[36:37]
	v_pk_mul_f32 v[72:73], v[70:71], v[72:73] op_sel_hi:[0,1]
	v_pk_mul_f32 v[38:39], v[46:47], v[38:39]
	v_pk_mul_f32 v[42:43], v[14:15], v[42:43]
	v_pk_mul_f32 v[72:73], v[10:11], v[72:73]
	v_bfe_u32 v63, v39, 16, 1
	v_bfe_u32 v67, v38, 16, 1
	v_bfe_u32 v69, v37, 16, 1
	v_bfe_u32 v70, v36, 16, 1
	v_add3_u32 v36, v36, v70, s63
	v_add3_u32 v37, v37, v69, s63
	v_add3_u32 v38, v38, v67, s63
	v_add3_u32 v39, v39, v63, s63
	v_bfe_u32 v63, v42, 16, 1
	v_bfe_u32 v67, v43, 16, 1
	v_bfe_u32 v69, v72, 16, 1
	v_bfe_u32 v70, v73, 16, 1
	v_add3_u32 v70, v73, v70, s63
	v_add3_u32 v69, v72, v69, s63
	v_add3_u32 v43, v43, v67, s63
	v_add3_u32 v42, v42, v63, s63
	v_lshrrev_b32_e32 v42, 16, v42
	v_lshrrev_b32_e32 v43, 16, v43
	v_lshrrev_b32_e32 v63, 16, v69
	v_lshrrev_b32_e32 v67, 16, v70
	v_and_or_b32 v39, v39, s60, v67
	v_and_or_b32 v38, v38, s60, v63
	v_and_or_b32 v37, v37, s60, v43
	v_and_or_b32 v36, v36, s60, v42
	global_store_dwordx4 v[64:65], v[36:39], off offset:128 sc1
	s_waitcnt vmcnt(16)
	v_lshlrev_b32_e32 v43, 16, v35
	v_lshlrev_b32_e32 v42, 16, v34
	v_lshlrev_b32_e32 v37, 16, v33
	v_lshlrev_b32_e32 v36, 16, v32
	v_pk_mul_f32 v[38:39], v[36:37], v[36:37]
	v_and_b32_e32 v33, 0xffff0000, v33
	v_and_b32_e32 v32, 0xffff0000, v32
	v_pk_fma_f32 v[38:39], v[32:33], v[32:33], v[38:39]
	v_pk_mul_f32 v[70:71], v[42:43], v[42:43]
	v_and_b32_e32 v35, 0xffff0000, v35
	v_and_b32_e32 v34, 0xffff0000, v34
	v_pk_fma_f32 v[70:71], v[34:35], v[34:35], v[70:71]
	v_add_f32_e32 v38, v38, v39
	v_add_f32_e32 v38, v70, v38
	v_add_f32_e32 v38, v71, v38
	s_nop 1
	v_add_f32_dpp v38, v38, v38 quad_perm:[1,0,3,2] row_mask:0xf bank_mask:0xf bound_ctrl:1
	s_nop 1
	v_add_f32_dpp v38, v38, v38 quad_perm:[2,3,0,1] row_mask:0xf bank_mask:0xf bound_ctrl:1
	s_nop 1
	v_add_f32_dpp v38, v38, v38 row_half_mirror row_mask:0xf bank_mask:0xf bound_ctrl:1
	s_nop 1
	v_add_f32_dpp v38, v38, v38 row_mirror row_mask:0xf bank_mask:0xf bound_ctrl:1
	v_mov_b32_e32 v39, v38
	s_nop 1
	v_permlane16_swap_b32_e32 v38, v39
	v_add_f32_e32 v38, v38, v39
	v_mov_b32_e32 v39, v38
	s_nop 1
	v_permlane32_swap_b32_e32 v38, v39
	v_add_f32_e32 v38, v38, v39
	v_fmamk_f32 v38, v38, 0x3b000000, v218
	v_cmp_gt_f32_e32 vcc, s30, v38
	v_mul_f32_e32 v39, 0x4f800000, v38
	s_nop 0
	v_cndmask_b32_e32 v38, v38, v39, vcc
	v_sqrt_f32_e32 v39, v38
	s_nop 0
	v_add_u32_e32 v63, -1, v39
	v_fma_f32 v67, -v63, v39, v38
	v_cmp_ge_f32_e64 s[42:43], 0, v67
	v_add_u32_e32 v67, 1, v39
	s_nop 0
	v_cndmask_b32_e64 v63, v39, v63, s[42:43]
	v_fma_f32 v39, -v67, v39, v38
	v_cmp_lt_f32_e64 s[42:43], 0, v39
	s_nop 1
	v_cndmask_b32_e64 v39, v63, v67, s[42:43]
	v_mul_f32_e32 v63, 0x37800000, v39
	v_cndmask_b32_e32 v39, v39, v63, vcc
	v_cmp_class_f32_e32 vcc, v38, v215
	s_nop 1
	v_cndmask_b32_e32 v38, v39, v38, vcc
	v_div_scale_f32 v39, s[0:1], v38, v38, 1.0
	v_rcp_f32_e32 v63, v39
	s_nop 0
	v_fma_f32 v67, -v39, v63, 1.0
	v_fmac_f32_e32 v63, v67, v63
	v_div_scale_f32 v67, vcc, 1.0, v38, 1.0
	v_mul_f32_e32 v69, v67, v63
	v_fma_f32 v70, -v39, v69, v67
	v_fmac_f32_e32 v69, v70, v63
	v_fma_f32 v39, -v39, v69, v67
	v_div_fmas_f32 v39, v39, v63, v69
	v_div_fixup_f32 v38, v39, v38, 1.0
	v_pk_mul_f32 v[34:35], v[38:39], v[34:35] op_sel_hi:[0,1]
	v_pk_mul_f32 v[36:37], v[38:39], v[36:37] op_sel_hi:[0,1]
	v_pk_mul_f32 v[32:33], v[38:39], v[32:33] op_sel_hi:[0,1]
	v_pk_mul_f32 v[34:35], v[8:9], v[34:35]
	v_pk_mul_f32 v[36:37], v[6:7], v[36:37]
	v_pk_mul_f32 v[32:33], v[12:13], v[32:33]
	v_pk_mul_f32 v[42:43], v[38:39], v[42:43] op_sel_hi:[0,1]
	v_bfe_u32 v38, v35, 16, 1
	v_pk_mul_f32 v[42:43], v[2:3], v[42:43]
	v_bfe_u32 v39, v34, 16, 1
	v_bfe_u32 v63, v33, 16, 1
	v_bfe_u32 v67, v32, 16, 1
	v_add3_u32 v35, v35, v38, s63
	v_bfe_u32 v38, v36, 16, 1
	v_add3_u32 v32, v32, v67, s63
	v_add3_u32 v33, v33, v63, s63
	v_add3_u32 v34, v34, v39, s63
	v_bfe_u32 v39, v37, 16, 1
	v_bfe_u32 v63, v42, 16, 1
	v_bfe_u32 v67, v43, 16, 1
	v_add3_u32 v36, v36, v38, s63
	v_add3_u32 v43, v43, v67, s63
	v_add3_u32 v42, v42, v63, s63
	v_add3_u32 v37, v37, v39, s63
	v_lshrrev_b32_e32 v36, 16, v36
	v_lshrrev_b32_e32 v37, 16, v37
	v_lshrrev_b32_e32 v38, 16, v42
	v_lshrrev_b32_e32 v39, 16, v43
	v_and_or_b32 v32, v32, s60, v36
	v_add_co_u32_e32 v36, vcc, 0x1e000000, v58
	v_and_or_b32 v35, v35, s60, v39
	v_and_or_b32 v34, v34, s60, v38
	v_and_or_b32 v33, v33, s60, v37
	v_addc_co_u32_e32 v37, vcc, 0, v59, vcc
	global_store_dwordx4 v[36:37], v[32:35], off offset:128 sc1
	s_and_saveexec_b64 s[6:7], s[40:41]
	s_cbranch_execz .LBB0_216
; __device__ __forceinline__ float bf2f(unsigned h) { return __uint_as_float(h << 16); }
; __device__ __forceinline__ unsigned pk2(float lo, float hi) { return f2bf(lo) | (f2bf(hi) << 16); }
; __device__ __forceinline__ void mla_mid(const bf16_t* __restrict__ wino, const float* __restrict__ gq, const float* __restrict__ gkv, const float* __restrict__ cs_tab, const float* __restrict__ sn_tab, ...
;     ...
;             for (int part = 0; part < 2; ++part) {
;                 float f[8]; float s = 0.f;
; #pragma unroll
;                 for (int e = 0; e < 4; ++e) { f[2 * e] = bf2f(v[rr][part][e] & 0xffffu); f[2 * e + 1] = bf2f(v[rr][part][e] >> 16); s += f[2 * e] * f[2 * e] + f[2 * e + 1] * f[2 * e + 1]; }
;                 const float rstd = 1.0f / sqrtf(wave_sum(s) * (1.f / LORA) + RMS_EPS);
;                 const f32x4 g0 = part == 0 ? gq0 : gk0, g1 = part == 0 ? gq1 : gk1;
;                 v4u o; o.x = pk2(f[0] * rstd * g0[0], f[1] * rstd * g0[1]); o.y = pk2(f[2] * rstd * g0[2], f[3] * rstd * g0[3]);
;                 o.z = pk2(f[4] * rstd * g1[0], f[5] * rstd * g1[1]); o.w = pk2(f[6] * rstd * g1[2], f[7] * rstd * g1[3]);
;                 *(v4u*)((part == 0 ? cqn : ckvn) + ((size_t)(lane >> 3) * M_TOK + m) * 64 + (lane & 7) * 8) = o;
;             }
;             if (lane < 32) { const float x1 = bf2f(w[rr] & 0xffffu), x2 = bf2f(w[rr] >> 16);
;                 *(unsigned*)(kr + (size_t)m * 64 + 2 * lane) = pk2(x1 * cc[rr] - x2 * ss[rr], x1 * ss[rr] + x2 * cc[rr]); }
	s_waitcnt vmcnt(16)
	v_lshlrev_b32_e32 v33, 16, v61
	v_and_b32_e32 v32, 0xffff0000, v61
	s_waitcnt vmcnt(14)
	v_pk_mul_f32 v[34:35], v[68:69], v[32:33] op_sel:[0,1] op_sel_hi:[0,0]
	v_pk_fma_f32 v[36:37], v[66:67], v[32:33], v[34:35]
	v_pk_fma_f32 v[32:33], v[66:67], v[32:33], v[34:35] op_sel_hi:[0,1,1] neg_lo:[0,0,1] neg_hi:[0,0,1]
	v_and_b32_sdwa v32, v33, v217 dst_sel:DWORD dst_unused:UNUSED_PAD src0_sel:WORD_1 src1_sel:DWORD
	v_and_b32_sdwa v34, v36, v217 dst_sel:DWORD dst_unused:UNUSED_PAD src0_sel:WORD_1 src1_sel:DWORD
	v_add3_u32 v32, v33, v32, s63
	v_add3_u32 v34, v36, v34, s63
	v_lshrrev_b32_e32 v32, 16, v32
	v_and_or_b32 v32, v34, s60, v32
	global_store_dword v[40:41], v32, off offset:-128
.LBB0_216:
	s_or_b64 exec, exec, s[6:7]
	s_waitcnt vmcnt(13)
	v_lshlrev_b32_e32 v33, 16, v29
	v_lshlrev_b32_e32 v32, 16, v28
	v_pk_mul_f32 v[34:35], v[32:33], v[32:33]
	v_and_b32_e32 v29, 0xffff0000, v29
	v_and_b32_e32 v28, 0xffff0000, v28
	v_lshlrev_b32_e32 v37, 16, v31
	v_lshlrev_b32_e32 v36, 16, v30
	v_pk_fma_f32 v[34:35], v[28:29], v[28:29], v[34:35]
	v_pk_mul_f32 v[38:39], v[36:37], v[36:37]
	v_and_b32_e32 v31, 0xffff0000, v31
	v_and_b32_e32 v30, 0xffff0000, v30
	v_pk_fma_f32 v[38:39], v[30:31], v[30:31], v[38:39]
	v_add_f32_e32 v34, v34, v35
	v_add_f32_e32 v34, v38, v34
	v_add_f32_e32 v34, v39, v34
	s_nop 1
	v_add_f32_dpp v34, v34, v34 quad_perm:[1,0,3,2] row_mask:0xf bank_mask:0xf bound_ctrl:1
	s_nop 1
	v_add_f32_dpp v34, v34, v34 quad_perm:[2,3,0,1] row_mask:0xf bank_mask:0xf bound_ctrl:1
	s_nop 1
	v_add_f32_dpp v34, v34, v34 row_half_mirror row_mask:0xf bank_mask:0xf bound_ctrl:1
	s_nop 1
	v_add_f32_dpp v34, v34, v34 row_mirror row_mask:0xf bank_mask:0xf bound_ctrl:1
	v_mov_b32_e32 v35, v34
	s_nop 1
	v_permlane16_swap_b32_e32 v34, v35
	v_add_f32_e32 v34, v34, v35
	v_mov_b32_e32 v35, v34
	s_nop 1
	v_permlane32_swap_b32_e32 v34, v35
	v_add_f32_e32 v34, v34, v35
	v_fmamk_f32 v34, v34, 0x3b000000, v218
	v_cmp_gt_f32_e32 vcc, s30, v34
	v_mul_f32_e32 v35, 0x4f800000, v34
	s_nop 0
	v_cndmask_b32_e32 v34, v34, v35, vcc
	v_sqrt_f32_e32 v35, v34
	s_nop 0
	v_add_u32_e32 v38, -1, v35
	v_fma_f32 v39, -v38, v35, v34
	v_cmp_ge_f32_e64 s[42:43], 0, v39
	v_add_u32_e32 v39, 1, v35
	s_nop 0
	v_cndmask_b32_e64 v38, v35, v38, s[42:43]
	v_fma_f32 v35, -v39, v35, v34
	v_cmp_lt_f32_e64 s[42:43], 0, v35
	s_nop 1
	v_cndmask_b32_e64 v35, v38, v39, s[42:43]
	v_mul_f32_e32 v38, 0x37800000, v35
	v_cndmask_b32_e32 v35, v35, v38, vcc
	v_cmp_class_f32_e32 vcc, v34, v215
	s_nop 1
	v_cndmask_b32_e32 v34, v35, v34, vcc
	v_div_scale_f32 v35, s[0:1], v34, v34, 1.0
	v_rcp_f32_e32 v38, v35
	s_nop 0
	v_fma_f32 v39, -v35, v38, 1.0
	v_fmac_f32_e32 v38, v39, v38
	v_div_scale_f32 v39, vcc, 1.0, v34, 1.0
	v_mul_f32_e32 v42, v39, v38
	v_fma_f32 v43, -v35, v42, v39
	v_fmac_f32_e32 v42, v43, v38
	v_fma_f32 v35, -v35, v42, v39
	v_div_fmas_f32 v35, v35, v38, v42
	v_div_fixup_f32 v34, v35, v34, 1.0
	v_pk_mul_f32 v[28:29], v[34:35], v[28:29] op_sel_hi:[0,1]
	v_pk_mul_f32 v[30:31], v[34:35], v[30:31] op_sel_hi:[0,1]
	v_pk_mul_f32 v[32:33], v[34:35], v[32:33] op_sel_hi:[0,1]
	v_pk_mul_f32 v[28:29], v[44:45], v[28:29]
	v_pk_mul_f32 v[36:37], v[34:35], v[36:37] op_sel_hi:[0,1]
	v_pk_mul_f32 v[30:31], v[46:47], v[30:31]
	v_pk_mul_f32 v[32:33], v[14:15], v[32:33]
	v_pk_mul_f32 v[36:37], v[10:11], v[36:37]
	v_bfe_u32 v34, v31, 16, 1
	v_bfe_u32 v35, v30, 16, 1
	v_bfe_u32 v38, v29, 16, 1
	v_bfe_u32 v39, v28, 16, 1
	v_add3_u32 v28, v28, v39, s63
	v_add3_u32 v29, v29, v38, s63
	v_add3_u32 v30, v30, v35, s63
	v_add3_u32 v31, v31, v34, s63
	v_bfe_u32 v34, v32, 16, 1
	v_bfe_u32 v35, v33, 16, 1
	v_bfe_u32 v38, v36, 16, 1
	v_bfe_u32 v39, v37, 16, 1
	v_add3_u32 v37, v37, v39, s63
	v_add3_u32 v36, v36, v38, s63
	v_add3_u32 v33, v33, v35, s63
	v_add3_u32 v32, v32, v34, s63
	v_lshrrev_b32_e32 v32, 16, v32
	v_lshrrev_b32_e32 v33, 16, v33
	v_lshrrev_b32_e32 v34, 16, v36
	v_lshrrev_b32_e32 v35, 16, v37
	v_and_or_b32 v31, v31, s60, v35
	v_and_or_b32 v30, v30, s60, v34
	v_and_or_b32 v29, v29, s60, v33
	v_and_or_b32 v28, v28, s60, v32
	global_store_dwordx4 v[64:65], v[28:31], off offset:256 sc1
	s_waitcnt vmcnt(13)
	v_lshlrev_b32_e32 v33, 16, v27
	v_lshlrev_b32_e32 v32, 16, v26
	v_lshlrev_b32_e32 v29, 16, v25
	v_lshlrev_b32_e32 v28, 16, v24
	v_pk_mul_f32 v[30:31], v[28:29], v[28:29]
	v_and_b32_e32 v25, 0xffff0000, v25
	v_and_b32_e32 v24, 0xffff0000, v24
	v_pk_fma_f32 v[30:31], v[24:25], v[24:25], v[30:31]
	v_pk_mul_f32 v[34:35], v[32:33], v[32:33]
	v_and_b32_e32 v27, 0xffff0000, v27
	v_and_b32_e32 v26, 0xffff0000, v26
	v_pk_fma_f32 v[34:35], v[26:27], v[26:27], v[34:35]
	v_add_f32_e32 v30, v30, v31
	v_add_f32_e32 v30, v34, v30
	v_add_f32_e32 v30, v35, v30
	s_nop 1
	v_add_f32_dpp v30, v30, v30 quad_perm:[1,0,3,2] row_mask:0xf bank_mask:0xf bound_ctrl:1
	s_nop 1
	v_add_f32_dpp v30, v30, v30 quad_perm:[2,3,0,1] row_mask:0xf bank_mask:0xf bound_ctrl:1
	s_nop 1
	v_add_f32_dpp v30, v30, v30 row_half_mirror row_mask:0xf bank_mask:0xf bound_ctrl:1
	s_nop 1
	v_add_f32_dpp v30, v30, v30 row_mirror row_mask:0xf bank_mask:0xf bound_ctrl:1
	v_mov_b32_e32 v31, v30
	s_nop 1
	v_permlane16_swap_b32_e32 v30, v31
	v_add_f32_e32 v30, v30, v31
	v_mov_b32_e32 v31, v30
	s_nop 1
	v_permlane32_swap_b32_e32 v30, v31
	v_add_f32_e32 v30, v30, v31
	v_fmamk_f32 v30, v30, 0x3b000000, v218
	v_cmp_gt_f32_e32 vcc, s30, v30
	v_mul_f32_e32 v31, 0x4f800000, v30
	s_nop 0
	v_cndmask_b32_e32 v30, v30, v31, vcc
	v_sqrt_f32_e32 v31, v30
	s_nop 0
	v_add_u32_e32 v34, -1, v31
	v_fma_f32 v35, -v34, v31, v30
	v_cmp_ge_f32_e64 s[42:43], 0, v35
	v_add_u32_e32 v35, 1, v31
	s_nop 0
	v_cndmask_b32_e64 v34, v31, v34, s[42:43]
	v_fma_f32 v31, -v35, v31, v30
; __device__ __forceinline__ float bf2f(unsigned h) { return __uint_as_float(h << 16); }
; __device__ __forceinline__ unsigned pk2(float lo, float hi) { return f2bf(lo) | (f2bf(hi) << 16); }
; __device__ __forceinline__ void mla_mid(const bf16_t* __restrict__ wino, const float* __restrict__ gq, const float* __restrict__ gkv, const float* __restrict__ cs_tab, const float* __restrict__ sn_tab, ...
;     ...
;             for (int part = 0; part < 2; ++part) {
;                 float f[8]; float s = 0.f;
; #pragma unroll
;                 for (int e = 0; e < 4; ++e) { f[2 * e] = bf2f(v[rr][part][e] & 0xffffu); f[2 * e + 1] = bf2f(v[rr][part][e] >> 16); s += f[2 * e] * f[2 * e] + f[2 * e + 1] * f[2 * e + 1]; }
;                 const float rstd = 1.0f / sqrtf(wave_sum(s) * (1.f / LORA) + RMS_EPS);
;                 const f32x4 g0 = part == 0 ? gq0 : gk0, g1 = part == 0 ? gq1 : gk1;
;                 v4u o; o.x = pk2(f[0] * rstd * g0[0], f[1] * rstd * g0[1]); o.y = pk2(f[2] * rstd * g0[2], f[3] * rstd * g0[3]);
;                 o.z = pk2(f[4] * rstd * g1[0], f[5] * rstd * g1[1]); o.w = pk2(f[6] * rstd * g1[2], f[7] * rstd * g1[3]);
;                 *(v4u*)((part == 0 ? cqn : ckvn) + ((size_t)(lane >> 3) * M_TOK + m) * 64 + (lane & 7) * 8) = o;
;             }
;             if (lane < 32) { const float x1 = bf2f(w[rr] & 0xffffu), x2 = bf2f(w[rr] >> 16);
;                 *(unsigned*)(kr + (size_t)m * 64 + 2 * lane) = pk2(x1 * cc[rr] - x2 * ss[rr], x1 * ss[rr] + x2 * cc[rr]); }
	v_cmp_lt_f32_e64 s[42:43], 0, v31
	s_nop 1
	v_cndmask_b32_e64 v31, v34, v35, s[42:43]
	v_mul_f32_e32 v34, 0x37800000, v31
	v_cndmask_b32_e32 v31, v31, v34, vcc
	v_cmp_class_f32_e32 vcc, v30, v215
	s_nop 1
	v_cndmask_b32_e32 v30, v31, v30, vcc
	v_div_scale_f32 v31, s[0:1], v30, v30, 1.0
	v_rcp_f32_e32 v34, v31
	s_nop 0
	v_fma_f32 v35, -v31, v34, 1.0
	v_fmac_f32_e32 v34, v35, v34
	v_div_scale_f32 v35, vcc, 1.0, v30, 1.0
	v_mul_f32_e32 v36, v35, v34
	v_fma_f32 v37, -v31, v36, v35
	v_fmac_f32_e32 v36, v37, v34
	v_fma_f32 v31, -v31, v36, v35
	v_div_fmas_f32 v31, v31, v34, v36
	v_div_fixup_f32 v30, v31, v30, 1.0
	v_pk_mul_f32 v[26:27], v[30:31], v[26:27] op_sel_hi:[0,1]
	v_pk_mul_f32 v[28:29], v[30:31], v[28:29] op_sel_hi:[0,1]
	v_pk_mul_f32 v[24:25], v[30:31], v[24:25] op_sel_hi:[0,1]
	v_pk_mul_f32 v[26:27], v[8:9], v[26:27]
	v_pk_mul_f32 v[28:29], v[6:7], v[28:29]
	v_pk_mul_f32 v[24:25], v[12:13], v[24:25]
	v_pk_mul_f32 v[32:33], v[30:31], v[32:33] op_sel_hi:[0,1]
	v_bfe_u32 v30, v27, 16, 1
	v_pk_mul_f32 v[32:33], v[2:3], v[32:33]
	v_bfe_u32 v31, v26, 16, 1
	v_bfe_u32 v34, v25, 16, 1
	v_bfe_u32 v35, v24, 16, 1
	v_add3_u32 v27, v27, v30, s63
	v_bfe_u32 v30, v28, 16, 1
	v_add3_u32 v24, v24, v35, s63
	v_add3_u32 v25, v25, v34, s63
	v_add3_u32 v26, v26, v31, s63
	v_bfe_u32 v31, v29, 16, 1
	v_bfe_u32 v34, v32, 16, 1
	v_bfe_u32 v35, v33, 16, 1
	v_add3_u32 v28, v28, v30, s63
	v_add3_u32 v33, v33, v35, s63
	v_add3_u32 v32, v32, v34, s63
	v_add3_u32 v29, v29, v31, s63
	v_lshrrev_b32_e32 v28, 16, v28
	v_lshrrev_b32_e32 v29, 16, v29
	v_lshrrev_b32_e32 v30, 16, v32
	v_lshrrev_b32_e32 v31, 16, v33
	v_and_or_b32 v24, v24, s60, v28
	v_add_co_u32_e32 v28, vcc, 0x1e000000, v58
	v_and_or_b32 v27, v27, s60, v31
	v_and_or_b32 v26, v26, s60, v30
	v_and_or_b32 v25, v25, s60, v29
	v_addc_co_u32_e32 v29, vcc, 0, v59, vcc
	global_store_dwordx4 v[28:29], v[24:27], off offset:256 sc1
	s_and_saveexec_b64 s[6:7], s[40:41]
	s_cbranch_execz .LBB0_218
	s_waitcnt vmcnt(13)
	v_lshlrev_b32_e32 v25, 16, v57
	v_and_b32_e32 v24, 0xffff0000, v57
	s_waitcnt vmcnt(11)
	v_pk_mul_f32 v[26:27], v[62:63], v[24:25] op_sel:[0,1] op_sel_hi:[0,0]
	v_pk_fma_f32 v[28:29], v[60:61], v[24:25], v[26:27]
	v_pk_fma_f32 v[24:25], v[60:61], v[24:25], v[26:27] op_sel_hi:[0,1,1] neg_lo:[0,0,1] neg_hi:[0,0,1]
	v_and_b32_sdwa v24, v25, v217 dst_sel:DWORD dst_unused:UNUSED_PAD src0_sel:WORD_1 src1_sel:DWORD
	v_and_b32_sdwa v26, v28, v217 dst_sel:DWORD dst_unused:UNUSED_PAD src0_sel:WORD_1 src1_sel:DWORD
	v_add3_u32 v24, v25, v24, s63
	v_add3_u32 v26, v28, v26, s63
	v_lshrrev_b32_e32 v24, 16, v24
	v_and_or_b32 v24, v26, s60, v24
	global_store_dword v[40:41], v24, off
.LBB0_218:
	s_or_b64 exec, exec, s[6:7]
	s_waitcnt vmcnt(10)
	v_lshlrev_b32_e32 v25, 16, v21
	v_lshlrev_b32_e32 v24, 16, v20
	v_pk_mul_f32 v[26:27], v[24:25], v[24:25]
	v_and_b32_e32 v21, 0xffff0000, v21
	v_and_b32_e32 v20, 0xffff0000, v20
	v_lshlrev_b32_e32 v29, 16, v23
	v_lshlrev_b32_e32 v28, 16, v22
	v_pk_fma_f32 v[26:27], v[20:21], v[20:21], v[26:27]
	v_pk_mul_f32 v[30:31], v[28:29], v[28:29]
	v_and_b32_e32 v23, 0xffff0000, v23
	v_and_b32_e32 v22, 0xffff0000, v22
	v_pk_fma_f32 v[30:31], v[22:23], v[22:23], v[30:31]
	v_add_f32_e32 v26, v26, v27
	v_add_f32_e32 v26, v30, v26
	v_add_f32_e32 v26, v31, v26
	s_nop 1
	v_add_f32_dpp v26, v26, v26 quad_perm:[1,0,3,2] row_mask:0xf bank_mask:0xf bound_ctrl:1
	s_nop 1
	v_add_f32_dpp v26, v26, v26 quad_perm:[2,3,0,1] row_mask:0xf bank_mask:0xf bound_ctrl:1
	s_nop 1
	v_add_f32_dpp v26, v26, v26 row_half_mirror row_mask:0xf bank_mask:0xf bound_ctrl:1
	s_nop 1
	v_add_f32_dpp v26, v26, v26 row_mirror row_mask:0xf bank_mask:0xf bound_ctrl:1
	v_mov_b32_e32 v27, v26
	s_nop 1
	v_permlane16_swap_b32_e32 v26, v27
	v_add_f32_e32 v26, v26, v27
	v_mov_b32_e32 v27, v26
	s_nop 1
	v_permlane32_swap_b32_e32 v26, v27
	v_add_f32_e32 v26, v26, v27
	v_fmamk_f32 v26, v26, 0x3b000000, v218
	v_cmp_gt_f32_e32 vcc, s30, v26
	v_mul_f32_e32 v27, 0x4f800000, v26
	s_nop 0
	v_cndmask_b32_e32 v26, v26, v27, vcc
	v_sqrt_f32_e32 v27, v26
	s_nop 0
	v_add_u32_e32 v30, -1, v27
	v_fma_f32 v31, -v30, v27, v26
	v_cmp_ge_f32_e64 s[42:43], 0, v31
	v_add_u32_e32 v31, 1, v27
	s_nop 0
	v_cndmask_b32_e64 v30, v27, v30, s[42:43]
	v_fma_f32 v27, -v31, v27, v26
	v_cmp_lt_f32_e64 s[42:43], 0, v27
	s_nop 1
	v_cndmask_b32_e64 v27, v30, v31, s[42:43]
	v_mul_f32_e32 v30, 0x37800000, v27
	v_cndmask_b32_e32 v27, v27, v30, vcc
	v_cmp_class_f32_e32 vcc, v26, v215
	s_nop 1
	v_cndmask_b32_e32 v26, v27, v26, vcc
	v_div_scale_f32 v27, s[0:1], v26, v26, 1.0
	v_rcp_f32_e32 v30, v27
	s_nop 0
	v_fma_f32 v31, -v27, v30, 1.0
	v_fmac_f32_e32 v30, v31, v30
	v_div_scale_f32 v31, vcc, 1.0, v26, 1.0
	v_mul_f32_e32 v32, v31, v30
	v_fma_f32 v33, -v27, v32, v31
	v_fmac_f32_e32 v32, v33, v30
	v_fma_f32 v27, -v27, v32, v31
	v_div_fmas_f32 v27, v27, v30, v32
	v_div_fixup_f32 v26, v27, v26, 1.0
	v_pk_mul_f32 v[20:21], v[26:27], v[20:21] op_sel_hi:[0,1]
	v_pk_mul_f32 v[22:23], v[26:27], v[22:23] op_sel_hi:[0,1]
	v_pk_mul_f32 v[24:25], v[26:27], v[24:25] op_sel_hi:[0,1]
	v_pk_mul_f32 v[20:21], v[44:45], v[20:21]
	v_pk_mul_f32 v[28:29], v[26:27], v[28:29] op_sel_hi:[0,1]
	v_pk_mul_f32 v[22:23], v[46:47], v[22:23]
	v_pk_mul_f32 v[24:25], v[14:15], v[24:25]
	v_pk_mul_f32 v[28:29], v[10:11], v[28:29]
	v_bfe_u32 v26, v23, 16, 1
	v_bfe_u32 v27, v22, 16, 1
	v_bfe_u32 v30, v21, 16, 1
	v_bfe_u32 v31, v20, 16, 1
	v_add3_u32 v20, v20, v31, s63
	v_add3_u32 v21, v21, v30, s63
	v_add3_u32 v22, v22, v27, s63
	v_add3_u32 v23, v23, v26, s63
	v_bfe_u32 v26, v24, 16, 1
	v_bfe_u32 v27, v25, 16, 1
	v_bfe_u32 v30, v28, 16, 1
	v_bfe_u32 v31, v29, 16, 1
	v_add3_u32 v29, v29, v31, s63
	v_add3_u32 v28, v28, v30, s63
	v_add3_u32 v25, v25, v27, s63
	v_add3_u32 v24, v24, v26, s63
	v_lshrrev_b32_e32 v24, 16, v24
	v_lshrrev_b32_e32 v25, 16, v25
	v_lshrrev_b32_e32 v26, 16, v28
	v_lshrrev_b32_e32 v27, 16, v29
	v_and_or_b32 v23, v23, s60, v27
	v_and_or_b32 v22, v22, s60, v26
	v_and_or_b32 v21, v21, s60, v25
	v_and_or_b32 v20, v20, s60, v24
	global_store_dwordx4 v[64:65], v[20:23], off offset:384 sc1
	s_waitcnt vmcnt(10)
; __device__ __forceinline__ float bf2f(unsigned h) { return __uint_as_float(h << 16); }
; __device__ __forceinline__ unsigned pk2(float lo, float hi) { return f2bf(lo) | (f2bf(hi) << 16); }
; __device__ __forceinline__ void mla_mid(const bf16_t* __restrict__ wino, const float* __restrict__ gq, const float* __restrict__ gkv, const float* __restrict__ cs_tab, const float* __restrict__ sn_tab, ...
;     ...
;             for (int part = 0; part < 2; ++part) {
;                 float f[8]; float s = 0.f;
; #pragma unroll
;                 for (int e = 0; e < 4; ++e) { f[2 * e] = bf2f(v[rr][part][e] & 0xffffu); f[2 * e + 1] = bf2f(v[rr][part][e] >> 16); s += f[2 * e] * f[2 * e] + f[2 * e + 1] * f[2 * e + 1]; }
;                 const float rstd = 1.0f / sqrtf(wave_sum(s) * (1.f / LORA) + RMS_EPS);
;                 const f32x4 g0 = part == 0 ? gq0 : gk0, g1 = part == 0 ? gq1 : gk1;
;                 v4u o; o.x = pk2(f[0] * rstd * g0[0], f[1] * rstd * g0[1]); o.y = pk2(f[2] * rstd * g0[2], f[3] * rstd * g0[3]);
;                 o.z = pk2(f[4] * rstd * g1[0], f[5] * rstd * g1[1]); o.w = pk2(f[6] * rstd * g1[2], f[7] * rstd * g1[3]);
;                 *(v4u*)((part == 0 ? cqn : ckvn) + ((size_t)(lane >> 3) * M_TOK + m) * 64 + (lane & 7) * 8) = o;
;             }
;             if (lane < 32) { const float x1 = bf2f(w[rr] & 0xffffu), x2 = bf2f(w[rr] >> 16);
;                 *(unsigned*)(kr + (size_t)m * 64 + 2 * lane) = pk2(x1 * cc[rr] - x2 * ss[rr], x1 * ss[rr] + x2 * cc[rr]); }
;         }
	v_lshlrev_b32_e32 v25, 16, v19
	v_lshlrev_b32_e32 v24, 16, v18
	v_lshlrev_b32_e32 v21, 16, v17
	v_lshlrev_b32_e32 v20, 16, v16
	v_pk_mul_f32 v[22:23], v[20:21], v[20:21]
	v_and_b32_e32 v17, 0xffff0000, v17
	v_and_b32_e32 v16, 0xffff0000, v16
	v_pk_fma_f32 v[22:23], v[16:17], v[16:17], v[22:23]
	v_pk_mul_f32 v[26:27], v[24:25], v[24:25]
	v_and_b32_e32 v19, 0xffff0000, v19
	v_and_b32_e32 v18, 0xffff0000, v18
	v_pk_fma_f32 v[26:27], v[18:19], v[18:19], v[26:27]
	v_add_f32_e32 v22, v22, v23
	v_add_f32_e32 v22, v26, v22
	v_add_f32_e32 v22, v27, v22
	s_nop 1
	v_add_f32_dpp v22, v22, v22 quad_perm:[1,0,3,2] row_mask:0xf bank_mask:0xf bound_ctrl:1
	s_nop 1
	v_add_f32_dpp v22, v22, v22 quad_perm:[2,3,0,1] row_mask:0xf bank_mask:0xf bound_ctrl:1
	s_nop 1
	v_add_f32_dpp v22, v22, v22 row_half_mirror row_mask:0xf bank_mask:0xf bound_ctrl:1
	s_nop 1
	v_add_f32_dpp v22, v22, v22 row_mirror row_mask:0xf bank_mask:0xf bound_ctrl:1
	v_mov_b32_e32 v23, v22
	s_nop 1
	v_permlane16_swap_b32_e32 v22, v23
	v_add_f32_e32 v22, v22, v23
	v_mov_b32_e32 v23, v22
	s_nop 1
	v_permlane32_swap_b32_e32 v22, v23
	v_add_f32_e32 v22, v22, v23
	v_fmamk_f32 v22, v22, 0x3b000000, v218
	v_cmp_gt_f32_e32 vcc, s30, v22
	v_mul_f32_e32 v23, 0x4f800000, v22
	s_nop 0
	v_cndmask_b32_e32 v22, v22, v23, vcc
	v_sqrt_f32_e32 v23, v22
	s_nop 0
	v_add_u32_e32 v26, -1, v23
	v_fma_f32 v27, -v26, v23, v22
	v_cmp_ge_f32_e64 s[42:43], 0, v27
	v_add_u32_e32 v27, 1, v23
	s_nop 0
	v_cndmask_b32_e64 v26, v23, v26, s[42:43]
	v_fma_f32 v23, -v27, v23, v22
	v_cmp_lt_f32_e64 s[42:43], 0, v23
	s_nop 1
	v_cndmask_b32_e64 v23, v26, v27, s[42:43]
	v_mul_f32_e32 v26, 0x37800000, v23
	v_cndmask_b32_e32 v23, v23, v26, vcc
	v_cmp_class_f32_e32 vcc, v22, v215
	s_nop 1
	v_cndmask_b32_e32 v22, v23, v22, vcc
	v_div_scale_f32 v23, s[0:1], v22, v22, 1.0
	v_rcp_f32_e32 v26, v23
	s_nop 0
	v_fma_f32 v27, -v23, v26, 1.0
	v_fmac_f32_e32 v26, v27, v26
	v_div_scale_f32 v27, vcc, 1.0, v22, 1.0
	v_mul_f32_e32 v28, v27, v26
	v_fma_f32 v29, -v23, v28, v27
	v_fmac_f32_e32 v28, v29, v26
	v_fma_f32 v23, -v23, v28, v27
	v_div_fmas_f32 v23, v23, v26, v28
	v_div_fixup_f32 v22, v23, v22, 1.0
	v_pk_mul_f32 v[18:19], v[22:23], v[18:19] op_sel_hi:[0,1]
	v_pk_mul_f32 v[20:21], v[22:23], v[20:21] op_sel_hi:[0,1]
	v_pk_mul_f32 v[16:17], v[22:23], v[16:17] op_sel_hi:[0,1]
	v_pk_mul_f32 v[18:19], v[8:9], v[18:19]
	v_pk_mul_f32 v[20:21], v[6:7], v[20:21]
	v_pk_mul_f32 v[16:17], v[12:13], v[16:17]
	v_pk_mul_f32 v[24:25], v[22:23], v[24:25] op_sel_hi:[0,1]
	v_bfe_u32 v22, v19, 16, 1
	v_pk_mul_f32 v[24:25], v[2:3], v[24:25]
	v_bfe_u32 v23, v18, 16, 1
	v_bfe_u32 v26, v17, 16, 1
	v_bfe_u32 v27, v16, 16, 1
	v_add3_u32 v19, v19, v22, s63
	v_bfe_u32 v22, v20, 16, 1
	v_add3_u32 v16, v16, v27, s63
	v_add3_u32 v17, v17, v26, s63
	v_add3_u32 v18, v18, v23, s63
	v_bfe_u32 v23, v21, 16, 1
	v_bfe_u32 v26, v24, 16, 1
	v_bfe_u32 v27, v25, 16, 1
	v_add3_u32 v20, v20, v22, s63
	v_add3_u32 v25, v25, v27, s63
	v_add3_u32 v24, v24, v26, s63
	v_add3_u32 v21, v21, v23, s63
	v_lshrrev_b32_e32 v20, 16, v20
	v_lshrrev_b32_e32 v21, 16, v21
	v_lshrrev_b32_e32 v22, 16, v24
	v_lshrrev_b32_e32 v23, 16, v25
	v_and_or_b32 v16, v16, s60, v20
	v_add_co_u32_e32 v20, vcc, 0x1e000000, v58
	v_and_or_b32 v19, v19, s60, v23
	v_and_or_b32 v18, v18, s60, v22
	v_and_or_b32 v17, v17, s60, v21
	v_addc_co_u32_e32 v21, vcc, 0, v59, vcc
	global_store_dwordx4 v[20:21], v[16:19], off offset:384 sc1
	s_and_saveexec_b64 s[6:7], s[40:41]
	s_cbranch_execz .LBB0_211
	s_waitcnt vmcnt(10)
	v_lshlrev_b32_e32 v17, 16, v55
	v_and_b32_e32 v16, 0xffff0000, v55
	s_waitcnt vmcnt(8)
	v_pk_mul_f32 v[18:19], v[56:57], v[16:17] op_sel:[0,1] op_sel_hi:[0,0]
	v_pk_fma_f32 v[20:21], v[54:55], v[16:17], v[18:19]
	v_pk_fma_f32 v[16:17], v[54:55], v[16:17], v[18:19] op_sel_hi:[0,1,1] neg_lo:[0,0,1] neg_hi:[0,0,1]
	v_and_b32_sdwa v16, v17, v217 dst_sel:DWORD dst_unused:UNUSED_PAD src0_sel:WORD_1 src1_sel:DWORD
	v_and_b32_sdwa v18, v20, v217 dst_sel:DWORD dst_unused:UNUSED_PAD src0_sel:WORD_1 src1_sel:DWORD
	v_add3_u32 v16, v17, v16, s63
	v_add3_u32 v18, v20, v18, s63
	v_lshrrev_b32_e32 v16, 16, v16
	v_and_or_b32 v16, v18, s60, v16
	global_store_dword v[40:41], v16, off offset:128
	s_branch .LBB0_211

; __device__ __forceinline__ float bf2f(unsigned h) { return __uint_as_float(h << 16); }
; template <int MODE> ...
;     for (int m = RPW * gw; m < M_TOK; m += RPW * NGW) {
;         f32x4 xv[RPW][8]; v2u yy[RPW][8];
; #pragma unroll
;         for (int rr = 0; rr < RPW; ++rr) {
;             const float* xr = ((MODE == 0 || xin != nullptr) ? xin : xres) + (size_t)(m + rr) * DM + lane * 4;
; #pragma unroll
;             for (int k = 0; k < 8; ++k) xv[rr][k] = *(const f32x4*)(xr + k * 256);
;             if (MODE >= 1) { const bf16_t* yr = y + (size_t)(m + rr) * 256 + lane * 4;
; #pragma unroll
;                 for (int k = 0; k < 8; ++k) yy[rr][k] = *(const v2u*)(yr + (size_t)k * ((size_t)M_TOK * 256)); }
;         }
;         if (MODE >= 1) {
;             float rstd[RPW];
; #pragma unroll
;             for (int rr = 0; rr < RPW; ++rr) { float s = 0.f;
; #pragma unroll
;                 for (int k = 0; k < 8; ++k)
; #pragma unroll
;                     for (int e = 0; e < 2; ++e) { const float a = bf2f(yy[rr][k][e] & 0xffffu), b = bf2f(yy[rr][k][e] >> 16); s += a * a + b * b; }
;                 rstd[rr] = 1.0f / sqrtf(wave_sum(s) * (1.f / DM) + RMS_EPS); }
.LBB0_225:
	v_lshl_add_u64 v[98:99], s[64:65], 0, v[146:147]
	v_add_co_u32_e32 v66, vcc, 0x1000, v98
	v_lshl_add_u64 v[100:101], v[150:151], 0, s[46:47]
	s_nop 0
	v_addc_co_u32_e32 v67, vcc, 0, v99, vcc
	v_add_co_u32_e32 v114, vcc, 0x8800000, v100
	global_load_dwordx4 v[94:97], v[98:99], off
	global_load_dwordx4 v[90:93], v[98:99], off offset:1024
	global_load_dwordx4 v[86:89], v[98:99], off offset:2048
	global_load_dwordx4 v[82:85], v[98:99], off offset:3072
	v_addc_co_u32_e32 v115, vcc, 0, v101, vcc
	global_load_dwordx4 v[78:81], v[66:67], off
	global_load_dwordx4 v[74:77], v[66:67], off offset:1024
	global_load_dwordx4 v[70:73], v[66:67], off offset:2048
	s_nop 0
	global_load_dwordx4 v[66:69], v[66:67], off offset:3072
	v_add_co_u32_e32 v118, vcc, 0x9000000, v100
	global_load_dwordx2 v[116:117], v[114:115], off
	s_nop 0
	v_addc_co_u32_e32 v119, vcc, 0, v101, vcc
	global_load_dwordx2 v[120:121], v[118:119], off
	v_add_co_u32_e32 v122, vcc, 0x9800000, v100
	s_add_i32 s42, s42, s18
	s_nop 0
	v_addc_co_u32_e32 v123, vcc, 0, v101, vcc
	global_load_dwordx2 v[124:125], v[122:123], off
	v_add_co_u32_e32 v126, vcc, 0xa000000, v100
	v_lshl_add_u64 v[150:151], v[150:151], 0, s[22:23]
	s_nop 0
	v_addc_co_u32_e32 v127, vcc, 0, v101, vcc
	global_load_dwordx2 v[128:129], v[126:127], off
	v_add_co_u32_e32 v152, vcc, 0xa800000, v100
	s_waitcnt vmcnt(3)
	v_lshlrev_b32_e32 v168, 16, v116
	v_addc_co_u32_e32 v153, vcc, 0, v101, vcc
	global_load_dwordx2 v[154:155], v[152:153], off
	v_add_co_u32_e32 v156, vcc, 0xb000000, v100
	v_and_b32_e32 v169, 0xffff0000, v116
	s_nop 0
	v_addc_co_u32_e32 v157, vcc, 0, v101, vcc
	global_load_dwordx2 v[158:159], v[156:157], off
	v_add_co_u32_e32 v160, vcc, 0xb800000, v100
	v_lshlrev_b32_e32 v116, 16, v117
	s_nop 0
	v_addc_co_u32_e32 v161, vcc, 0, v101, vcc
	global_load_dwordx2 v[162:163], v[160:161], off
	v_add_co_u32_e32 v164, vcc, 0xc000000, v100
	v_and_b32_e32 v117, 0xffff0000, v117
	s_nop 0
	v_addc_co_u32_e32 v165, vcc, 0, v101, vcc
	global_load_dwordx2 v[166:167], v[164:165], off
	v_add_co_u32_e32 v100, vcc, s31, v98
	v_mul_f32_e32 v1, v169, v169
	s_nop 0
	v_addc_co_u32_e32 v101, vcc, 0, v99, vcc
	v_add_co_u32_e32 v130, vcc, s33, v98
	v_mul_f32_e32 v170, v117, v117
	s_nop 0
	v_addc_co_u32_e32 v131, vcc, 0, v99, vcc
	global_load_dwordx4 v[110:113], v[130:131], off offset:-4096
	global_load_dwordx4 v[106:109], v[100:101], off offset:1024
	global_load_dwordx4 v[102:105], v[100:101], off offset:2048
	s_nop 0
	global_load_dwordx4 v[98:101], v[100:101], off offset:3072
	s_nop 0
	global_load_dwordx4 v[142:145], v[130:131], off
	global_load_dwordx4 v[138:141], v[130:131], off offset:1024
	global_load_dwordx4 v[134:137], v[130:131], off offset:2048
	s_nop 0
	global_load_dwordx4 v[130:133], v[130:131], off offset:3072
	s_nop 0
	global_load_dwordx2 v[114:115], v[114:115], off offset:512
	s_nop 0
	global_load_dwordx2 v[118:119], v[118:119], off offset:512
	s_nop 0
	global_load_dwordx2 v[122:123], v[122:123], off offset:512
	s_nop 0
	global_load_dwordx2 v[126:127], v[126:127], off offset:512
	s_nop 0
	global_load_dwordx2 v[152:153], v[152:153], off offset:512
	s_nop 0
	global_load_dwordx2 v[156:157], v[156:157], off offset:512
	s_nop 0
	global_load_dwordx2 v[160:161], v[160:161], off offset:512
	s_nop 0
	global_load_dwordx2 v[164:165], v[164:165], off offset:512
	v_fmac_f32_e32 v1, v168, v168
	v_fmac_f32_e32 v170, v116, v116
	s_waitcnt vmcnt(22)
	v_and_b32_e32 v171, 0xffff0000, v120
	v_add_f32_e32 v1, v1, v170
	v_lshlrev_b32_e32 v170, 16, v120
	v_mul_f32_e32 v120, v171, v171
	v_fmac_f32_e32 v120, v170, v170
	v_add_f32_e32 v1, v1, v120
	v_lshlrev_b32_e32 v120, 16, v121
	v_and_b32_e32 v121, 0xffff0000, v121
	v_mul_f32_e32 v172, v121, v121
	v_fmac_f32_e32 v172, v120, v120
	s_waitcnt vmcnt(21)
	v_and_b32_e32 v173, 0xffff0000, v124
	v_add_f32_e32 v1, v172, v1
	v_lshlrev_b32_e32 v172, 16, v124
	v_mul_f32_e32 v124, v173, v173
	v_fmac_f32_e32 v124, v172, v172
	v_and_b32_e32 v175, 0xffff0000, v125
	v_add_f32_e32 v1, v124, v1
	v_lshlrev_b32_e32 v174, 16, v125
	v_mul_f32_e32 v124, v175, v175
	v_fmac_f32_e32 v124, v174, v174
	s_waitcnt vmcnt(20)
	v_and_b32_e32 v177, 0xffff0000, v128
	v_add_f32_e32 v1, v124, v1
	v_lshlrev_b32_e32 v176, 16, v128
	v_mul_f32_e32 v124, v177, v177
	v_fmac_f32_e32 v124, v176, v176
	v_and_b32_e32 v179, 0xffff0000, v129
	v_add_f32_e32 v1, v124, v1
	v_lshlrev_b32_e32 v178, 16, v129
	v_mul_f32_e32 v124, v179, v179
	v_fmac_f32_e32 v124, v178, v178
	v_add_f32_e32 v1, v124, v1
	s_waitcnt vmcnt(19)
	v_and_b32_e32 v181, 0xffff0000, v154
	v_lshlrev_b32_e32 v180, 16, v154
	v_mul_f32_e32 v124, v181, v181
	v_fmac_f32_e32 v124, v180, v180
	v_lshlrev_b32_e32 v154, 16, v155
	v_and_b32_e32 v155, 0xffff0000, v155
	v_add_f32_e32 v1, v124, v1
	v_mul_f32_e32 v124, v155, v155
	v_fmac_f32_e32 v124, v154, v154
	s_waitcnt vmcnt(18)
	v_and_b32_e32 v183, 0xffff0000, v158
	v_add_f32_e32 v1, v124, v1
	v_lshlrev_b32_e32 v182, 16, v158
	v_mul_f32_e32 v124, v183, v183
	v_fmac_f32_e32 v124, v182, v182
	v_lshlrev_b32_e32 v158, 16, v159
	v_and_b32_e32 v159, 0xffff0000, v159
	v_add_f32_e32 v1, v124, v1
	v_mul_f32_e32 v124, v159, v159
	v_fmac_f32_e32 v124, v158, v158
	s_waitcnt vmcnt(17)
	v_and_b32_e32 v185, 0xffff0000, v162
	v_add_f32_e32 v1, v124, v1
	v_lshlrev_b32_e32 v184, 16, v162
	v_mul_f32_e32 v124, v185, v185
	v_fmac_f32_e32 v124, v184, v184
	v_lshlrev_b32_e32 v162, 16, v163
	v_and_b32_e32 v163, 0xffff0000, v163
	v_add_f32_e32 v1, v124, v1
	v_mul_f32_e32 v124, v163, v163
	v_fmac_f32_e32 v124, v162, v162
	s_waitcnt vmcnt(16)
; __device__ __forceinline__ float bf2f(unsigned h) { return __uint_as_float(h << 16); }
; template <int MODE> ...
;     ...
;         if (MODE >= 1) {
;             float rstd[RPW];
; #pragma unroll
;             for (int rr = 0; rr < RPW; ++rr) { float s = 0.f;
; #pragma unroll
;                 for (int k = 0; k < 8; ++k)
; #pragma unroll
;                     for (int e = 0; e < 2; ++e) { const float a = bf2f(yy[rr][k][e] & 0xffffu), b = bf2f(yy[rr][k][e] >> 16); s += a * a + b * b; }
;                 rstd[rr] = 1.0f / sqrtf(wave_sum(s) * (1.f / DM) + RMS_EPS); }
	v_and_b32_e32 v187, 0xffff0000, v166
	v_add_f32_e32 v1, v124, v1
	v_lshlrev_b32_e32 v186, 16, v166
	v_mul_f32_e32 v124, v187, v187
	v_fmac_f32_e32 v124, v186, v186
	v_lshlrev_b32_e32 v166, 16, v167
	v_and_b32_e32 v167, 0xffff0000, v167
	v_add_f32_e32 v1, v124, v1
	v_mul_f32_e32 v124, v167, v167
	v_fmac_f32_e32 v124, v166, v166
	v_add_f32_e32 v1, v124, v1
	s_waitcnt vmcnt(6)
	v_and_b32_e32 v191, 0xffff0000, v118
	v_lshlrev_b32_e32 v190, 16, v118
	v_add_f32_dpp v1, v1, v1 quad_perm:[1,0,3,2] row_mask:0xf bank_mask:0xf bound_ctrl:1
	v_mul_f32_e32 v118, v191, v191
	v_fmac_f32_e32 v118, v190, v190
	v_add_f32_dpp v1, v1, v1 quad_perm:[2,3,0,1] row_mask:0xf bank_mask:0xf bound_ctrl:1
	v_and_b32_e32 v193, 0xffff0000, v119
	v_lshlrev_b32_e32 v192, 16, v119
	v_add_f32_dpp v1, v1, v1 row_half_mirror row_mask:0xf bank_mask:0xf bound_ctrl:1
	s_waitcnt vmcnt(5)
	v_and_b32_e32 v195, 0xffff0000, v122
	v_lshlrev_b32_e32 v194, 16, v122
	v_add_f32_dpp v1, v1, v1 row_mirror row_mask:0xf bank_mask:0xf bound_ctrl:1
	v_mov_b32_e32 v124, v1
	s_nop 1
	v_permlane16_swap_b32_e32 v1, v124
	v_add_f32_e32 v1, v1, v124
	v_mov_b32_e32 v124, v1
	s_nop 1
	v_permlane32_swap_b32_e32 v1, v124
	v_add_f32_e32 v1, v1, v124
	v_fmamk_f32 v1, v1, 0x3a000000, v218
	v_cmp_gt_f32_e32 vcc, s30, v1
	v_mul_f32_e32 v124, 0x4f800000, v1
	v_and_b32_e32 v197, 0xffff0000, v123
	v_cndmask_b32_e32 v1, v1, v124, vcc
	v_sqrt_f32_e32 v124, v1
	v_lshlrev_b32_e32 v196, 16, v123
	s_waitcnt vmcnt(4)
	v_and_b32_e32 v199, 0xffff0000, v126
	v_lshlrev_b32_e32 v198, 16, v126
	v_add_u32_e32 v125, -1, v124
	v_fma_f32 v128, -v125, v124, v1
	v_cmp_ge_f32_e64 s[40:41], 0, v128
	v_add_u32_e32 v128, 1, v124
	v_and_b32_e32 v201, 0xffff0000, v127
	v_cndmask_b32_e64 v125, v124, v125, s[40:41]
	v_fma_f32 v124, -v128, v124, v1
	v_cmp_lt_f32_e64 s[40:41], 0, v124
	v_lshlrev_b32_e32 v200, 16, v127
	s_waitcnt vmcnt(3)
	v_and_b32_e32 v203, 0xffff0000, v152
	v_cndmask_b32_e64 v124, v125, v128, s[40:41]
	v_mul_f32_e32 v125, 0x37800000, v124
	v_cndmask_b32_e32 v124, v124, v125, vcc
	v_cmp_class_f32_e32 vcc, v1, v215
	v_lshlrev_b32_e32 v202, 16, v152
	v_lshlrev_b32_e32 v152, 16, v153
	v_cndmask_b32_e32 v1, v124, v1, vcc
	v_div_scale_f32 v124, s[0:1], v1, v1, 1.0
	v_rcp_f32_e32 v125, v124
	v_and_b32_e32 v153, 0xffff0000, v153
	s_waitcnt vmcnt(2)
	v_and_b32_e32 v205, 0xffff0000, v156
	v_lshlrev_b32_e32 v204, 16, v156
	v_fma_f32 v128, -v124, v125, 1.0
	v_fmac_f32_e32 v125, v128, v125
	v_div_scale_f32 v128, vcc, 1.0, v1, 1.0
	v_mul_f32_e32 v129, v128, v125
	v_fma_f32 v188, -v124, v129, v128
	v_fmac_f32_e32 v129, v188, v125
	v_fma_f32 v124, -v124, v129, v128
	v_div_fmas_f32 v124, v124, v125, v129
	v_div_fixup_f32 v188, v124, v1, 1.0
	v_lshlrev_b32_e32 v124, 16, v114
	v_and_b32_e32 v125, 0xffff0000, v114
	v_lshlrev_b32_e32 v114, 16, v115
	v_and_b32_e32 v115, 0xffff0000, v115
	v_mul_f32_e32 v1, v125, v125
	v_mul_f32_e32 v128, v115, v115
	v_fmac_f32_e32 v1, v124, v124
	v_fmac_f32_e32 v128, v114, v114
	v_add_f32_e32 v1, v1, v128
	v_add_f32_e32 v1, v1, v118
	v_mul_f32_e32 v118, v193, v193
	v_fmac_f32_e32 v118, v192, v192
	v_add_f32_e32 v1, v118, v1
	v_mul_f32_e32 v118, v195, v195
	v_fmac_f32_e32 v118, v194, v194
	v_add_f32_e32 v1, v118, v1
	v_mul_f32_e32 v118, v197, v197
	v_fmac_f32_e32 v118, v196, v196
	v_add_f32_e32 v1, v118, v1
	v_mul_f32_e32 v118, v199, v199
	v_fmac_f32_e32 v118, v198, v198
	v_add_f32_e32 v1, v118, v1
	v_mul_f32_e32 v118, v201, v201
	v_fmac_f32_e32 v118, v200, v200
	v_add_f32_e32 v1, v118, v1
	v_mul_f32_e32 v118, v203, v203
	v_fmac_f32_e32 v118, v202, v202
	v_add_f32_e32 v1, v118, v1
	v_mul_f32_e32 v118, v153, v153
	v_fmac_f32_e32 v118, v152, v152
	v_add_f32_e32 v1, v118, v1
	v_mul_f32_e32 v118, v205, v205
	v_fmac_f32_e32 v118, v204, v204
	v_lshlrev_b32_e32 v156, 16, v157
	v_and_b32_e32 v157, 0xffff0000, v157
	v_add_f32_e32 v1, v118, v1
	v_mul_f32_e32 v118, v157, v157
	v_fmac_f32_e32 v118, v156, v156
	s_waitcnt vmcnt(1)
	v_and_b32_e32 v207, 0xffff0000, v160
	v_add_f32_e32 v1, v118, v1
	v_lshlrev_b32_e32 v206, 16, v160
	v_mul_f32_e32 v118, v207, v207
	v_fmac_f32_e32 v118, v206, v206
	v_lshlrev_b32_e32 v160, 16, v161
	v_and_b32_e32 v161, 0xffff0000, v161
	v_add_f32_e32 v1, v118, v1
	v_mul_f32_e32 v118, v161, v161
	v_fmac_f32_e32 v118, v160, v160
	s_waitcnt vmcnt(0)
; __device__ __forceinline__ float bf2f(unsigned h) { return __uint_as_float(h << 16); }
; template <int MODE> ...
;     ...
;             for (int rr = 0; rr < RPW; ++rr) { float s = 0.f;
; #pragma unroll
;                 for (int k = 0; k < 8; ++k)
; #pragma unroll
;                     for (int e = 0; e < 2; ++e) { const float a = bf2f(yy[rr][k][e] & 0xffffu), b = bf2f(yy[rr][k][e] >> 16); s += a * a + b * b; }
;                 rstd[rr] = 1.0f / sqrtf(wave_sum(s) * (1.f / DM) + RMS_EPS); }
; #pragma unroll
;             for (int k = 0; k < 8; ++k) { const f32x4 g = *(const f32x4*)(gpost + k * 256 + lane * 4);
; #pragma unroll
;                 for (int rr = 0; rr < RPW; ++rr) { f32x4 yv;
;                     yv[0] = bf2f(yy[rr][k][0] & 0xffffu); yv[1] = bf2f(yy[rr][k][0] >> 16); yv[2] = bf2f(yy[rr][k][1] & 0xffffu); yv[3] = bf2f(yy[rr][k][1] >> 16);
;                     xv[rr][k] += yv * rstd[rr] * g; } }
	v_and_b32_e32 v209, 0xffff0000, v164
	v_add_f32_e32 v1, v118, v1
	v_lshlrev_b32_e32 v208, 16, v164
	v_mul_f32_e32 v118, v209, v209
	v_fmac_f32_e32 v118, v208, v208
	v_lshlrev_b32_e32 v164, 16, v165
	v_and_b32_e32 v165, 0xffff0000, v165
	v_add_f32_e32 v1, v118, v1
	v_mul_f32_e32 v118, v165, v165
	v_fmac_f32_e32 v118, v164, v164
	v_add_f32_e32 v1, v118, v1
	v_pk_mul_f32 v[116:117], v[188:189], v[116:117] op_sel_hi:[0,1]
	v_pk_fma_f32 v[128:129], v[4:5], v[116:117], v[96:97]
	v_add_f32_dpp v1, v1, v1 quad_perm:[1,0,3,2] row_mask:0xf bank_mask:0xf bound_ctrl:1
	s_nop 1
	v_add_f32_dpp v1, v1, v1 quad_perm:[2,3,0,1] row_mask:0xf bank_mask:0xf bound_ctrl:1
	s_nop 1
	v_add_f32_dpp v1, v1, v1 row_half_mirror row_mask:0xf bank_mask:0xf bound_ctrl:1
	s_nop 1
	v_add_f32_dpp v1, v1, v1 row_mirror row_mask:0xf bank_mask:0xf bound_ctrl:1
	v_mov_b32_e32 v118, v1
	s_nop 1
	v_permlane16_swap_b32_e32 v1, v118
	v_add_f32_e32 v1, v1, v118
	v_mov_b32_e32 v118, v1
	s_nop 1
	v_permlane32_swap_b32_e32 v1, v118
	v_add_f32_e32 v1, v1, v118
	v_fmamk_f32 v1, v1, 0x3a000000, v218
	v_cmp_gt_f32_e32 vcc, s30, v1
	v_mul_f32_e32 v118, 0x4f800000, v1
	s_nop 0
	v_cndmask_b32_e32 v1, v1, v118, vcc
	v_sqrt_f32_e32 v118, v1
	s_nop 0
	v_add_u32_e32 v119, -1, v118
	v_fma_f32 v122, -v119, v118, v1
	v_cmp_ge_f32_e64 s[40:41], 0, v122
	v_add_u32_e32 v122, 1, v118
	s_nop 0
	v_cndmask_b32_e64 v119, v118, v119, s[40:41]
	v_fma_f32 v118, -v122, v118, v1
	v_cmp_lt_f32_e64 s[40:41], 0, v118
	s_nop 1
	v_cndmask_b32_e64 v118, v119, v122, s[40:41]
	v_mul_f32_e32 v119, 0x37800000, v118
	v_cndmask_b32_e32 v118, v118, v119, vcc
	v_cmp_class_f32_e32 vcc, v1, v215
	s_nop 1
	v_cndmask_b32_e32 v1, v118, v1, vcc
	v_div_scale_f32 v118, s[0:1], v1, v1, 1.0
	v_rcp_f32_e32 v119, v118
	s_nop 0
	v_fma_f32 v122, -v118, v119, 1.0
	v_fmac_f32_e32 v119, v122, v119
	v_div_scale_f32 v122, vcc, 1.0, v1, 1.0
	v_mul_f32_e32 v123, v122, v119
	v_fma_f32 v126, -v118, v123, v122
	v_fmac_f32_e32 v123, v126, v119
	v_fma_f32 v118, -v118, v123, v122
	v_div_fmas_f32 v118, v118, v119, v123
	v_div_fixup_f32 v210, v118, v1, 1.0
	v_pk_mul_f32 v[118:119], v[188:189], v[168:169] op_sel_hi:[0,1]
	v_pk_fma_f32 v[126:127], v[2:3], v[118:119], v[94:95]
	v_pk_mul_f32 v[94:95], v[210:211], v[124:125] op_sel_hi:[0,1]
	v_pk_mul_f32 v[96:97], v[210:211], v[114:115] op_sel_hi:[0,1]
	v_pk_fma_f32 v[122:123], v[2:3], v[94:95], v[110:111]
	v_pk_mul_f32 v[94:95], v[188:189], v[170:171] op_sel_hi:[0,1]
	v_pk_fma_f32 v[124:125], v[4:5], v[96:97], v[112:113]
	v_pk_mul_f32 v[96:97], v[188:189], v[120:121] op_sel_hi:[0,1]
	v_pk_fma_f32 v[118:119], v[6:7], v[94:95], v[90:91]
	v_pk_mul_f32 v[90:91], v[210:211], v[190:191] op_sel_hi:[0,1]
	v_pk_fma_f32 v[120:121], v[8:9], v[96:97], v[92:93]
	v_pk_mul_f32 v[92:93], v[210:211], v[192:193] op_sel_hi:[0,1]
	v_pk_fma_f32 v[114:115], v[6:7], v[90:91], v[106:107]
	v_pk_mul_f32 v[90:91], v[188:189], v[172:173] op_sel_hi:[0,1]
	v_pk_fma_f32 v[116:117], v[8:9], v[92:93], v[108:109]
	v_pk_mul_f32 v[92:93], v[188:189], v[174:175] op_sel_hi:[0,1]
	v_pk_fma_f32 v[110:111], v[10:11], v[90:91], v[86:87]
	v_pk_mul_f32 v[86:87], v[210:211], v[194:195] op_sel_hi:[0,1]
	v_pk_fma_f32 v[112:113], v[12:13], v[92:93], v[88:89]
	v_pk_mul_f32 v[88:89], v[210:211], v[196:197] op_sel_hi:[0,1]
	v_pk_fma_f32 v[106:107], v[10:11], v[86:87], v[102:103]
	v_pk_mul_f32 v[86:87], v[188:189], v[176:177] op_sel_hi:[0,1]
	v_pk_fma_f32 v[108:109], v[12:13], v[88:89], v[104:105]
	v_pk_mul_f32 v[88:89], v[188:189], v[178:179] op_sel_hi:[0,1]
	v_pk_fma_f32 v[102:103], v[14:15], v[86:87], v[82:83]
	v_pk_mul_f32 v[82:83], v[210:211], v[198:199] op_sel_hi:[0,1]
	v_pk_fma_f32 v[104:105], v[16:17], v[88:89], v[84:85]
	v_pk_mul_f32 v[84:85], v[210:211], v[200:201] op_sel_hi:[0,1]
	v_pk_fma_f32 v[98:99], v[14:15], v[82:83], v[98:99]
	v_pk_mul_f32 v[82:83], v[188:189], v[180:181] op_sel_hi:[0,1]
	v_pk_fma_f32 v[100:101], v[16:17], v[84:85], v[100:101]
	v_pk_mul_f32 v[84:85], v[188:189], v[154:155] op_sel_hi:[0,1]
	v_pk_fma_f32 v[94:95], v[18:19], v[82:83], v[78:79]
	v_pk_mul_f32 v[78:79], v[210:211], v[202:203] op_sel_hi:[0,1]
	v_pk_fma_f32 v[96:97], v[20:21], v[84:85], v[80:81]
	v_pk_mul_f32 v[80:81], v[210:211], v[152:153] op_sel_hi:[0,1]
	v_pk_fma_f32 v[90:91], v[18:19], v[78:79], v[142:143]
	v_pk_mul_f32 v[78:79], v[188:189], v[182:183] op_sel_hi:[0,1]
	v_pk_fma_f32 v[92:93], v[20:21], v[80:81], v[144:145]
	v_pk_mul_f32 v[80:81], v[188:189], v[158:159] op_sel_hi:[0,1]
	v_pk_fma_f32 v[86:87], v[22:23], v[78:79], v[74:75]
	v_pk_mul_f32 v[74:75], v[210:211], v[204:205] op_sel_hi:[0,1]
	v_pk_fma_f32 v[88:89], v[24:25], v[80:81], v[76:77]
	v_pk_mul_f32 v[76:77], v[210:211], v[156:157] op_sel_hi:[0,1]
	v_pk_fma_f32 v[82:83], v[22:23], v[74:75], v[138:139]
	v_pk_mul_f32 v[74:75], v[188:189], v[184:185] op_sel_hi:[0,1]
	v_pk_fma_f32 v[84:85], v[24:25], v[76:77], v[140:141]
	v_pk_mul_f32 v[76:77], v[188:189], v[162:163] op_sel_hi:[0,1]
	v_pk_fma_f32 v[78:79], v[26:27], v[74:75], v[70:71]
	v_pk_mul_f32 v[70:71], v[210:211], v[206:207] op_sel_hi:[0,1]
	v_pk_fma_f32 v[80:81], v[28:29], v[76:77], v[72:73]
	v_pk_mul_f32 v[72:73], v[210:211], v[160:161] op_sel_hi:[0,1]
	v_pk_fma_f32 v[74:75], v[26:27], v[70:71], v[134:135]
	v_pk_mul_f32 v[70:71], v[188:189], v[186:187] op_sel_hi:[0,1]
	v_pk_fma_f32 v[76:77], v[28:29], v[72:73], v[136:137]
	v_pk_mul_f32 v[72:73], v[188:189], v[166:167] op_sel_hi:[0,1]
	v_pk_fma_f32 v[70:71], v[30:31], v[70:71], v[66:67]
	v_pk_mul_f32 v[66:67], v[210:211], v[208:209] op_sel_hi:[0,1]
	v_pk_fma_f32 v[72:73], v[32:33], v[72:73], v[68:69]
	v_pk_mul_f32 v[68:69], v[210:211], v[164:165] op_sel_hi:[0,1]
; template <int MODE> ...
;     ...
;         if (MODE != 0)
; #pragma unroll
;         for (int rr = 0; rr < RPW; ++rr) { float* xo = xres + (size_t)(m + rr) * DM + lane * 4;
; #pragma unroll
;             for (int k = 0; k < 8; ++k) *(f32x4*)(xo + k * 256) = xv[rr][k]; }
;         if (MODE <= 1) {
;             float rstd[RPW];
; #pragma unroll
;             for (int rr = 0; rr < RPW; ++rr) { float s = 0.f;
; #pragma unroll
;                 for (int k = 0; k < 8; ++k) s += (xv[rr][k][0] * xv[rr][k][0] + xv[rr][k][1] * xv[rr][k][1]) + (xv[rr][k][2] * xv[rr][k][2] + xv[rr][k][3] * xv[rr][k][3]);
;                 rstd[rr] = 1.0f / sqrtf(wave_sum(s) * (1.f / DM) + RMS_EPS); }
	v_pk_fma_f32 v[66:67], v[30:31], v[66:67], v[130:131]
	v_lshl_add_u64 v[130:131], s[78:79], 0, v[146:147]
	v_pk_fma_f32 v[68:69], v[32:33], v[68:69], v[132:133]
	v_add_co_u32_e32 v132, vcc, s19, v130
	global_store_dwordx4 v[130:131], v[126:129], off sc1
	global_store_dwordx4 v[130:131], v[118:121], off offset:1024 sc1
	global_store_dwordx4 v[130:131], v[110:113], off offset:2048 sc1
	global_store_dwordx4 v[130:131], v[102:105], off offset:3072 sc1
	v_addc_co_u32_e32 v133, vcc, 0, v131, vcc
	v_add_co_u32_e32 v134, vcc, s31, v130
	v_mul_f32_e32 v1, v127, v127
	s_nop 0
	v_addc_co_u32_e32 v135, vcc, 0, v131, vcc
	v_add_co_u32_e32 v130, vcc, s33, v130
	global_store_dwordx4 v[134:135], v[94:97], off offset:-4096 sc1
	global_store_dwordx4 v[132:133], v[86:89], off offset:1024 sc1
	global_store_dwordx4 v[132:133], v[78:81], off offset:2048 sc1
	global_store_dwordx4 v[132:133], v[70:73], off offset:3072 sc1
	global_store_dwordx4 v[134:135], v[122:125], off sc1
	global_store_dwordx4 v[134:135], v[114:117], off offset:1024 sc1
	global_store_dwordx4 v[134:135], v[106:109], off offset:2048 sc1
	global_store_dwordx4 v[134:135], v[98:101], off offset:3072 sc1
	v_addc_co_u32_e32 v131, vcc, 0, v131, vcc
	global_store_dwordx4 v[130:131], v[90:93], off sc1
	global_store_dwordx4 v[130:131], v[82:85], off offset:1024 sc1
	global_store_dwordx4 v[130:131], v[74:77], off offset:2048 sc1
	global_store_dwordx4 v[130:131], v[66:69], off offset:3072 sc1
	v_mul_f32_e32 v130, v129, v129
	v_fmac_f32_e32 v1, v126, v126
	v_fmac_f32_e32 v130, v128, v128
	v_add_f32_e32 v1, v1, v130
	v_mul_f32_e32 v130, v119, v119
	v_mul_f32_e32 v131, v121, v121
	v_fmac_f32_e32 v130, v118, v118
	v_fmac_f32_e32 v131, v120, v120
	v_add_f32_e32 v130, v130, v131
	v_add_f32_e32 v1, v1, v130
	v_mul_f32_e32 v130, v111, v111
	v_mul_f32_e32 v131, v113, v113
	v_fmac_f32_e32 v130, v110, v110
	v_fmac_f32_e32 v131, v112, v112
	v_add_f32_e32 v130, v130, v131
	v_add_f32_e32 v1, v130, v1
	v_mul_f32_e32 v130, v103, v103
	v_mul_f32_e32 v131, v105, v105
	v_fmac_f32_e32 v130, v102, v102
	v_fmac_f32_e32 v131, v104, v104
	v_add_f32_e32 v130, v130, v131
	v_add_f32_e32 v1, v130, v1
	v_mul_f32_e32 v130, v95, v95
	v_mul_f32_e32 v131, v97, v97
	v_fmac_f32_e32 v130, v94, v94
	v_fmac_f32_e32 v131, v96, v96
	v_add_f32_e32 v130, v130, v131
	v_add_f32_e32 v1, v130, v1
	v_mul_f32_e32 v130, v87, v87
	v_mul_f32_e32 v131, v89, v89
	v_fmac_f32_e32 v130, v86, v86
	v_fmac_f32_e32 v131, v88, v88
	v_add_f32_e32 v130, v130, v131
	v_add_f32_e32 v1, v130, v1
	v_mul_f32_e32 v130, v79, v79
	v_mul_f32_e32 v131, v81, v81
	v_fmac_f32_e32 v130, v78, v78
	v_fmac_f32_e32 v131, v80, v80
	v_add_f32_e32 v130, v130, v131
	v_add_f32_e32 v1, v130, v1
	v_mul_f32_e32 v130, v71, v71
	v_mul_f32_e32 v131, v73, v73
	v_fmac_f32_e32 v130, v70, v70
	v_fmac_f32_e32 v131, v72, v72
	v_add_f32_e32 v130, v130, v131
	v_add_f32_e32 v1, v130, v1
	s_add_u32 s78, s78, s26
	s_addc_u32 s79, s79, s27
	v_add_f32_dpp v1, v1, v1 quad_perm:[1,0,3,2] row_mask:0xf bank_mask:0xf bound_ctrl:1
	s_add_u32 s64, s64, s26
	s_addc_u32 s65, s65, s27
	v_add_f32_dpp v1, v1, v1 quad_perm:[2,3,0,1] row_mask:0xf bank_mask:0xf bound_ctrl:1
	s_cmpk_gt_i32 s42, 0x3fff
	s_nop 0
	v_add_f32_dpp v1, v1, v1 row_half_mirror row_mask:0xf bank_mask:0xf bound_ctrl:1
	s_nop 1
	v_add_f32_dpp v1, v1, v1 row_mirror row_mask:0xf bank_mask:0xf bound_ctrl:1
	v_mov_b32_e32 v130, v1
	s_nop 1
	v_permlane16_swap_b32_e32 v1, v130
	v_add_f32_e32 v1, v1, v130
	v_mov_b32_e32 v130, v1
	s_nop 1
	v_permlane32_swap_b32_e32 v1, v130
	v_add_f32_e32 v1, v1, v130
	v_fmamk_f32 v1, v1, 0x3a000000, v218
	v_cmp_gt_f32_e32 vcc, s30, v1
	v_mul_f32_e32 v130, 0x4f800000, v1
	s_nop 0
	v_cndmask_b32_e32 v1, v1, v130, vcc
	v_sqrt_f32_e32 v130, v1
	s_nop 0
	v_add_u32_e32 v131, -1, v130
	v_fma_f32 v132, -v131, v130, v1
	v_cmp_ge_f32_e64 s[40:41], 0, v132
	v_add_u32_e32 v132, 1, v130
	s_nop 0
	v_cndmask_b32_e64 v131, v130, v131, s[40:41]
	v_fma_f32 v130, -v132, v130, v1
	v_cmp_lt_f32_e64 s[40:41], 0, v130
	s_nop 1
	v_cndmask_b32_e64 v130, v131, v132, s[40:41]
	v_mul_f32_e32 v131, 0x37800000, v130
	v_cndmask_b32_e32 v130, v130, v131, vcc
	v_cmp_class_f32_e32 vcc, v1, v215
	s_nop 1
	v_cndmask_b32_e32 v1, v130, v1, vcc
	v_div_scale_f32 v130, s[0:1], v1, v1, 1.0
	v_rcp_f32_e32 v131, v130
	s_nop 0
	v_fma_f32 v132, -v130, v131, 1.0
	v_fmac_f32_e32 v131, v132, v131
	v_div_scale_f32 v132, vcc, 1.0, v1, 1.0
	v_mul_f32_e32 v133, v132, v131
	v_fma_f32 v134, -v130, v133, v132
	v_fmac_f32_e32 v133, v134, v131
	v_fma_f32 v130, -v130, v133, v132
	v_div_fmas_f32 v130, v130, v131, v133
	v_div_fixup_f32 v130, v130, v1, 1.0
	v_mul_f32_e32 v1, v123, v123
	v_mul_f32_e32 v131, v125, v125
	v_fmac_f32_e32 v1, v122, v122
	v_fmac_f32_e32 v131, v124, v124
	v_add_f32_e32 v1, v1, v131
	v_mul_f32_e32 v131, v115, v115
	v_mul_f32_e32 v132, v117, v117
	v_fmac_f32_e32 v131, v114, v114
	v_fmac_f32_e32 v132, v116, v116
	v_add_f32_e32 v131, v131, v132
	v_add_f32_e32 v1, v1, v131
	v_mul_f32_e32 v131, v107, v107
	v_mul_f32_e32 v132, v109, v109
	v_fmac_f32_e32 v131, v106, v106
	v_fmac_f32_e32 v132, v108, v108
	v_add_f32_e32 v131, v131, v132
	v_add_f32_e32 v1, v131, v1
	v_mul_f32_e32 v131, v99, v99
	v_mul_f32_e32 v132, v101, v101
	v_fmac_f32_e32 v131, v98, v98
	v_fmac_f32_e32 v132, v100, v100
	v_add_f32_e32 v131, v131, v132
	v_add_f32_e32 v1, v131, v1
	v_mul_f32_e32 v131, v91, v91
	v_mul_f32_e32 v132, v93, v93
	v_fmac_f32_e32 v131, v90, v90
	v_fmac_f32_e32 v132, v92, v92
	v_add_f32_e32 v131, v131, v132
	v_add_f32_e32 v1, v131, v1
	v_mul_f32_e32 v131, v83, v83
	v_mul_f32_e32 v132, v85, v85
	v_fmac_f32_e32 v131, v82, v82
	v_fmac_f32_e32 v132, v84, v84
	v_add_f32_e32 v131, v131, v132
; __device__ __forceinline__ unsigned pk2(float lo, float hi) { return f2bf(lo) | (f2bf(hi) << 16); }
; template <int MODE> ...
;     ...
;             for (int rr = 0; rr < RPW; ++rr) { float s = 0.f;
; #pragma unroll
;                 for (int k = 0; k < 8; ++k) s += (xv[rr][k][0] * xv[rr][k][0] + xv[rr][k][1] * xv[rr][k][1]) + (xv[rr][k][2] * xv[rr][k][2] + xv[rr][k][3] * xv[rr][k][3]);
;                 rstd[rr] = 1.0f / sqrtf(wave_sum(s) * (1.f / DM) + RMS_EPS); }
; #pragma unroll
;             for (int k = 0; k < 8; ++k) { const f32x4 g = *(const f32x4*)(gpre + k * 256 + lane * 4);
; #pragma unroll
;                 for (int rr = 0; rr < RPW; ++rr) { const f32x4 a = xv[rr][k] * rstd[rr] * g;
;                     v2u o; o.x = pk2(a[0], a[1]); o.y = pk2(a[2], a[3]);
;                     *(v2u*)(h + ((size_t)(k * 4 + (lane >> 4)) * M_TOK + (m + rr)) * 64 + (lane & 15) * 4) = o; } }
	v_add_f32_e32 v1, v131, v1
	v_mul_f32_e32 v131, v75, v75
	v_mul_f32_e32 v132, v77, v77
	v_fmac_f32_e32 v131, v74, v74
	v_fmac_f32_e32 v132, v76, v76
	v_add_f32_e32 v131, v131, v132
	v_add_f32_e32 v1, v131, v1
	v_mul_f32_e32 v131, v67, v67
	v_mul_f32_e32 v132, v69, v69
	v_fmac_f32_e32 v131, v66, v66
	v_fmac_f32_e32 v132, v68, v68
	v_add_f32_e32 v131, v131, v132
	v_add_f32_e32 v1, v131, v1
	s_nop 1
	v_add_f32_dpp v1, v1, v1 quad_perm:[1,0,3,2] row_mask:0xf bank_mask:0xf bound_ctrl:1
	s_nop 1
	v_add_f32_dpp v1, v1, v1 quad_perm:[2,3,0,1] row_mask:0xf bank_mask:0xf bound_ctrl:1
	s_nop 1
	v_add_f32_dpp v1, v1, v1 row_half_mirror row_mask:0xf bank_mask:0xf bound_ctrl:1
	s_nop 1
	v_add_f32_dpp v1, v1, v1 row_mirror row_mask:0xf bank_mask:0xf bound_ctrl:1
	v_mov_b32_e32 v131, v1
	s_nop 1
	v_permlane16_swap_b32_e32 v1, v131
	v_add_f32_e32 v1, v1, v131
	v_mov_b32_e32 v131, v1
	s_nop 1
	v_permlane32_swap_b32_e32 v1, v131
	v_add_f32_e32 v1, v1, v131
	v_fmamk_f32 v1, v1, 0x3a000000, v218
	v_cmp_gt_f32_e32 vcc, s30, v1
	v_mul_f32_e32 v131, 0x4f800000, v1
	s_nop 0
	v_cndmask_b32_e32 v1, v1, v131, vcc
	v_sqrt_f32_e32 v131, v1
	s_nop 0
	v_add_u32_e32 v132, -1, v131
	v_fma_f32 v133, -v132, v131, v1
	v_cmp_ge_f32_e64 s[40:41], 0, v133
	v_add_u32_e32 v133, 1, v131
	s_nop 0
	v_cndmask_b32_e64 v132, v131, v132, s[40:41]
	v_fma_f32 v131, -v133, v131, v1
	v_cmp_lt_f32_e64 s[40:41], 0, v131
	s_nop 1
	v_cndmask_b32_e64 v131, v132, v133, s[40:41]
	v_mul_f32_e32 v132, 0x37800000, v131
	v_cndmask_b32_e32 v131, v131, v132, vcc
	v_cmp_class_f32_e32 vcc, v1, v215
	s_nop 1
	v_cndmask_b32_e32 v1, v131, v1, vcc
	v_div_scale_f32 v131, s[0:1], v1, v1, 1.0
	v_rcp_f32_e32 v132, v131
	s_mov_b32 s0, 0x4800000
	v_fma_f32 v133, -v131, v132, 1.0
	v_fmac_f32_e32 v132, v133, v132
	v_div_scale_f32 v133, vcc, 1.0, v1, 1.0
	v_mul_f32_e32 v134, v133, v132
	v_fma_f32 v135, -v131, v134, v133
	v_fmac_f32_e32 v134, v135, v132
	v_fma_f32 v131, -v131, v134, v133
	v_div_fmas_f32 v131, v131, v132, v134
	v_pk_mul_f32 v[126:127], v[126:127], v[130:131] op_sel_hi:[1,0]
	v_div_fixup_f32 v132, v131, v1, 1.0
	v_pk_mul_f32 v[126:127], v[46:47], v[126:127]
	v_pk_mul_f32 v[128:129], v[128:129], v[130:131] op_sel_hi:[1,0]
	v_bfe_u32 v1, v126, 16, 1
	v_add3_u32 v1, v126, v1, s63
	v_bfe_u32 v126, v127, 16, 1
	v_pk_mul_f32 v[128:129], v[48:49], v[128:129]
	v_lshrrev_b32_e32 v1, 16, v1
	v_add3_u32 v126, v127, v126, s63
	v_and_or_b32 v126, v126, s60, v1
	v_bfe_u32 v1, v128, 16, 1
	v_add3_u32 v1, v128, v1, s63
	v_bfe_u32 v127, v129, 16, 1
	v_pk_mul_f32 v[122:123], v[122:123], v[132:133] op_sel_hi:[1,0]
	v_lshrrev_b32_e32 v1, 16, v1
	v_add3_u32 v127, v129, v127, s63
	v_pk_mul_f32 v[122:123], v[46:47], v[122:123]
	v_and_or_b32 v127, v127, s60, v1
	v_bfe_u32 v1, v122, 16, 1
	v_pk_mul_f32 v[124:125], v[124:125], v[132:133] op_sel_hi:[1,0]
	v_add3_u32 v1, v122, v1, s63
	v_bfe_u32 v122, v123, 16, 1
	v_pk_mul_f32 v[124:125], v[48:49], v[124:125]
	v_lshrrev_b32_e32 v1, 16, v1
	v_add3_u32 v122, v123, v122, s63
	v_and_or_b32 v122, v122, s60, v1
	v_bfe_u32 v1, v124, 16, 1
	v_add3_u32 v1, v124, v1, s63
	v_bfe_u32 v123, v125, 16, 1
	v_pk_mul_f32 v[118:119], v[118:119], v[130:131] op_sel_hi:[1,0]
	v_lshrrev_b32_e32 v1, 16, v1
	v_add3_u32 v123, v125, v123, s63
	v_pk_mul_f32 v[118:119], v[34:35], v[118:119]
	v_and_or_b32 v123, v123, s60, v1
	v_bfe_u32 v1, v118, 16, 1
	v_pk_mul_f32 v[120:121], v[120:121], v[130:131] op_sel_hi:[1,0]
	v_add3_u32 v1, v118, v1, s63
	v_bfe_u32 v118, v119, 16, 1
	v_pk_mul_f32 v[120:121], v[36:37], v[120:121]
	v_lshrrev_b32_e32 v1, 16, v1
	v_add3_u32 v118, v119, v118, s63
	v_and_or_b32 v118, v118, s60, v1
	v_bfe_u32 v1, v120, 16, 1
	v_add3_u32 v1, v120, v1, s63
	v_bfe_u32 v119, v121, 16, 1
	v_pk_mul_f32 v[114:115], v[114:115], v[132:133] op_sel_hi:[1,0]
	v_lshrrev_b32_e32 v1, 16, v1
	v_add3_u32 v119, v121, v119, s63
	v_pk_mul_f32 v[114:115], v[34:35], v[114:115]
	v_and_or_b32 v119, v119, s60, v1
	v_bfe_u32 v1, v114, 16, 1
	v_pk_mul_f32 v[116:117], v[116:117], v[132:133] op_sel_hi:[1,0]
	v_add3_u32 v1, v114, v1, s63
	v_bfe_u32 v114, v115, 16, 1
	v_pk_mul_f32 v[116:117], v[36:37], v[116:117]
	v_lshrrev_b32_e32 v1, 16, v1
	v_add3_u32 v114, v115, v114, s63
	v_and_or_b32 v114, v114, s60, v1
	v_bfe_u32 v1, v116, 16, 1
	v_add3_u32 v1, v116, v1, s63
	v_bfe_u32 v115, v117, 16, 1
	v_pk_mul_f32 v[110:111], v[110:111], v[130:131] op_sel_hi:[1,0]
	v_lshrrev_b32_e32 v1, 16, v1
	v_add3_u32 v115, v117, v115, s63
	v_pk_mul_f32 v[110:111], v[38:39], v[110:111]
	v_and_or_b32 v115, v115, s60, v1
	v_bfe_u32 v1, v110, 16, 1
	v_pk_mul_f32 v[112:113], v[112:113], v[130:131] op_sel_hi:[1,0]
	v_add3_u32 v1, v110, v1, s63
	v_bfe_u32 v110, v111, 16, 1
	v_pk_mul_f32 v[112:113], v[40:41], v[112:113]
	v_lshrrev_b32_e32 v1, 16, v1
	v_add3_u32 v110, v111, v110, s63
	v_and_or_b32 v110, v110, s60, v1
	v_bfe_u32 v1, v112, 16, 1
	v_add3_u32 v1, v112, v1, s63
	v_bfe_u32 v111, v113, 16, 1
	v_pk_mul_f32 v[106:107], v[106:107], v[132:133] op_sel_hi:[1,0]
	v_lshrrev_b32_e32 v1, 16, v1
	v_add3_u32 v111, v113, v111, s63
	v_pk_mul_f32 v[106:107], v[38:39], v[106:107]
	v_and_or_b32 v111, v111, s60, v1
	v_bfe_u32 v1, v106, 16, 1
	v_pk_mul_f32 v[108:109], v[108:109], v[132:133] op_sel_hi:[1,0]
	v_add3_u32 v1, v106, v1, s63
	v_bfe_u32 v106, v107, 16, 1
	v_pk_mul_f32 v[108:109], v[40:41], v[108:109]
	v_lshrrev_b32_e32 v1, 16, v1
	v_add3_u32 v106, v107, v106, s63
	v_and_or_b32 v106, v106, s60, v1
	v_bfe_u32 v1, v108, 16, 1
	v_add3_u32 v1, v108, v1, s63
	v_bfe_u32 v107, v109, 16, 1
	v_pk_mul_f32 v[102:103], v[102:103], v[130:131] op_sel_hi:[1,0]
	v_lshrrev_b32_e32 v1, 16, v1
	v_add3_u32 v107, v109, v107, s63
	v_pk_mul_f32 v[102:103], v[42:43], v[102:103]
; __device__ __forceinline__ unsigned pk2(float lo, float hi) { return f2bf(lo) | (f2bf(hi) << 16); }
; template <int MODE> ...
;     ...
; #pragma unroll
;             for (int k = 0; k < 8; ++k) { const f32x4 g = *(const f32x4*)(gpre + k * 256 + lane * 4);
; #pragma unroll
;                 for (int rr = 0; rr < RPW; ++rr) { const f32x4 a = xv[rr][k] * rstd[rr] * g;
;                     v2u o; o.x = pk2(a[0], a[1]); o.y = pk2(a[2], a[3]);
;                     *(v2u*)(h + ((size_t)(k * 4 + (lane >> 4)) * M_TOK + (m + rr)) * 64 + (lane & 15) * 4) = o; } }
	v_and_or_b32 v107, v107, s60, v1
	v_bfe_u32 v1, v102, 16, 1
	v_pk_mul_f32 v[104:105], v[104:105], v[130:131] op_sel_hi:[1,0]
	v_add3_u32 v1, v102, v1, s63
	v_bfe_u32 v102, v103, 16, 1
	v_pk_mul_f32 v[104:105], v[44:45], v[104:105]
	v_lshrrev_b32_e32 v1, 16, v1
	v_add3_u32 v102, v103, v102, s63
	v_and_or_b32 v102, v102, s60, v1
	v_bfe_u32 v1, v104, 16, 1
	v_add3_u32 v1, v104, v1, s63
	v_bfe_u32 v103, v105, 16, 1
	v_pk_mul_f32 v[98:99], v[98:99], v[132:133] op_sel_hi:[1,0]
	v_lshrrev_b32_e32 v1, 16, v1
	v_add3_u32 v103, v105, v103, s63
	v_pk_mul_f32 v[98:99], v[42:43], v[98:99]
	v_and_or_b32 v103, v103, s60, v1
	v_bfe_u32 v1, v98, 16, 1
	v_pk_mul_f32 v[100:101], v[100:101], v[132:133] op_sel_hi:[1,0]
	v_add3_u32 v1, v98, v1, s63
	v_bfe_u32 v98, v99, 16, 1
	v_pk_mul_f32 v[100:101], v[44:45], v[100:101]
	v_lshrrev_b32_e32 v1, 16, v1
	v_add3_u32 v98, v99, v98, s63
	v_and_or_b32 v98, v98, s60, v1
	v_bfe_u32 v1, v100, 16, 1
	v_add3_u32 v1, v100, v1, s63
	v_bfe_u32 v99, v101, 16, 1
	v_pk_mul_f32 v[94:95], v[94:95], v[130:131] op_sel_hi:[1,0]
	v_lshrrev_b32_e32 v1, 16, v1
	v_add3_u32 v99, v101, v99, s63
	v_pk_mul_f32 v[94:95], v[50:51], v[94:95]
	v_and_or_b32 v99, v99, s60, v1
	v_bfe_u32 v1, v94, 16, 1
	v_pk_mul_f32 v[96:97], v[96:97], v[130:131] op_sel_hi:[1,0]
	v_add3_u32 v1, v94, v1, s63
	v_bfe_u32 v94, v95, 16, 1
	v_pk_mul_f32 v[96:97], v[52:53], v[96:97]
	v_lshrrev_b32_e32 v1, 16, v1
	v_add3_u32 v94, v95, v94, s63
	v_and_or_b32 v94, v94, s60, v1
	v_bfe_u32 v1, v96, 16, 1
	v_add3_u32 v1, v96, v1, s63
	v_bfe_u32 v95, v97, 16, 1
	v_pk_mul_f32 v[90:91], v[90:91], v[132:133] op_sel_hi:[1,0]
	v_lshrrev_b32_e32 v1, 16, v1
	v_add3_u32 v95, v97, v95, s63
	v_pk_mul_f32 v[90:91], v[50:51], v[90:91]
	v_and_or_b32 v95, v95, s60, v1
	v_bfe_u32 v1, v90, 16, 1
	v_pk_mul_f32 v[92:93], v[92:93], v[132:133] op_sel_hi:[1,0]
	v_add3_u32 v1, v90, v1, s63
	v_bfe_u32 v90, v91, 16, 1
	v_pk_mul_f32 v[92:93], v[52:53], v[92:93]
	v_lshrrev_b32_e32 v1, 16, v1
	v_add3_u32 v90, v91, v90, s63
	v_and_or_b32 v90, v90, s60, v1
	v_bfe_u32 v1, v92, 16, 1
	v_add3_u32 v1, v92, v1, s63
	v_bfe_u32 v91, v93, 16, 1
	v_pk_mul_f32 v[86:87], v[86:87], v[130:131] op_sel_hi:[1,0]
	v_lshrrev_b32_e32 v1, 16, v1
	v_add3_u32 v91, v93, v91, s63
	v_pk_mul_f32 v[86:87], v[54:55], v[86:87]
	v_and_or_b32 v91, v91, s60, v1
	v_bfe_u32 v1, v86, 16, 1
	v_pk_mul_f32 v[88:89], v[88:89], v[130:131] op_sel_hi:[1,0]
	v_add3_u32 v1, v86, v1, s63
	v_bfe_u32 v86, v87, 16, 1
	v_pk_mul_f32 v[88:89], v[56:57], v[88:89]
	v_lshrrev_b32_e32 v1, 16, v1
	v_add3_u32 v86, v87, v86, s63
	v_and_or_b32 v86, v86, s60, v1
	v_bfe_u32 v1, v88, 16, 1
	v_add3_u32 v1, v88, v1, s63
	v_bfe_u32 v87, v89, 16, 1
	v_pk_mul_f32 v[82:83], v[82:83], v[132:133] op_sel_hi:[1,0]
	v_lshrrev_b32_e32 v1, 16, v1
	v_add3_u32 v87, v89, v87, s63
	v_pk_mul_f32 v[82:83], v[54:55], v[82:83]
	v_and_or_b32 v87, v87, s60, v1
	v_bfe_u32 v1, v82, 16, 1
	v_pk_mul_f32 v[84:85], v[84:85], v[132:133] op_sel_hi:[1,0]
	v_add3_u32 v1, v82, v1, s63
	v_bfe_u32 v82, v83, 16, 1
	v_pk_mul_f32 v[84:85], v[56:57], v[84:85]
	v_lshrrev_b32_e32 v1, 16, v1
	v_add3_u32 v82, v83, v82, s63
	v_and_or_b32 v82, v82, s60, v1
	v_bfe_u32 v1, v84, 16, 1
	v_add3_u32 v1, v84, v1, s63
	v_bfe_u32 v83, v85, 16, 1
	v_pk_mul_f32 v[78:79], v[78:79], v[130:131] op_sel_hi:[1,0]
	v_lshrrev_b32_e32 v1, 16, v1
	v_add3_u32 v83, v85, v83, s63
	v_pk_mul_f32 v[78:79], v[58:59], v[78:79]
	v_and_or_b32 v83, v83, s60, v1
	v_bfe_u32 v1, v78, 16, 1
	v_pk_mul_f32 v[80:81], v[80:81], v[130:131] op_sel_hi:[1,0]
	v_add3_u32 v1, v78, v1, s63
	v_bfe_u32 v78, v79, 16, 1
	v_pk_mul_f32 v[80:81], v[60:61], v[80:81]
	v_lshrrev_b32_e32 v1, 16, v1
	v_add3_u32 v78, v79, v78, s63
; __device__ __forceinline__ unsigned pk2(float lo, float hi) { return f2bf(lo) | (f2bf(hi) << 16); }
; template <int MODE> ...
;     ...
; #pragma unroll
;             for (int k = 0; k < 8; ++k) { const f32x4 g = *(const f32x4*)(gpre + k * 256 + lane * 4);
; #pragma unroll
;                 for (int rr = 0; rr < RPW; ++rr) { const f32x4 a = xv[rr][k] * rstd[rr] * g;
;                     v2u o; o.x = pk2(a[0], a[1]); o.y = pk2(a[2], a[3]);
;                     *(v2u*)(h + ((size_t)(k * 4 + (lane >> 4)) * M_TOK + (m + rr)) * 64 + (lane & 15) * 4) = o; } }
;         }
	v_and_or_b32 v78, v78, s60, v1
	v_bfe_u32 v1, v80, 16, 1
	v_add3_u32 v1, v80, v1, s63
	v_bfe_u32 v79, v81, 16, 1
	v_pk_mul_f32 v[74:75], v[74:75], v[132:133] op_sel_hi:[1,0]
	v_lshrrev_b32_e32 v1, 16, v1
	v_add3_u32 v79, v81, v79, s63
	v_pk_mul_f32 v[74:75], v[58:59], v[74:75]
	v_and_or_b32 v79, v79, s60, v1
	v_bfe_u32 v1, v74, 16, 1
	v_pk_mul_f32 v[76:77], v[76:77], v[132:133] op_sel_hi:[1,0]
	v_add3_u32 v1, v74, v1, s63
	v_bfe_u32 v74, v75, 16, 1
	v_lshl_add_u64 v[128:129], v[148:149], 0, s[46:47]
	v_pk_mul_f32 v[76:77], v[60:61], v[76:77]
	v_lshrrev_b32_e32 v1, 16, v1
	v_add3_u32 v74, v75, v74, s63
	v_add_co_u32_e32 v134, vcc, s0, v128
	v_and_or_b32 v74, v74, s60, v1
	v_bfe_u32 v1, v76, 16, 1
	v_addc_co_u32_e32 v135, vcc, 0, v129, vcc
	s_mov_b32 s0, 0x5000000
	v_add3_u32 v1, v76, v1, s63
	v_bfe_u32 v75, v77, 16, 1
	v_pk_mul_f32 v[70:71], v[70:71], v[130:131] op_sel_hi:[1,0]
	v_add_co_u32_e32 v120, vcc, s0, v128
	v_lshrrev_b32_e32 v1, 16, v1
	v_add3_u32 v75, v77, v75, s63
	v_pk_mul_f32 v[70:71], v[62:63], v[70:71]
	v_addc_co_u32_e32 v121, vcc, 0, v129, vcc
	s_mov_b32 s0, 0x5800000
	v_and_or_b32 v75, v75, s60, v1
	v_bfe_u32 v1, v70, 16, 1
	v_add_co_u32_e32 v112, vcc, s0, v128
	v_pk_mul_f32 v[72:73], v[72:73], v[130:131] op_sel_hi:[1,0]
	v_add3_u32 v1, v70, v1, s63
	v_bfe_u32 v70, v71, 16, 1
	v_addc_co_u32_e32 v113, vcc, 0, v129, vcc
	s_mov_b32 s0, 0x6000000
	v_pk_mul_f32 v[72:73], v[64:65], v[72:73]
	v_lshrrev_b32_e32 v1, 16, v1
	v_add3_u32 v70, v71, v70, s63
	v_add_co_u32_e32 v104, vcc, s0, v128
	v_and_or_b32 v70, v70, s60, v1
	v_bfe_u32 v1, v72, 16, 1
	v_addc_co_u32_e32 v105, vcc, 0, v129, vcc
	s_mov_b32 s0, 0x6800000
	v_add3_u32 v1, v72, v1, s63
	v_bfe_u32 v71, v73, 16, 1
	v_pk_mul_f32 v[66:67], v[66:67], v[132:133] op_sel_hi:[1,0]
	v_add_co_u32_e32 v96, vcc, s0, v128
	v_lshrrev_b32_e32 v1, 16, v1
	v_add3_u32 v71, v73, v71, s63
	v_pk_mul_f32 v[66:67], v[62:63], v[66:67]
	v_addc_co_u32_e32 v97, vcc, 0, v129, vcc
	s_mov_b32 s0, 0x7000000
	v_and_or_b32 v71, v71, s60, v1
	v_bfe_u32 v1, v66, 16, 1
	v_add_co_u32_e32 v88, vcc, s0, v128
	v_pk_mul_f32 v[68:69], v[68:69], v[132:133] op_sel_hi:[1,0]
	v_add3_u32 v1, v66, v1, s63
	v_bfe_u32 v66, v67, 16, 1
	v_addc_co_u32_e32 v89, vcc, 0, v129, vcc
	s_mov_b32 s0, 0x7800000
	v_pk_mul_f32 v[68:69], v[64:65], v[68:69]
	v_lshrrev_b32_e32 v1, 16, v1
	v_add3_u32 v66, v67, v66, s63
	v_add_co_u32_e32 v80, vcc, s0, v128
	v_and_or_b32 v66, v66, s60, v1
	v_bfe_u32 v1, v68, 16, 1
	v_addc_co_u32_e32 v81, vcc, 0, v129, vcc
	s_brev_b32 s0, 16
	v_add3_u32 v1, v68, v1, s63
	v_bfe_u32 v67, v69, 16, 1
	v_add_co_u32_e32 v72, vcc, s0, v128
	v_lshrrev_b32_e32 v1, 16, v1
	v_add3_u32 v67, v69, v67, s63
	v_addc_co_u32_e32 v73, vcc, 0, v129, vcc
	v_and_or_b32 v67, v67, s60, v1
	v_lshl_add_u64 v[148:149], v[148:149], 0, s[20:21]
	global_store_dwordx2 v[134:135], v[126:127], off
	global_store_dwordx2 v[134:135], v[122:123], off offset:128
	global_store_dwordx2 v[120:121], v[118:119], off
	global_store_dwordx2 v[120:121], v[114:115], off offset:128
	global_store_dwordx2 v[112:113], v[110:111], off
	global_store_dwordx2 v[112:113], v[106:107], off offset:128
	global_store_dwordx2 v[104:105], v[102:103], off
	global_store_dwordx2 v[104:105], v[98:99], off offset:128
	global_store_dwordx2 v[96:97], v[94:95], off
	global_store_dwordx2 v[96:97], v[90:91], off offset:128
	global_store_dwordx2 v[88:89], v[86:87], off
	global_store_dwordx2 v[88:89], v[82:83], off offset:128
	global_store_dwordx2 v[80:81], v[78:79], off
	global_store_dwordx2 v[80:81], v[74:75], off offset:128
	global_store_dwordx2 v[72:73], v[70:71], off
	global_store_dwordx2 v[72:73], v[66:67], off offset:128
	s_cbranch_scc0 .LBB0_225

; __device__ __forceinline__ float bf2f(unsigned h) { return __uint_as_float(h << 16); }
; template <int MODE> ...
;     for (int m = RPW * gw; m < M_TOK; m += RPW * NGW) {
;         f32x4 xv[RPW][8]; v2u yy[RPW][8];
; #pragma unroll
;         for (int rr = 0; rr < RPW; ++rr) {
;             const float* xr = ((MODE == 0 || xin != nullptr) ? xin : xres) + (size_t)(m + rr) * DM + lane * 4;
; #pragma unroll
;             for (int k = 0; k < 8; ++k) xv[rr][k] = *(const f32x4*)(xr + k * 256);
;             if (MODE >= 1) { const bf16_t* yr = y + (size_t)(m + rr) * 256 + lane * 4;
; #pragma unroll
;                 for (int k = 0; k < 8; ++k) yy[rr][k] = *(const v2u*)(yr + (size_t)k * ((size_t)M_TOK * 256)); }
;         }
;         if (MODE >= 1) {
;             float rstd[RPW];
; #pragma unroll
;             for (int rr = 0; rr < RPW; ++rr) { float s = 0.f;
; #pragma unroll
;                 for (int k = 0; k < 8; ++k)
; #pragma unroll
;                     for (int e = 0; e < 2; ++e) { const float a = bf2f(yy[rr][k][e] & 0xffffu), b = bf2f(yy[rr][k][e] >> 16); s += a * a + b * b; }
;                 rstd[rr] = 1.0f / sqrtf(wave_sum(s) * (1.f / DM) + RMS_EPS); }
.LBB0_230:
	v_add_co_u32_e32 v104, vcc, 0xffffe000, v100
	s_add_i32 s30, s30, s6
	s_nop 0
	v_addc_co_u32_e32 v105, vcc, -1, v101, vcc
	v_add_co_u32_e32 v102, vcc, 0xfffff000, v100
	global_load_dwordx4 v[62:65], v[104:105], off
	s_nop 0
	v_addc_co_u32_e32 v103, vcc, -1, v101, vcc
	v_add_co_u32_e32 v116, vcc, 0xfc800000, v98
	global_load_dwordx4 v[58:61], v[102:103], off offset:-3072
	global_load_dwordx4 v[54:57], v[102:103], off offset:-2048
	global_load_dwordx4 v[50:53], v[102:103], off offset:-1024
	global_load_dwordx4 v[46:49], v[100:101], off offset:-4096
	global_load_dwordx4 v[42:45], v[100:101], off offset:-3072
	global_load_dwordx4 v[38:41], v[100:101], off offset:-2048
	global_load_dwordx4 v[34:37], v[100:101], off offset:-1024
	v_addc_co_u32_e32 v117, vcc, -1, v99, vcc
	v_add_co_u32_e32 v124, vcc, 0xfd000000, v98
	global_load_dwordx2 v[122:123], v[116:117], off offset:-512
	s_nop 0
	v_addc_co_u32_e32 v125, vcc, -1, v99, vcc
	global_load_dwordx2 v[120:121], v[124:125], off offset:-512
	v_add_co_u32_e32 v126, vcc, 0xfd800000, v98
	s_cmpk_gt_i32 s30, 0x3fff
	s_nop 0
	v_addc_co_u32_e32 v127, vcc, -1, v99, vcc
	global_load_dwordx2 v[118:119], v[126:127], off offset:-512
	v_add_co_u32_e32 v128, vcc, 0xfe000000, v98
	s_nop 1
	v_addc_co_u32_e32 v129, vcc, -1, v99, vcc
	global_load_dwordx2 v[112:113], v[128:129], off offset:-512
	v_add_co_u32_e32 v130, vcc, 0xfe800000, v98
	s_waitcnt vmcnt(3)
	v_and_b32_e32 v141, 0xffff0000, v123
	v_addc_co_u32_e32 v131, vcc, -1, v99, vcc
	global_load_dwordx2 v[108:109], v[130:131], off offset:-512
	v_add_co_u32_e32 v134, vcc, 0xff000000, v98
	v_lshlrev_b32_e32 v140, 16, v123
	s_nop 0
	v_addc_co_u32_e32 v135, vcc, -1, v99, vcc
	global_load_dwordx2 v[154:155], v[134:135], off offset:-512
	v_add_co_u32_e32 v136, vcc, 0xff800000, v98
	s_waitcnt vmcnt(4)
	v_and_b32_e32 v149, 0xffff0000, v121
	v_addc_co_u32_e32 v137, vcc, -1, v99, vcc
	global_load_dwordx2 v[114:115], v[136:137], off offset:-512
	global_load_dwordx2 v[110:111], v[98:99], off offset:-512
	global_load_dwordx4 v[94:97], v[100:101], off
	global_load_dwordx4 v[90:93], v[100:101], off offset:1024
	global_load_dwordx4 v[86:89], v[100:101], off offset:2048
	global_load_dwordx4 v[82:85], v[100:101], off offset:3072
	v_add_co_u32_e32 v106, vcc, s5, v100
	v_lshlrev_b32_e32 v148, 16, v121
	s_nop 0
	v_addc_co_u32_e32 v107, vcc, 0, v101, vcc
	global_load_dwordx4 v[78:81], v[106:107], off
	global_load_dwordx4 v[74:77], v[106:107], off offset:1024
	global_load_dwordx4 v[70:73], v[106:107], off offset:2048
	global_load_dwordx4 v[66:69], v[106:107], off offset:3072
	global_load_dwordx2 v[156:157], v[116:117], off
	global_load_dwordx2 v[152:153], v[124:125], off
	global_load_dwordx2 v[150:151], v[126:127], off
	global_load_dwordx2 v[142:143], v[128:129], off
	global_load_dwordx2 v[132:133], v[130:131], off
	s_nop 0
	global_load_dwordx2 v[124:125], v[134:135], off
	global_load_dwordx2 v[116:117], v[136:137], off
	global_load_dwordx2 v[146:147], v[98:99], off
	v_and_b32_e32 v131, 0xffff0000, v122
	v_lshlrev_b32_e32 v130, 16, v122
	v_mul_f32_e32 v1, v131, v131
	v_mul_f32_e32 v122, v141, v141
	v_and_b32_e32 v137, 0xffff0000, v120
	v_fmac_f32_e32 v1, v130, v130
	v_fmac_f32_e32 v122, v140, v140
	v_lshlrev_b32_e32 v136, 16, v120
	v_mul_f32_e32 v120, v137, v137
	v_add_f32_e32 v1, v1, v122
	v_fmac_f32_e32 v120, v136, v136
	v_add_f32_e32 v1, v1, v120
	v_mul_f32_e32 v120, v149, v149
	s_waitcnt vmcnt(21)
	v_and_b32_e32 v139, 0xffff0000, v118
	v_fmac_f32_e32 v120, v148, v148
	v_lshlrev_b32_e32 v138, 16, v118
	v_mul_f32_e32 v118, v139, v139
	v_add_f32_e32 v1, v120, v1
	v_fmac_f32_e32 v118, v138, v138
	v_and_b32_e32 v145, 0xffff0000, v119
	v_add_f32_e32 v1, v118, v1
	v_lshlrev_b32_e32 v144, 16, v119
	v_mul_f32_e32 v118, v145, v145
	s_waitcnt vmcnt(20)
	v_and_b32_e32 v129, 0xffff0000, v112
	v_fmac_f32_e32 v118, v144, v144
	v_lshlrev_b32_e32 v128, 16, v112
	v_mul_f32_e32 v112, v129, v129
	v_add_f32_e32 v1, v118, v1
	v_fmac_f32_e32 v112, v128, v128
	v_and_b32_e32 v135, 0xffff0000, v113
	v_add_f32_e32 v1, v112, v1
	v_lshlrev_b32_e32 v134, 16, v113
	v_mul_f32_e32 v112, v135, v135
	v_fmac_f32_e32 v112, v134, v134
	v_add_f32_e32 v1, v112, v1
	v_lshl_add_u64 v[98:99], v[98:99], 0, s[8:9]
	s_waitcnt vmcnt(19)
	v_and_b32_e32 v123, 0xffff0000, v108
	v_lshlrev_b32_e32 v122, 16, v108
	v_mul_f32_e32 v108, v123, v123
	v_fmac_f32_e32 v108, v122, v122
	v_and_b32_e32 v127, 0xffff0000, v109
	v_add_f32_e32 v1, v108, v1
	v_lshlrev_b32_e32 v126, 16, v109
	v_mul_f32_e32 v108, v127, v127
	v_fmac_f32_e32 v108, v126, v126
	s_waitcnt vmcnt(18)
	v_and_b32_e32 v119, 0xffff0000, v154
	v_add_f32_e32 v1, v108, v1
	v_lshlrev_b32_e32 v118, 16, v154
	v_mul_f32_e32 v108, v119, v119
	v_fmac_f32_e32 v108, v118, v118
	v_and_b32_e32 v121, 0xffff0000, v155
	v_add_f32_e32 v1, v108, v1
	v_lshlrev_b32_e32 v120, 16, v155
	v_mul_f32_e32 v108, v121, v121
	v_fmac_f32_e32 v108, v120, v120
	s_waitcnt vmcnt(17)
	v_and_b32_e32 v113, 0xffff0000, v114
	v_add_f32_e32 v1, v108, v1
	v_lshlrev_b32_e32 v112, 16, v114
	v_mul_f32_e32 v108, v113, v113
	v_fmac_f32_e32 v108, v112, v112
	v_lshlrev_b32_e32 v114, 16, v115
	v_and_b32_e32 v115, 0xffff0000, v115
	v_add_f32_e32 v1, v108, v1
	v_mul_f32_e32 v108, v115, v115
	v_fmac_f32_e32 v108, v114, v114
	s_waitcnt vmcnt(16)
	v_and_b32_e32 v109, 0xffff0000, v110
	v_add_f32_e32 v1, v108, v1
	v_lshlrev_b32_e32 v108, 16, v110
	v_mul_f32_e32 v110, v109, v109
	v_fmac_f32_e32 v110, v108, v108
	v_add_f32_e32 v1, v110, v1
	v_lshlrev_b32_e32 v110, 16, v111
	v_and_b32_e32 v111, 0xffff0000, v111
	v_mul_f32_e32 v154, v111, v111
	v_fmac_f32_e32 v154, v110, v110
	v_add_f32_e32 v1, v154, v1
	s_waitcnt vmcnt(6)
; __device__ __forceinline__ float bf2f(unsigned h) { return __uint_as_float(h << 16); }
; template <int MODE> ...
;     ...
;         if (MODE >= 1) {
;             float rstd[RPW];
; #pragma unroll
;             for (int rr = 0; rr < RPW; ++rr) { float s = 0.f;
; #pragma unroll
;                 for (int k = 0; k < 8; ++k)
; #pragma unroll
;                     for (int e = 0; e < 2; ++e) { const float a = bf2f(yy[rr][k][e] & 0xffffu), b = bf2f(yy[rr][k][e] >> 16); s += a * a + b * b; }
;                 rstd[rr] = 1.0f / sqrtf(wave_sum(s) * (1.f / DM) + RMS_EPS); }
	v_and_b32_e32 v161, 0xffff0000, v152
	s_waitcnt vmcnt(5)
	v_and_b32_e32 v163, 0xffff0000, v150
	v_add_f32_dpp v1, v1, v1 quad_perm:[1,0,3,2] row_mask:0xf bank_mask:0xf bound_ctrl:1
	v_lshlrev_b32_e32 v162, 16, v150
	v_mul_f32_e32 v150, v163, v163
	v_add_f32_dpp v1, v1, v1 quad_perm:[2,3,0,1] row_mask:0xf bank_mask:0xf bound_ctrl:1
	v_fmac_f32_e32 v150, v162, v162
	s_waitcnt vmcnt(4)
	v_and_b32_e32 v165, 0xffff0000, v142
	v_add_f32_dpp v1, v1, v1 row_half_mirror row_mask:0xf bank_mask:0xf bound_ctrl:1
	v_lshlrev_b32_e32 v164, 16, v142
	v_mul_f32_e32 v142, v165, v165
	v_add_f32_dpp v1, v1, v1 row_mirror row_mask:0xf bank_mask:0xf bound_ctrl:1
	v_mov_b32_e32 v154, v1
	s_nop 1
	v_permlane16_swap_b32_e32 v1, v154
	v_add_f32_e32 v1, v1, v154
	v_mov_b32_e32 v154, v1
	s_nop 1
	v_permlane32_swap_b32_e32 v1, v154
	v_add_f32_e32 v1, v1, v154
	v_fmamk_f32 v1, v1, 0x3a000000, v218
	v_cmp_gt_f32_e32 vcc, s14, v1
	v_mul_f32_e32 v154, 0x4f800000, v1
	v_fmac_f32_e32 v142, v164, v164
	v_cndmask_b32_e32 v1, v1, v154, vcc
	v_sqrt_f32_e32 v154, v1
	s_waitcnt vmcnt(3)
	v_and_b32_e32 v167, 0xffff0000, v132
	v_lshlrev_b32_e32 v166, 16, v132
	v_mul_f32_e32 v132, v167, v167
	v_add_u32_e32 v155, -1, v154
	v_fma_f32 v158, -v155, v154, v1
	v_cmp_ge_f32_e64 s[40:41], 0, v158
	v_add_u32_e32 v158, 1, v154
	v_fmac_f32_e32 v132, v166, v166
	v_cndmask_b32_e64 v155, v154, v155, s[40:41]
	v_fma_f32 v154, -v158, v154, v1
	v_cmp_lt_f32_e64 s[40:41], 0, v154
	s_waitcnt vmcnt(2)
	v_and_b32_e32 v169, 0xffff0000, v124
	v_lshlrev_b32_e32 v168, 16, v124
	v_cndmask_b32_e64 v154, v155, v158, s[40:41]
	v_mul_f32_e32 v155, 0x37800000, v154
	v_cndmask_b32_e32 v154, v154, v155, vcc
	v_cmp_class_f32_e32 vcc, v1, v215
	v_mul_f32_e32 v124, v169, v169
	v_fmac_f32_e32 v124, v168, v168
	v_cndmask_b32_e32 v1, v154, v1, vcc
	v_div_scale_f32 v154, s[0:1], v1, v1, 1.0
	v_rcp_f32_e32 v155, v154
	s_waitcnt vmcnt(1)
	v_and_b32_e32 v171, 0xffff0000, v116
	v_lshlrev_b32_e32 v170, 16, v116
	v_mul_f32_e32 v116, v171, v171
	v_fma_f32 v158, -v154, v155, 1.0
	v_fmac_f32_e32 v155, v158, v155
	v_div_scale_f32 v158, vcc, 1.0, v1, 1.0
	v_mul_f32_e32 v159, v158, v155
	v_fma_f32 v160, -v154, v159, v158
	v_fmac_f32_e32 v159, v160, v155
	v_fma_f32 v154, -v154, v159, v158
	v_div_fmas_f32 v154, v154, v155, v159
	v_lshlrev_b32_e32 v158, 16, v156
	v_and_b32_e32 v159, 0xffff0000, v156
	v_lshlrev_b32_e32 v156, 16, v157
	v_and_b32_e32 v157, 0xffff0000, v157
	v_div_fixup_f32 v154, v154, v1, 1.0
	v_mul_f32_e32 v1, v159, v159
	v_mul_f32_e32 v155, v157, v157
	v_fmac_f32_e32 v1, v158, v158
	v_fmac_f32_e32 v155, v156, v156
	v_lshlrev_b32_e32 v160, 16, v152
	v_mul_f32_e32 v152, v161, v161
	v_add_f32_e32 v1, v1, v155
	v_fmac_f32_e32 v152, v160, v160
	v_add_f32_e32 v1, v1, v152
	v_lshlrev_b32_e32 v152, 16, v153
	v_and_b32_e32 v153, 0xffff0000, v153
	v_mul_f32_e32 v155, v153, v153
	v_fmac_f32_e32 v155, v152, v152
	v_add_f32_e32 v1, v155, v1
	v_add_f32_e32 v1, v150, v1
	v_lshlrev_b32_e32 v150, 16, v151
	v_and_b32_e32 v151, 0xffff0000, v151
	v_mul_f32_e32 v155, v151, v151
	v_fmac_f32_e32 v155, v150, v150
	v_add_f32_e32 v1, v155, v1
	v_add_f32_e32 v1, v142, v1
	v_lshlrev_b32_e32 v142, 16, v143
	v_and_b32_e32 v143, 0xffff0000, v143
	v_mul_f32_e32 v155, v143, v143
	v_fmac_f32_e32 v155, v142, v142
	v_add_f32_e32 v1, v155, v1
	v_add_f32_e32 v1, v132, v1
	v_lshlrev_b32_e32 v132, 16, v133
	v_and_b32_e32 v133, 0xffff0000, v133
	v_mul_f32_e32 v155, v133, v133
	v_fmac_f32_e32 v155, v132, v132
	v_add_f32_e32 v1, v155, v1
	v_add_f32_e32 v1, v124, v1
	v_lshlrev_b32_e32 v124, 16, v125
	v_and_b32_e32 v125, 0xffff0000, v125
	v_mul_f32_e32 v155, v125, v125
	v_fmac_f32_e32 v155, v124, v124
	v_add_f32_e32 v1, v155, v1
	v_fmac_f32_e32 v116, v170, v170
	v_and_b32_e32 v173, 0xffff0000, v117
	v_add_f32_e32 v1, v116, v1
	v_lshlrev_b32_e32 v172, 16, v117
	v_mul_f32_e32 v116, v173, v173
	v_fmac_f32_e32 v116, v172, v172
	s_waitcnt vmcnt(0)
; __device__ __forceinline__ float bf2f(unsigned h) { return __uint_as_float(h << 16); }
; template <int MODE> ...
;     ...
; #pragma unroll
;             for (int k = 0; k < 8; ++k) { const f32x4 g = *(const f32x4*)(gpost + k * 256 + lane * 4);
; #pragma unroll
;                 for (int rr = 0; rr < RPW; ++rr) { f32x4 yv;
;                     yv[0] = bf2f(yy[rr][k][0] & 0xffffu); yv[1] = bf2f(yy[rr][k][0] >> 16); yv[2] = bf2f(yy[rr][k][1] & 0xffffu); yv[3] = bf2f(yy[rr][k][1] >> 16);
;                     xv[rr][k] += yv * rstd[rr] * g; } }
;         }
;         if (MODE != 0)
; #pragma unroll
;         for (int rr = 0; rr < RPW; ++rr) { float* xo = xres + (size_t)(m + rr) * DM + lane * 4;
; #pragma unroll
;             for (int k = 0; k < 8; ++k) *(f32x4*)(xo + k * 256) = xv[rr][k]; }
	v_and_b32_e32 v117, 0xffff0000, v146
	v_add_f32_e32 v1, v116, v1
	v_lshlrev_b32_e32 v116, 16, v146
	v_mul_f32_e32 v146, v117, v117
	v_fmac_f32_e32 v146, v116, v116
	v_add_f32_e32 v1, v146, v1
	v_lshlrev_b32_e32 v146, 16, v147
	v_and_b32_e32 v147, 0xffff0000, v147
	v_mul_f32_e32 v155, v147, v147
	v_fmac_f32_e32 v155, v146, v146
	v_add_f32_e32 v1, v155, v1
	s_nop 1
	v_add_f32_dpp v1, v1, v1 quad_perm:[1,0,3,2] row_mask:0xf bank_mask:0xf bound_ctrl:1
	s_nop 1
	v_add_f32_dpp v1, v1, v1 quad_perm:[2,3,0,1] row_mask:0xf bank_mask:0xf bound_ctrl:1
	s_nop 1
	v_add_f32_dpp v1, v1, v1 row_half_mirror row_mask:0xf bank_mask:0xf bound_ctrl:1
	s_nop 1
	v_add_f32_dpp v1, v1, v1 row_mirror row_mask:0xf bank_mask:0xf bound_ctrl:1
	v_mov_b32_e32 v155, v1
	s_nop 1
	v_permlane16_swap_b32_e32 v1, v155
	v_add_f32_e32 v1, v1, v155
	v_mov_b32_e32 v155, v1
	s_nop 1
	v_permlane32_swap_b32_e32 v1, v155
	v_add_f32_e32 v1, v1, v155
	v_fmamk_f32 v1, v1, 0x3a000000, v218
	v_cmp_gt_f32_e32 vcc, s14, v1
	v_mul_f32_e32 v155, 0x4f800000, v1
	s_nop 0
	v_cndmask_b32_e32 v1, v1, v155, vcc
	v_sqrt_f32_e32 v155, v1
	s_nop 0
	v_add_u32_e32 v174, -1, v155
	v_fma_f32 v175, -v174, v155, v1
	v_cmp_ge_f32_e64 s[40:41], 0, v175
	v_add_u32_e32 v175, 1, v155
	s_nop 0
	v_cndmask_b32_e64 v174, v155, v174, s[40:41]
	v_fma_f32 v155, -v175, v155, v1
	v_cmp_lt_f32_e64 s[40:41], 0, v155
	s_nop 1
	v_cndmask_b32_e64 v155, v174, v175, s[40:41]
	v_mul_f32_e32 v174, 0x37800000, v155
	v_cndmask_b32_e32 v155, v155, v174, vcc
	v_cmp_class_f32_e32 vcc, v1, v215
	s_nop 1
	v_cndmask_b32_e32 v1, v155, v1, vcc
	v_div_scale_f32 v155, s[0:1], v1, v1, 1.0
	v_rcp_f32_e32 v174, v155
	s_nop 0
	v_fma_f32 v175, -v155, v174, 1.0
	v_fmac_f32_e32 v174, v175, v174
	v_div_scale_f32 v175, vcc, 1.0, v1, 1.0
	v_mul_f32_e32 v176, v175, v174
	v_fma_f32 v177, -v155, v176, v175
	v_fmac_f32_e32 v176, v177, v174
	v_fma_f32 v155, -v155, v176, v175
	v_div_fmas_f32 v155, v155, v174, v176
	v_div_fixup_f32 v174, v155, v1, 1.0
	v_pk_mul_f32 v[130:131], v[154:155], v[130:131] op_sel_hi:[0,1]
	v_pk_fma_f32 v[62:63], v[2:3], v[130:131], v[62:63]
	v_pk_mul_f32 v[130:131], v[174:175], v[158:159] op_sel_hi:[0,1]
	v_pk_fma_f32 v[94:95], v[2:3], v[130:131], v[94:95]
	v_pk_mul_f32 v[130:131], v[154:155], v[136:137] op_sel_hi:[0,1]
	v_pk_fma_f32 v[58:59], v[6:7], v[130:131], v[58:59]
	v_pk_mul_f32 v[130:131], v[174:175], v[160:161] op_sel_hi:[0,1]
	v_pk_mul_f32 v[136:137], v[154:155], v[148:149] op_sel_hi:[0,1]
	v_pk_fma_f32 v[90:91], v[6:7], v[130:131], v[90:91]
	v_pk_mul_f32 v[130:131], v[154:155], v[138:139] op_sel_hi:[0,1]
	v_pk_fma_f32 v[60:61], v[8:9], v[136:137], v[60:61]
	v_pk_mul_f32 v[136:137], v[174:175], v[152:153] op_sel_hi:[0,1]
	v_pk_fma_f32 v[54:55], v[10:11], v[130:131], v[54:55]
	v_pk_mul_f32 v[130:131], v[174:175], v[162:163] op_sel_hi:[0,1]
	v_pk_mul_f32 v[140:141], v[154:155], v[140:141] op_sel_hi:[0,1]
	v_pk_fma_f32 v[92:93], v[8:9], v[136:137], v[92:93]
	v_pk_mul_f32 v[136:137], v[154:155], v[144:145] op_sel_hi:[0,1]
	v_pk_fma_f32 v[86:87], v[10:11], v[130:131], v[86:87]
	v_pk_mul_f32 v[128:129], v[154:155], v[128:129] op_sel_hi:[0,1]
	v_pk_mul_f32 v[130:131], v[154:155], v[134:135] op_sel_hi:[0,1]
	v_pk_mul_f32 v[122:123], v[154:155], v[122:123] op_sel_hi:[0,1]
	v_pk_mul_f32 v[126:127], v[154:155], v[126:127] op_sel_hi:[0,1]
	v_pk_mul_f32 v[118:119], v[154:155], v[118:119] op_sel_hi:[0,1]
	v_pk_mul_f32 v[120:121], v[154:155], v[120:121] op_sel_hi:[0,1]
	v_pk_mul_f32 v[112:113], v[154:155], v[112:113] op_sel_hi:[0,1]
	v_pk_mul_f32 v[114:115], v[154:155], v[114:115] op_sel_hi:[0,1]
	v_pk_mul_f32 v[108:109], v[154:155], v[108:109] op_sel_hi:[0,1]
	v_pk_mul_f32 v[110:111], v[154:155], v[110:111] op_sel_hi:[0,1]
	v_pk_fma_f32 v[64:65], v[4:5], v[140:141], v[64:65]
	v_pk_mul_f32 v[140:141], v[174:175], v[156:157] op_sel_hi:[0,1]
	v_pk_fma_f32 v[56:57], v[12:13], v[136:137], v[56:57]
	v_pk_mul_f32 v[136:137], v[174:175], v[150:151] op_sel_hi:[0,1]
	v_pk_fma_f32 v[52:53], v[16:17], v[130:131], v[52:53]
	v_pk_fma_f32 v[50:51], v[14:15], v[128:129], v[50:51]
	v_pk_mul_f32 v[128:129], v[174:175], v[164:165] op_sel_hi:[0,1]
	v_pk_mul_f32 v[130:131], v[174:175], v[142:143] op_sel_hi:[0,1]
	v_pk_fma_f32 v[48:49], v[20:21], v[126:127], v[48:49]
	v_pk_fma_f32 v[46:47], v[18:19], v[122:123], v[46:47]
	v_pk_mul_f32 v[122:123], v[174:175], v[166:167] op_sel_hi:[0,1]
	v_pk_mul_f32 v[126:127], v[174:175], v[132:133] op_sel_hi:[0,1]
	v_pk_fma_f32 v[44:45], v[24:25], v[120:121], v[44:45]
	v_pk_fma_f32 v[42:43], v[22:23], v[118:119], v[42:43]
	v_pk_mul_f32 v[118:119], v[174:175], v[168:169] op_sel_hi:[0,1]
	v_pk_mul_f32 v[120:121], v[174:175], v[124:125] op_sel_hi:[0,1]
	v_pk_fma_f32 v[40:41], v[28:29], v[114:115], v[40:41]
	v_pk_fma_f32 v[38:39], v[26:27], v[112:113], v[38:39]
	v_pk_mul_f32 v[112:113], v[174:175], v[170:171] op_sel_hi:[0,1]
	v_pk_mul_f32 v[114:115], v[174:175], v[172:173] op_sel_hi:[0,1]
	v_pk_fma_f32 v[36:37], v[32:33], v[110:111], v[36:37]
	v_pk_fma_f32 v[34:35], v[30:31], v[108:109], v[34:35]
	v_pk_mul_f32 v[108:109], v[174:175], v[116:117] op_sel_hi:[0,1]
	v_pk_mul_f32 v[110:111], v[174:175], v[146:147] op_sel_hi:[0,1]
	v_pk_fma_f32 v[96:97], v[4:5], v[140:141], v[96:97]
	v_pk_fma_f32 v[88:89], v[12:13], v[136:137], v[88:89]
	v_pk_fma_f32 v[84:85], v[16:17], v[130:131], v[84:85]
	v_pk_fma_f32 v[82:83], v[14:15], v[128:129], v[82:83]
	v_pk_fma_f32 v[80:81], v[20:21], v[126:127], v[80:81]
	v_pk_fma_f32 v[78:79], v[18:19], v[122:123], v[78:79]
	v_pk_fma_f32 v[76:77], v[24:25], v[120:121], v[76:77]
	v_pk_fma_f32 v[74:75], v[22:23], v[118:119], v[74:75]
	v_pk_fma_f32 v[72:73], v[28:29], v[114:115], v[72:73]
	v_pk_fma_f32 v[70:71], v[26:27], v[112:113], v[70:71]
	v_pk_fma_f32 v[68:69], v[32:33], v[110:111], v[68:69]
	v_pk_fma_f32 v[66:67], v[30:31], v[108:109], v[66:67]
	global_store_dwordx4 v[104:105], v[62:65], off sc1
	global_store_dwordx4 v[102:103], v[58:61], off offset:-3072 sc1
	global_store_dwordx4 v[102:103], v[54:57], off offset:-2048 sc1
	global_store_dwordx4 v[102:103], v[50:53], off offset:-1024 sc1
	global_store_dwordx4 v[100:101], v[46:49], off offset:-4096 sc1
	global_store_dwordx4 v[100:101], v[42:45], off offset:-3072 sc1
	global_store_dwordx4 v[100:101], v[38:41], off offset:-2048 sc1
	global_store_dwordx4 v[100:101], v[34:37], off offset:-1024 sc1
	global_store_dwordx4 v[100:101], v[94:97], off sc1
	global_store_dwordx4 v[100:101], v[90:93], off offset:1024 sc1
	global_store_dwordx4 v[100:101], v[86:89], off offset:2048 sc1
	global_store_dwordx4 v[100:101], v[82:85], off offset:3072 sc1
	global_store_dwordx4 v[106:107], v[78:81], off sc1
	global_store_dwordx4 v[106:107], v[74:77], off offset:1024 sc1
	global_store_dwordx4 v[106:107], v[70:73], off offset:2048 sc1
	global_store_dwordx4 v[106:107], v[66:69], off offset:3072 sc1
	v_lshl_add_u64 v[100:101], v[100:101], 0, s[12:13]
	s_cbranch_scc0 .LBB0_230

; __device__ __forceinline__ unsigned cvt_pk_bf16(float lo, float hi) { unsigned r; asm volatile("v_cvt_pk_bf16_f32 %0, %1, %2" : "=v"(r) : "v"(lo), "v"(hi)); return r; }
;     __device__ __forceinline__ void operator()(const f32x4 (&acc)[2][2][4][2], const Unit& u, int wr, int wc, int fr, int fq) const {
;         const int row0 = u.pm * BM + wr * 64 + fr; int colt = u.pn * BM; bf16_t* base = O;
;         float sc = 1.f; if (split_cols) { const int t = colt / split_cols; base += (size_t)t * split_stride; colt -= t * split_cols; if (t == 0) sc = scale0; }
;         const int col0 = colt + wc * 32 + 8 * fq, bcol0 = u.pn * BM + wc * 32 + 8 * fq;
;         f32x4 bv[2][2];
; #pragma unroll
;         for (int bj = 0; bj < 2; ++bj)
; #pragma unroll
;             for (int n = 0; n < 2; ++n) bv[bj][n] = bias ? *(const f32x4*)(bias + bcol0 + bj * HALF + 4 * n) : (f32x4){0.f, 0.f, 0.f, 0.f};
; #pragma unroll
;         for (int ai = 0; ai < 2; ++ai)
; #pragma unroll
;             for (int m = 0; m < 4; ++m) { bf16_t* rowp = base + (size_t)(row0 + ai * HALF + m * 16) * ldc + col0;
; #pragma unroll
;                 for (int bj = 0; bj < 2; ++bj) { f32x4 v0 = acc[ai][bj][m][0] + bv[bj][0], v1 = acc[ai][bj][m][1] + bv[bj][1];
;                     if (ACT == 1) { f32x2 a = gelu_pk((f32x2){v0[0], v0[1]}), b = gelu_pk((f32x2){v0[2], v0[3]}), c = gelu_pk((f32x2){v1[0], v1[1]}), d = gelu_pk((f32x2){v1[2], v1[3]});
;                         v0 = (f32x4){a.x, a.y, b.x, b.y}; v1 = (f32x4){c.x, c.y, d.x, d.y}; }
;                     v0 = v0 * sc; v1 = v1 * sc; u32x4 w; w.x = cvt_pk_bf16(v0[0], v0[1]); w.y = cvt_pk_bf16(v0[2], v0[3]); w.z = cvt_pk_bf16(v1[0], v1[1]); w.w = cvt_pk_bf16(v1[2], v1[3]);
;                     *(u32x4*)(rowp + bj * HALF) = w; } }
.LBB0_377:
	s_ashr_i32 s69, s68, 31
	s_lshl_b32 s12, s68, 8
	s_lshl_b64 s[6:7], s[68:69], 23
	s_and_b64 s[8:9], s[98:99], exec
	s_cselect_b32 s6, 0, s6
	s_cselect_b32 s7, 0, s7
	s_add_u32 s6, s30, s6
	s_addc_u32 s7, s31, s7
	s_and_b64 s[8:9], s[98:99], exec
	s_cselect_b32 s8, s12, 0
	v_lshl_add_u32 v147, s44, 8, v1
	v_or_b32_e32 v142, s8, v145
	v_ashrrev_i32_e32 v143, 31, v142
	v_ashrrev_i32_e32 v148, 31, v147
	v_lshl_add_u64 v[142:143], v[142:143], 1, s[6:7]
	v_mul_lo_u32 v152, s57, v148
	v_mad_u64_u32 v[148:149], s[6:7], s57, v147, 0
	v_add_u32_e32 v149, v149, v152
	v_lshl_add_u64 v[148:149], v[148:149], 1, v[142:143]
	v_pk_add_f32 v[128:129], v[128:129], 0 op_sel_hi:[1,0]
	v_pk_add_f32 v[126:127], v[126:127], 0 op_sel_hi:[1,0]
	v_pk_add_f32 v[150:151], v[124:125], 0 op_sel_hi:[1,0]
	v_pk_add_f32 v[124:125], v[122:123], 0 op_sel_hi:[1,0]
	v_cvt_pk_bf16_f32 v122, v126, v127
	v_cvt_pk_bf16_f32 v123, v128, v129
	v_pk_add_f32 v[118:119], v[118:119], 0 op_sel_hi:[1,0]
	v_cvt_pk_bf16_f32 v124, v124, v125
	v_cvt_pk_bf16_f32 v125, v150, v151
	global_store_dwordx4 v[148:149], v[122:125], off sc1
	v_pk_add_f32 v[120:121], v[120:121], 0 op_sel_hi:[1,0]
	v_pk_add_f32 v[114:115], v[114:115], 0 op_sel_hi:[1,0]
	v_pk_add_f32 v[122:123], v[112:113], 0 op_sel_hi:[1,0]
	v_pk_add_f32 v[112:113], v[110:111], 0 op_sel_hi:[1,0]
	v_cvt_pk_bf16_f32 v110, v118, v119
	v_cvt_pk_bf16_f32 v111, v120, v121
	v_pk_add_f32 v[102:103], v[102:103], 0 op_sel_hi:[1,0]
	v_cvt_pk_bf16_f32 v112, v112, v113
	v_cvt_pk_bf16_f32 v113, v122, v123
	global_store_dwordx4 v[148:149], v[110:113], off offset:256 sc1
	v_pk_add_f32 v[104:105], v[104:105], 0 op_sel_hi:[1,0]
	v_pk_add_f32 v[98:99], v[98:99], 0 op_sel_hi:[1,0]
	v_or_b32_e32 v110, 16, v147
	v_mad_u64_u32 v[110:111], s[6:7], s57, v110, 0
	v_add_u32_e32 v111, v111, v152
	v_lshl_add_u64 v[110:111], v[110:111], 1, v[142:143]
	v_pk_add_f32 v[112:113], v[116:117], 0 op_sel_hi:[1,0]
	v_pk_add_f32 v[116:117], v[108:109], 0 op_sel_hi:[1,0]
	v_pk_add_f32 v[108:109], v[106:107], 0 op_sel_hi:[1,0]
	v_cvt_pk_bf16_f32 v106, v114, v115
	v_cvt_pk_bf16_f32 v107, v112, v113
	v_pk_add_f32 v[86:87], v[86:87], 0 op_sel_hi:[1,0]
	v_cvt_pk_bf16_f32 v108, v108, v109
	v_cvt_pk_bf16_f32 v109, v116, v117
	global_store_dwordx4 v[110:111], v[106:109], off sc1
	v_pk_add_f32 v[88:89], v[88:89], 0 op_sel_hi:[1,0]
	v_pk_add_f32 v[82:83], v[82:83], 0 op_sel_hi:[1,0]
	v_pk_add_f32 v[106:107], v[96:97], 0 op_sel_hi:[1,0]
	v_pk_add_f32 v[96:97], v[94:95], 0 op_sel_hi:[1,0]
	v_cvt_pk_bf16_f32 v94, v102, v103
	v_cvt_pk_bf16_f32 v95, v104, v105
	v_pk_add_f32 v[70:71], v[70:71], 0 op_sel_hi:[1,0]
	v_cvt_pk_bf16_f32 v96, v96, v97
	v_cvt_pk_bf16_f32 v97, v106, v107
	global_store_dwordx4 v[110:111], v[94:97], off offset:256 sc1
	v_pk_add_f32 v[72:73], v[72:73], 0 op_sel_hi:[1,0]
	v_pk_add_f32 v[64:65], v[64:65], 0 op_sel_hi:[1,0]
	v_or_b32_e32 v94, 32, v147
	v_mad_u64_u32 v[94:95], s[6:7], s57, v94, 0
	v_add_u32_e32 v95, v95, v152
	v_lshl_add_u64 v[94:95], v[94:95], 1, v[142:143]
	v_pk_add_f32 v[96:97], v[100:101], 0 op_sel_hi:[1,0]
	v_pk_add_f32 v[100:101], v[92:93], 0 op_sel_hi:[1,0]
	v_pk_add_f32 v[92:93], v[90:91], 0 op_sel_hi:[1,0]
	v_cvt_pk_bf16_f32 v90, v98, v99
	v_cvt_pk_bf16_f32 v91, v96, v97
	v_pk_add_f32 v[62:63], v[62:63], 0 op_sel_hi:[1,0]
	v_cvt_pk_bf16_f32 v92, v92, v93
	v_cvt_pk_bf16_f32 v93, v100, v101
	global_store_dwordx4 v[94:95], v[90:93], off sc1
	v_pk_add_f32 v[54:55], v[54:55], 0 op_sel_hi:[1,0]
	v_pk_add_f32 v[56:57], v[56:57], 0 op_sel_hi:[1,0]
	v_pk_add_f32 v[90:91], v[80:81], 0 op_sel_hi:[1,0]
	v_pk_add_f32 v[80:81], v[78:79], 0 op_sel_hi:[1,0]
	v_cvt_pk_bf16_f32 v78, v86, v87
	v_cvt_pk_bf16_f32 v79, v88, v89
	v_pk_add_f32 v[48:49], v[48:49], 0 op_sel_hi:[1,0]
	v_cvt_pk_bf16_f32 v80, v80, v81
	v_cvt_pk_bf16_f32 v81, v90, v91
	global_store_dwordx4 v[94:95], v[78:81], off offset:256 sc1
	v_pk_add_f32 v[46:47], v[46:47], 0 op_sel_hi:[1,0]
	v_pk_add_f32 v[38:39], v[38:39], 0 op_sel_hi:[1,0]
	v_or_b32_e32 v78, 48, v147
	v_mad_u64_u32 v[78:79], s[6:7], s57, v78, 0
	v_add_u32_e32 v79, v79, v152
	v_lshl_add_u64 v[78:79], v[78:79], 1, v[142:143]
	v_pk_add_f32 v[80:81], v[84:85], 0 op_sel_hi:[1,0]
	v_pk_add_f32 v[84:85], v[76:77], 0 op_sel_hi:[1,0]
	v_pk_add_f32 v[76:77], v[74:75], 0 op_sel_hi:[1,0]
	v_cvt_pk_bf16_f32 v74, v82, v83
	v_cvt_pk_bf16_f32 v75, v80, v81
	v_pk_add_f32 v[40:41], v[40:41], 0 op_sel_hi:[1,0]
	v_cvt_pk_bf16_f32 v76, v76, v77
; __device__ __forceinline__ unsigned cvt_pk_bf16(float lo, float hi) { unsigned r; asm volatile("v_cvt_pk_bf16_f32 %0, %1, %2" : "=v"(r) : "v"(lo), "v"(hi)); return r; }
; #define PG8_BAR __builtin_amdgcn_s_barrier()
;     __device__ __forceinline__ void operator()(const f32x4 (&acc)[2][2][4][2], const Unit& u, int wr, int wc, int fr, int fq) const {
;     ...
;         for (int ai = 0; ai < 2; ++ai)
; #pragma unroll
;             for (int m = 0; m < 4; ++m) { bf16_t* rowp = base + (size_t)(row0 + ai * HALF + m * 16) * ldc + col0;
; #pragma unroll
;                 for (int bj = 0; bj < 2; ++bj) { f32x4 v0 = acc[ai][bj][m][0] + bv[bj][0], v1 = acc[ai][bj][m][1] + bv[bj][1];
;                     if (ACT == 1) { f32x2 a = gelu_pk((f32x2){v0[0], v0[1]}), b = gelu_pk((f32x2){v0[2], v0[3]}), c = gelu_pk((f32x2){v1[0], v1[1]}), d = gelu_pk((f32x2){v1[2], v1[3]});
;                         v0 = (f32x4){a.x, a.y, b.x, b.y}; v1 = (f32x4){c.x, c.y, d.x, d.y}; }
;                     v0 = v0 * sc; v1 = v1 * sc; u32x4 w; w.x = cvt_pk_bf16(v0[0], v0[1]); w.y = cvt_pk_bf16(v0[2], v0[3]); w.z = cvt_pk_bf16(v1[0], v1[1]); w.w = cvt_pk_bf16(v1[2], v1[3]);
;                     *(u32x4*)(rowp + bj * HALF) = w; } }
; template <class Epi, class Sched, bool ALIGN_EPI = false, bool SP2 = false>
; __device__ __forceinline__ void gemm_phase(PG8_LAS unsigned char* lds, const Gemm g, const Sched& S, const Epi& E) {
;     ...
;         cur = nxt; cA = nA; cB = nB; ++ui;
;         if constexpr (ALIGN_EPI) { if (wr == 1) PG8_BAR; }
	v_cvt_pk_bf16_f32 v77, v84, v85
	global_store_dwordx4 v[78:79], v[74:77], off sc1
	v_pk_add_f32 v[32:33], v[32:33], 0 op_sel_hi:[1,0]
	v_pk_add_f32 v[30:31], v[30:31], 0 op_sel_hi:[1,0]
	v_pk_add_f32 v[74:75], v[68:69], 0 op_sel_hi:[1,0]
	v_pk_add_f32 v[68:69], v[66:67], 0 op_sel_hi:[1,0]
	v_cvt_pk_bf16_f32 v66, v70, v71
	v_cvt_pk_bf16_f32 v67, v72, v73
	v_pk_add_f32 v[22:23], v[22:23], 0 op_sel_hi:[1,0]
	v_cvt_pk_bf16_f32 v68, v68, v69
	v_cvt_pk_bf16_f32 v69, v74, v75
	global_store_dwordx4 v[78:79], v[66:69], off offset:256 sc1
	v_pk_add_f32 v[24:25], v[24:25], 0 op_sel_hi:[1,0]
	v_pk_add_f32 v[16:17], v[16:17], 0 op_sel_hi:[1,0]
	v_add_u32_e32 v66, 0x80, v147
	v_ashrrev_i32_e32 v69, 31, v66
	v_mad_u64_u32 v[66:67], s[6:7], s57, v66, 0
	v_mov_b32_e32 v68, v67
	v_mad_u64_u32 v[68:69], s[6:7], s57, v69, v[68:69]
	v_mov_b32_e32 v67, v68
	v_lshl_add_u64 v[66:67], v[66:67], 1, v[142:143]
	v_pk_add_f32 v[68:69], v[60:61], 0 op_sel_hi:[1,0]
	v_pk_add_f32 v[60:61], v[58:59], 0 op_sel_hi:[1,0]
	v_cvt_pk_bf16_f32 v58, v62, v63
	v_cvt_pk_bf16_f32 v59, v64, v65
	v_pk_add_f32 v[14:15], v[14:15], 0 op_sel_hi:[1,0]
	v_cvt_pk_bf16_f32 v60, v60, v61
	v_cvt_pk_bf16_f32 v61, v68, v69
	global_store_dwordx4 v[66:67], v[58:61], off sc1
	s_andn2_b64 vcc, exec, s[40:41]
	v_pk_add_f32 v[8:9], v[8:9], 0 op_sel_hi:[1,0]
	v_pk_add_f32 v[58:59], v[52:53], 0 op_sel_hi:[1,0]
	v_pk_add_f32 v[52:53], v[50:51], 0 op_sel_hi:[1,0]
	v_cvt_pk_bf16_f32 v50, v54, v55
	v_cvt_pk_bf16_f32 v51, v56, v57
	v_pk_add_f32 v[6:7], v[6:7], 0 op_sel_hi:[1,0]
	v_cvt_pk_bf16_f32 v52, v52, v53
	v_cvt_pk_bf16_f32 v53, v58, v59
	global_store_dwordx4 v[66:67], v[50:53], off offset:256 sc1
	s_nop 1
	v_add_u32_e32 v50, 0x90, v147
	v_ashrrev_i32_e32 v53, 31, v50
	v_mad_u64_u32 v[50:51], s[6:7], s57, v50, 0
	v_mov_b32_e32 v52, v51
	v_mad_u64_u32 v[52:53], s[6:7], s57, v53, v[52:53]
	v_mov_b32_e32 v51, v52
	v_lshl_add_u64 v[50:51], v[50:51], 1, v[142:143]
	v_pk_add_f32 v[52:53], v[44:45], 0 op_sel_hi:[1,0]
	v_pk_add_f32 v[44:45], v[42:43], 0 op_sel_hi:[1,0]
	v_cvt_pk_bf16_f32 v42, v46, v47
	v_cvt_pk_bf16_f32 v43, v48, v49
	s_nop 0
	v_cvt_pk_bf16_f32 v44, v44, v45
	v_cvt_pk_bf16_f32 v45, v52, v53
	global_store_dwordx4 v[50:51], v[42:45], off sc1
	s_nop 1
	v_pk_add_f32 v[42:43], v[36:37], 0 op_sel_hi:[1,0]
	v_pk_add_f32 v[36:37], v[34:35], 0 op_sel_hi:[1,0]
	v_cvt_pk_bf16_f32 v34, v38, v39
	v_cvt_pk_bf16_f32 v35, v40, v41
	s_nop 0
	v_cvt_pk_bf16_f32 v36, v36, v37
	v_cvt_pk_bf16_f32 v37, v42, v43
	global_store_dwordx4 v[50:51], v[34:37], off offset:256 sc1
	s_nop 1
	v_add_u32_e32 v34, 0xa0, v147
	v_ashrrev_i32_e32 v37, 31, v34
	v_mad_u64_u32 v[34:35], s[6:7], s57, v34, 0
	v_mov_b32_e32 v36, v35
	v_mad_u64_u32 v[36:37], s[6:7], s57, v37, v[36:37]
	v_mov_b32_e32 v35, v36
	v_lshl_add_u64 v[34:35], v[34:35], 1, v[142:143]
	v_pk_add_f32 v[36:37], v[28:29], 0 op_sel_hi:[1,0]
	v_pk_add_f32 v[28:29], v[26:27], 0 op_sel_hi:[1,0]
	v_cvt_pk_bf16_f32 v26, v30, v31
	v_cvt_pk_bf16_f32 v27, v32, v33
	s_nop 0
	v_cvt_pk_bf16_f32 v28, v28, v29
	v_cvt_pk_bf16_f32 v29, v36, v37
	global_store_dwordx4 v[34:35], v[26:29], off sc1
	s_nop 1
	v_pk_add_f32 v[26:27], v[20:21], 0 op_sel_hi:[1,0]
	v_pk_add_f32 v[20:21], v[18:19], 0 op_sel_hi:[1,0]
	v_cvt_pk_bf16_f32 v18, v22, v23
	v_cvt_pk_bf16_f32 v19, v24, v25
	s_nop 0
	v_cvt_pk_bf16_f32 v20, v20, v21
	v_cvt_pk_bf16_f32 v21, v26, v27
	global_store_dwordx4 v[34:35], v[18:21], off offset:256 sc1
	s_nop 1
	v_add_u32_e32 v18, 0xb0, v147
	v_ashrrev_i32_e32 v21, 31, v18
	v_mad_u64_u32 v[18:19], s[6:7], s57, v18, 0
	v_mov_b32_e32 v20, v19
	v_mad_u64_u32 v[20:21], s[6:7], s57, v21, v[20:21]
	v_mov_b32_e32 v19, v20
	v_lshl_add_u64 v[18:19], v[18:19], 1, v[142:143]
	v_pk_add_f32 v[20:21], v[12:13], 0 op_sel_hi:[1,0]
	v_pk_add_f32 v[12:13], v[10:11], 0 op_sel_hi:[1,0]
	v_cvt_pk_bf16_f32 v10, v14, v15
	v_cvt_pk_bf16_f32 v11, v16, v17
	s_mov_b64 s[6:7], -1
	v_cvt_pk_bf16_f32 v12, v12, v13
	v_cvt_pk_bf16_f32 v13, v20, v21
	global_store_dwordx4 v[18:19], v[10:13], off sc1
	s_nop 1
	v_pk_add_f32 v[10:11], v[4:5], 0 op_sel_hi:[1,0]
	v_pk_add_f32 v[4:5], v[2:3], 0 op_sel_hi:[1,0]
	v_cvt_pk_bf16_f32 v2, v6, v7
	v_cvt_pk_bf16_f32 v3, v8, v9
	s_nop 0
	v_cvt_pk_bf16_f32 v4, v4, v5
	v_cvt_pk_bf16_f32 v5, v10, v11
	global_store_dwordx4 v[18:19], v[2:5], off offset:256 sc1
	s_cbranch_vccnz .LBB0_368
	s_andn2_b64 vcc, exec, s[84:85]
	s_cbranch_vccnz .LBB0_367
	s_barrier
	s_branch .LBB0_367

; #define LAS __attribute__((address_space(3)))
; __device__ __forceinline__ unsigned pk2(float lo, float hi) { return f2bf(lo) | (f2bf(hi) << 16); }
; #define LDS_WAIT() asm volatile("s_waitcnt lgkmcnt(0)" ::: "memory")
; __device__ __forceinline__ void wt_item(const float* __restrict__ W, int ldw, int K, int src_c0, bf16_t* __restrict__ WT, int dst_r0, int k0, LAS float* scr, int lane, int Ndst) {
; #pragma unroll 32
;     for (int i = 0; i < 32; ++i) { const int kk = 2 * i + (lane >> 5); scr[kk * 33 + (lane & 31)] = (src_c0 >= 0) ? W[(size_t)(k0 + kk) * ldw + src_c0 + (lane & 31)] : 0.f; }
;     LDS_WAIT(); asm volatile("" ::: "memory");
;     const int c = lane & 7;
; #pragma unroll
;     for (int j = 0; j < 4; ++j) { const int n = (lane >> 3) + 8 * j; const LAS float* s = scr + (8 * c) * 33 + n;
;         v4u o; o.x = pk2(s[0 * 33], s[1 * 33]); o.y = pk2(s[2 * 33], s[3 * 33]); o.z = pk2(s[4 * 33], s[5 * 33]); o.w = pk2(s[6 * 33], s[7 * 33]);
;         *(v4u*)(WT + ((size_t)(k0 >> 6) * Ndst + dst_r0 + n) * 64 + 8 * c) = o; }
;     LDS_WAIT(); asm volatile("" ::: "memory");
; }
; __device__ __forceinline__ void conv_generic(const float* W, int ldw, int K, int Ndst, bool win_map, bf16_t* WT, LAS float* scr, int gw, int NGW, int lane) {
;     const int nblk = Ndst / 32, items = (K / 64) * nblk;
;     for (int it = gw; it < items; it += NGW) { const int kb = it / nblk, nb = it % nblk; int src = nb * 32;
;         if (win_map) src = nb < 32 ? nb * 32 : nb < 96 ? 1088 + (nb - 32) * 32 : nb < 98 ? 1024 + (nb - 96) * 32 : -1;
;         wt_item(W, ldw, K, src, WT, nb * 32, kb * 64, scr, lane, Ndst); }
.LBB0_409:
	v_add_u32_e32 v13, 0x1400, v50
	s_waitcnt vmcnt(2)
	ds_write2_b32 v13, v11, v51 offset0:40 offset1:106
	s_waitcnt vmcnt(0)
	ds_write2_b32 v13, v52, v53 offset0:172 offset1:238
	s_waitcnt lgkmcnt(0)
	ds_read2_b32 v[18:19], v47 offset1:8
	ds_read2_b32 v[56:57], v47 offset0:33 offset1:41
	ds_read2_b32 v[58:59], v47 offset0:66 offset1:74
	ds_read2_b32 v[60:61], v47 offset0:99 offset1:107
	ds_read2_b32 v[62:63], v47 offset0:132 offset1:140
	s_waitcnt lgkmcnt(4)
	v_bfe_u32 v11, v18, 16, 1
	v_add3_u32 v11, v18, v11, s63
	s_waitcnt lgkmcnt(3)
	v_bfe_u32 v13, v56, 16, 1
	v_lshrrev_b32_e32 v11, 16, v11
	v_add3_u32 v13, v56, v13, s63
	ds_read2_b32 v[64:65], v47 offset0:165 offset1:173
	v_and_or_b32 v52, v13, s60, v11
	s_waitcnt lgkmcnt(3)
	v_bfe_u32 v11, v58, 16, 1
	v_add3_u32 v11, v58, v11, s63
	s_waitcnt lgkmcnt(2)
	v_bfe_u32 v13, v60, 16, 1
	ds_read2_b32 v[66:67], v47 offset0:198 offset1:206
	v_lshrrev_b32_e32 v11, 16, v11
	v_add3_u32 v13, v60, v13, s63
	ds_read2_b32 v[68:69], v47 offset0:231 offset1:239
	v_and_or_b32 v53, v13, s60, v11
	s_waitcnt lgkmcnt(3)
	v_bfe_u32 v11, v62, 16, 1
	s_ashr_i32 s0, s22, 31
	v_add3_u32 v11, v62, v11, s63
	s_waitcnt lgkmcnt(2)
	v_bfe_u32 v13, v64, 16, 1
	s_mul_hi_u32 s1, s22, s14
	s_mul_i32 s0, s0, s14
	v_lshrrev_b32_e32 v11, 16, v11
	v_add3_u32 v13, v64, v13, s63
	s_add_i32 s1, s1, s0
	s_mul_i32 s22, s22, s14
	s_ashr_i32 s0, s21, 31
	v_and_or_b32 v54, v13, s60, v11
	s_waitcnt lgkmcnt(1)
	v_bfe_u32 v11, v66, 16, 1
	s_add_u32 s5, s22, s21
	v_add3_u32 v11, v66, v11, s63
	s_waitcnt lgkmcnt(0)
	v_bfe_u32 v13, v68, 16, 1
	s_addc_u32 s0, s1, s0
	v_lshrrev_b32_e32 v11, 16, v11
	v_add3_u32 v13, v68, v13, s63
	v_and_or_b32 v55, v13, s60, v11
	v_mov_b32_e32 v71, s0
	v_or_b32_e32 v70, s5, v2
	v_bfe_u32 v11, v19, 16, 1
	v_lshlrev_b64 v[70:71], 7, v[70:71]
	v_add3_u32 v11, v19, v11, s63
	v_bfe_u32 v13, v57, 16, 1
	v_lshl_add_u64 v[70:71], v[16:17], 0, v[70:71]
	v_lshrrev_b32_e32 v11, 16, v11
	v_add3_u32 v13, v57, v13, s63
	global_store_dwordx4 v[70:71], v[52:55], off sc1
	v_mov_b32_e32 v19, s0
	v_or_b32_e32 v18, s5, v4
	v_and_or_b32 v52, v13, s60, v11
	v_bfe_u32 v11, v59, 16, 1
	v_add3_u32 v11, v59, v11, s63
	v_bfe_u32 v13, v61, 16, 1
	v_lshrrev_b32_e32 v11, 16, v11
	v_add3_u32 v13, v61, v13, s63
	v_and_or_b32 v53, v13, s60, v11
	v_bfe_u32 v11, v63, 16, 1
	v_add3_u32 v11, v63, v11, s63
	v_bfe_u32 v13, v65, 16, 1
	v_lshrrev_b32_e32 v11, 16, v11
	v_add3_u32 v13, v65, v13, s63
	v_and_or_b32 v54, v13, s60, v11
	v_bfe_u32 v11, v67, 16, 1
	v_add3_u32 v11, v67, v11, s63
	v_bfe_u32 v13, v69, 16, 1
	v_lshrrev_b32_e32 v11, 16, v11
	v_add3_u32 v13, v69, v13, s63
	v_lshlrev_b64 v[18:19], 7, v[18:19]
	v_and_or_b32 v55, v13, s60, v11
	ds_read2_b32 v[56:57], v47 offset0:16 offset1:24
	v_lshl_add_u64 v[18:19], v[16:17], 0, v[18:19]
	global_store_dwordx4 v[18:19], v[52:55], off sc1
	ds_read2_b32 v[18:19], v47 offset0:49 offset1:57
	ds_read2_b32 v[58:59], v47 offset0:82 offset1:90
	ds_read2_b32 v[60:61], v47 offset0:115 offset1:123
	s_waitcnt lgkmcnt(3)
	v_bfe_u32 v11, v56, 16, 1
	v_add3_u32 v11, v56, v11, s63
	s_waitcnt lgkmcnt(2)
	v_bfe_u32 v13, v18, 16, 1
	ds_read2_b32 v[62:63], v47 offset0:148 offset1:156
	v_lshrrev_b32_e32 v11, 16, v11
	v_add3_u32 v13, v18, v13, s63
	ds_read2_b32 v[64:65], v47 offset0:181 offset1:189
	v_and_or_b32 v52, v13, s60, v11
	s_waitcnt lgkmcnt(3)
	v_bfe_u32 v11, v58, 16, 1
	v_add3_u32 v11, v58, v11, s63
	s_waitcnt lgkmcnt(2)
	v_bfe_u32 v13, v60, 16, 1
	ds_read2_b32 v[66:67], v47 offset0:214 offset1:222
	v_lshrrev_b32_e32 v11, 16, v11
	v_add3_u32 v13, v60, v13, s63
	ds_read2_b32 v[68:69], v47 offset0:247 offset1:255
	v_and_or_b32 v53, v13, s60, v11
	s_waitcnt lgkmcnt(3)
	v_bfe_u32 v11, v62, 16, 1
	v_add3_u32 v11, v62, v11, s63
	s_waitcnt lgkmcnt(2)
	v_bfe_u32 v13, v64, 16, 1
	v_lshrrev_b32_e32 v11, 16, v11
	v_add3_u32 v13, v64, v13, s63
	v_and_or_b32 v54, v13, s60, v11
	s_waitcnt lgkmcnt(1)
	v_bfe_u32 v11, v66, 16, 1
	v_add3_u32 v11, v66, v11, s63
	s_waitcnt lgkmcnt(0)
	v_bfe_u32 v13, v68, 16, 1
	v_lshrrev_b32_e32 v11, 16, v11
	v_add3_u32 v13, v68, v13, s63
	v_and_or_b32 v55, v13, s60, v11
	v_mov_b32_e32 v71, s0
	v_or_b32_e32 v70, s5, v6
	v_bfe_u32 v11, v57, 16, 1
	v_lshlrev_b64 v[70:71], 7, v[70:71]
	v_add3_u32 v11, v57, v11, s63
	v_bfe_u32 v13, v19, 16, 1
	v_lshl_add_u64 v[70:71], v[16:17], 0, v[70:71]
	v_lshrrev_b32_e32 v11, 16, v11
	v_add3_u32 v13, v19, v13, s63
	global_store_dwordx4 v[70:71], v[52:55], off sc1
	v_mov_b32_e32 v19, s0
	v_or_b32_e32 v18, s5, v8
	v_and_or_b32 v52, v13, s60, v11
	v_bfe_u32 v11, v59, 16, 1
	v_add3_u32 v11, v59, v11, s63
	v_bfe_u32 v13, v61, 16, 1
	v_lshrrev_b32_e32 v11, 16, v11
	v_add3_u32 v13, v61, v13, s63
	v_and_or_b32 v53, v13, s60, v11
	v_bfe_u32 v11, v63, 16, 1
	v_add3_u32 v11, v63, v11, s63
	v_bfe_u32 v13, v65, 16, 1
	v_lshrrev_b32_e32 v11, 16, v11
	v_add3_u32 v13, v65, v13, s63
	v_and_or_b32 v54, v13, s60, v11
	v_bfe_u32 v11, v67, 16, 1
	v_add3_u32 v11, v67, v11, s63
	v_bfe_u32 v13, v69, 16, 1
	v_lshrrev_b32_e32 v11, 16, v11
	v_add3_u32 v13, v69, v13, s63
	v_lshlrev_b64 v[18:19], 7, v[18:19]
	v_and_or_b32 v55, v13, s60, v11
	v_lshl_add_u64 v[18:19], v[16:17], 0, v[18:19]
	global_store_dwordx4 v[18:19], v[52:55], off sc1
	s_waitcnt lgkmcnt(0)
	s_add_i32 s20, s20, s33
	s_add_i32 s18, s18, s19
	s_cmp_lt_i32 s20, s16
	s_cbranch_scc0 .LBB0_389
